# v104 + S5 z-gate loads as two 16-byte loads per four steps with an in-register lane exchange (half the memory segments)
# speedup vs baseline: 1.0009x; 1.0009x over previous
; #define LAS __attribute__((address_space(3)))
; __device__ __forceinline__ bf16x8 pack8(f32x4 lo, f32x4 hi) { v4u w; w.x = pk2(lo[0], lo[1]); w.y = pk2(lo[2], lo[3]); w.z = pk2(hi[0], hi[1]); w.w = pk2(hi[2], hi[3]); return __builtin_bit_cast(bf16x8, w); }
; __device__ __forceinline__ void gmlp_compute(GmlpRegs& R, const Args& a, const Ctx& C, int c, int hd) {
;     ...
;     __syncthreads();
;     const float lg = R.lg, lb = R.lb;
;     bf16x8 af[4];
; #pragma unroll
;     for (int ks = 0; ks < 4; ++ks) { f32x4 lo, hi;
; #pragma unroll
;         for (int e = 0; e < 8; ++e) { const int sl = 32 * ks + 8 * q + e;
;             const float v = __uint_as_float((unsigned)*(const LAS unsigned short*)(VL + sl * 260 + (16 * w + fr) * 2) << 16);
;             const float x = (v - ST[2 * sl]) * ST[2 * sl + 1] * lg + lb; if (e < 4) lo[e] = x; else hi[e - 4] = x; }
;         af[ks] = pack8(lo, hi); }
.LBB0_973:
	s_or_b64 exec, exec, s[4:5]
	s_waitcnt lgkmcnt(0)
	s_barrier
	v_add_u32_e32 v18, v165, v184
	ds_read_b128 v[2:5], v183
	ds_read_u16 v6, v18 offset:34816
	ds_read_u16 v7, v18 offset:35076
	ds_read_u16 v14, v18 offset:35596
	ds_read_u16 v15, v18 offset:36116
	ds_read_u16 v19, v18 offset:36636
	ds_read_u16 v20, v18 offset:43396
	ds_read_u16 v21, v18 offset:43916
	ds_read_u16 v22, v18 offset:44436
	s_waitcnt lgkmcnt(6)
	v_lshlrev_b32_e32 v11, 16, v7
	v_lshlrev_b32_e32 v10, 16, v6
	ds_read_b128 v[6:9], v168
	v_mov_b32_e32 v12, v2
	v_mov_b32_e32 v13, v4
	v_pk_add_f32 v[10:11], v[10:11], v[12:13] neg_lo:[0,1] neg_hi:[0,1]
	v_mov_b32_e32 v4, v3
	v_pk_mul_f32 v[2:3], v[4:5], v[10:11]
	s_waitcnt lgkmcnt(0)
	v_mov_b32_e32 v5, v8
	v_pk_fma_f32 v[10:11], v[98:99], v[2:3], v[100:101]
	v_add_u32_e32 v2, v165, v167
	v_lshlrev_b32_e32 v3, 16, v14
	ds_read_u16 v4, v2 offset:34816
	ds_read_u16 v14, v2 offset:35336
	ds_read_u16 v23, v2 offset:35856
	ds_read_u16 v24, v2 offset:42616
	ds_read_u16 v25, v2 offset:43136
	ds_read_u16 v113, v18 offset:61596
	s_waitcnt lgkmcnt(5)
	v_lshlrev_b32_e32 v2, 16, v4
	v_mov_b32_e32 v4, v6
	v_pk_add_f32 v[2:3], v[2:3], v[4:5] neg_lo:[0,1] neg_hi:[0,1]
	v_mov_b32_e32 v8, v7
	v_pk_mul_f32 v[6:7], v[8:9], v[2:3]
	ds_read_b128 v[2:5], v163
	v_pk_fma_f32 v[12:13], v[98:99], v[6:7], v[100:101]
	ds_read_b128 v[6:9], v166
	v_lshlrev_b32_e32 v15, 16, v15
	s_waitcnt lgkmcnt(6)
	v_lshlrev_b32_e32 v14, 16, v14
	s_waitcnt lgkmcnt(1)
	v_mov_b32_e32 v16, v2
	v_mov_b32_e32 v17, v4
	v_pk_add_f32 v[14:15], v[14:15], v[16:17] neg_lo:[0,1] neg_hi:[0,1]
	v_mov_b32_e32 v4, v3
	v_pk_mul_f32 v[2:3], v[4:5], v[14:15]
	s_waitcnt lgkmcnt(0)
	v_mov_b32_e32 v14, v6
	v_pk_fma_f32 v[4:5], v[98:99], v[2:3], v[100:101]
	v_lshlrev_b32_e32 v3, 16, v19
	v_lshlrev_b32_e32 v2, 16, v23
	v_mov_b32_e32 v15, v8
	v_pk_add_f32 v[2:3], v[2:3], v[14:15] neg_lo:[0,1] neg_hi:[0,1]
	v_mov_b32_e32 v8, v7
	v_pk_mul_f32 v[2:3], v[8:9], v[2:3]
	ds_read_b128 v[6:9], v185
	v_pk_fma_f32 v[14:15], v[98:99], v[2:3], v[100:101]
	v_cvt_pk_bf16_f32 v2, v10, v11
	v_cvt_pk_bf16_f32 v3, v12, v13
	ds_read_b128 v[10:13], v186
	v_cvt_pk_bf16_f32 v4, v4, v5
	v_cvt_pk_bf16_f32 v5, v14, v15
	v_lshlrev_b32_e32 v15, 16, v20
	v_lshlrev_b32_e32 v14, 16, v24
	s_waitcnt lgkmcnt(1)
	v_mov_b32_e32 v16, v6
	v_mov_b32_e32 v17, v8
	v_pk_add_f32 v[14:15], v[14:15], v[16:17] neg_lo:[0,1] neg_hi:[0,1]
	v_mov_b32_e32 v8, v7
	v_pk_mul_f32 v[6:7], v[8:9], v[14:15]
	s_waitcnt lgkmcnt(0)
	v_mov_b32_e32 v8, v10
	v_pk_fma_f32 v[14:15], v[98:99], v[6:7], v[100:101]
	v_lshlrev_b32_e32 v7, 16, v21
	v_lshlrev_b32_e32 v6, 16, v25
	v_mov_b32_e32 v9, v12
	v_pk_add_f32 v[16:17], v[6:7], v[8:9] neg_lo:[0,1] neg_hi:[0,1]
	ds_read_u16 v19, v187 offset:34816
	ds_read_u16 v20, v187 offset:35336
	ds_read_u16 v21, v187 offset:42096
	ds_read_b128 v[6:9], v188
	v_mov_b32_e32 v12, v11
	v_pk_mul_f32 v[10:11], v[12:13], v[16:17]
	v_lshlrev_b32_e32 v13, 16, v22
	s_waitcnt lgkmcnt(3)
	v_lshlrev_b32_e32 v12, 16, v19
	s_waitcnt lgkmcnt(0)
	v_mov_b32_e32 v16, v6
	v_mov_b32_e32 v17, v8
	v_pk_add_f32 v[12:13], v[12:13], v[16:17] neg_lo:[0,1] neg_hi:[0,1]
	v_mov_b32_e32 v8, v7
	v_pk_mul_f32 v[6:7], v[8:9], v[12:13]
	v_pk_fma_f32 v[10:11], v[98:99], v[10:11], v[100:101]
	v_pk_fma_f32 v[12:13], v[98:99], v[6:7], v[100:101]
	ds_read_b128 v[6:9], v189
	ds_read_u16 v16, v18 offset:44956
	ds_read_u16 v22, v18 offset:51716
	ds_read_u16 v23, v18 offset:52236
	ds_read_u16 v24, v18 offset:52756
	ds_read_u16 v26, v18 offset:53276
	ds_read_u16 v27, v18 offset:60036
	ds_read_u16 v28, v18 offset:60556
	ds_read_u16 v36, v18 offset:61076
	s_waitcnt lgkmcnt(7)
	v_lshlrev_b32_e32 v17, 16, v16
	v_lshlrev_b32_e32 v16, 16, v20
	v_mov_b32_e32 v18, v6
	v_mov_b32_e32 v19, v8
	v_pk_add_f32 v[16:17], v[16:17], v[18:19] neg_lo:[0,1] neg_hi:[0,1]
	v_mov_b32_e32 v8, v7
	v_pk_mul_f32 v[6:7], v[8:9], v[16:17]
	ds_read_u16 v25, v187 offset:42616
	ds_read_u16 v29, v187 offset:43136
	v_pk_fma_f32 v[16:17], v[98:99], v[6:7], v[100:101]
	v_cvt_pk_bf16_f32 v7, v10, v11
	v_cvt_pk_bf16_f32 v8, v12, v13
	ds_read_b128 v[10:13], v190
	v_cvt_pk_bf16_f32 v6, v14, v15
	v_cvt_pk_bf16_f32 v9, v16, v17
	ds_read_b128 v[14:17], v191
	s_waitcnt lgkmcnt(10)
	v_lshlrev_b32_e32 v19, 16, v22
	v_lshlrev_b32_e32 v18, 16, v21
	s_waitcnt lgkmcnt(1)
	v_mov_b32_e32 v20, v10
	v_mov_b32_e32 v21, v12
	v_pk_add_f32 v[18:19], v[18:19], v[20:21] neg_lo:[0,1] neg_hi:[0,1]
	v_mov_b32_e32 v12, v11
	v_pk_mul_f32 v[10:11], v[12:13], v[18:19]
	s_waitcnt lgkmcnt(0)
	v_mov_b32_e32 v12, v14
	v_pk_fma_f32 v[18:19], v[98:99], v[10:11], v[100:101]
	v_lshlrev_b32_e32 v11, 16, v23
	v_lshlrev_b32_e32 v10, 16, v25
	v_mov_b32_e32 v13, v16
	v_pk_add_f32 v[10:11], v[10:11], v[12:13] neg_lo:[0,1] neg_hi:[0,1]
	v_mov_b32_e32 v16, v15
	v_pk_mul_f32 v[14:15], v[16:17], v[10:11]
	ds_read_b128 v[10:13], v192
	v_pk_fma_f32 v[20:21], v[98:99], v[14:15], v[100:101]
	ds_read_b128 v[14:17], v194
	v_lshlrev_b32_e32 v23, 16, v24
	v_lshlrev_b32_e32 v22, 16, v29
	s_waitcnt lgkmcnt(1)
	v_mov_b32_e32 v24, v10
	v_mov_b32_e32 v25, v12
	v_pk_add_f32 v[22:23], v[22:23], v[24:25] neg_lo:[0,1] neg_hi:[0,1]
	v_mov_b32_e32 v12, v11
	v_pk_mul_f32 v[10:11], v[12:13], v[22:23]
	s_waitcnt lgkmcnt(0)
	v_mov_b32_e32 v22, v14
	v_pk_fma_f32 v[12:13], v[98:99], v[10:11], v[100:101]
	ds_read_u16 v10, v193 offset:34816
	ds_read_u16 v24, v193 offset:41576
	ds_read_u16 v29, v193 offset:42096
	ds_read_u16 v38, v193 offset:42616
	ds_read_u16 v121, v193 offset:43136
	v_lshlrev_b32_e32 v11, 16, v26
	s_waitcnt lgkmcnt(4)
; #define LAS __attribute__((address_space(3)))
; #define MFMA16(A, B, Cc) __builtin_amdgcn_mfma_f32_16x16x32_bf16((A), (B), (Cc), 0, 0, 0)
; #define PIN(x) asm volatile("" : "+v"(x))
; __device__ __forceinline__ float bf_lo(unsigned w) { return __uint_as_float(w << 16); }
; __device__ __forceinline__ unsigned pk4f8(float a, float b, float c, float d) { int p = __builtin_amdgcn_cvt_pk_fp8_f32(sat8(a), sat8(b), 0, false); p = __builtin_amdgcn_cvt_pk_fp8_f32(sat8(c), sat8(d), p, true); return (unsigned)p; }
; __device__ __forceinline__ float bf_hi(unsigned w) { return __uint_as_float(w & 0xffff0000u); }
; __device__ __forceinline__ bf16x8 pack8(f32x4 lo, f32x4 hi) { v4u w; w.x = pk2(lo[0], lo[1]); w.y = pk2(lo[2], lo[3]); w.z = pk2(hi[0], hi[1]); w.w = pk2(hi[2], hi[3]); return __builtin_bit_cast(bf16x8, w); }
; __device__ __forceinline__ void gmlp_compute(GmlpRegs& R, const Args& a, const Ctx& C, int c, int hd) {
;     ...
;     const float lg = R.lg, lb = R.lb;
;     bf16x8 af[4];
; #pragma unroll
;     for (int ks = 0; ks < 4; ++ks) { f32x4 lo, hi;
; #pragma unroll
;         for (int e = 0; e < 8; ++e) { const int sl = 32 * ks + 8 * q + e;
;             const float v = __uint_as_float((unsigned)*(const LAS unsigned short*)(VL + sl * 260 + (16 * w + fr) * 2) << 16);
;             const float x = (v - ST[2 * sl]) * ST[2 * sl + 1] * lg + lb; if (e < 4) lo[e] = x; else hi[e - 4] = x; }
;         af[ks] = pack8(lo, hi); }
;     f32x4 acc[8];
; #pragma unroll
;     for (int nt = 0; nt < 8; ++nt) { acc[nt] = (f32x4){0.f, 0.f, 0.f, 0.f};
; #pragma unroll
;         for (int ks = 0; ks <= nt / 2; ++ks) acc[nt] = MFMA16(af[ks], *(const LAS bf16x8*)(WL + (16 * nt + fr) * 272 + (32 * ks + 8 * q) * 2), acc[nt]); }
; #pragma unroll
;     for (int nt = 0; nt < 8; ++nt) PIN(R.uq[nt]);
; #pragma unroll
;     for (int nt = 0; nt < 8; ++nt) { const size_t row = T0 + 16 * nt + fr; const float bs = R.bsv[nt];
;         const float o0 = bf_lo(R.uq[nt].x) * (acc[nt][0] + bs), o1 = bf_hi(R.uq[nt].x) * (acc[nt][1] + bs);
;         const float o2 = bf_lo(R.uq[nt].y) * (acc[nt][2] + bs), o3 = bf_hi(R.uq[nt].y) * (acc[nt][3] + bs);
;         *(unsigned*)((unsigned char*)Y + row * DM + chs) = pk4f8(o0, o1, o2, o3); }
	v_lshlrev_b32_e32 v10, 16, v10
	v_mov_b32_e32 v23, v16
	v_pk_add_f32 v[10:11], v[10:11], v[22:23] neg_lo:[0,1] neg_hi:[0,1]
	v_mov_b32_e32 v16, v15
	v_pk_mul_f32 v[10:11], v[16:17], v[10:11]
	ds_read_b128 v[14:17], v195
	v_pk_fma_f32 v[22:23], v[98:99], v[10:11], v[100:101]
	v_cvt_pk_bf16_f32 v10, v18, v19
	v_cvt_pk_bf16_f32 v11, v20, v21
	v_cvt_pk_bf16_f32 v12, v12, v13
	v_cvt_pk_bf16_f32 v13, v22, v23
	v_lshlrev_b32_e32 v23, 16, v27
	s_waitcnt lgkmcnt(4)
	v_lshlrev_b32_e32 v22, 16, v24
	ds_read_b128 v[18:21], v196
	s_waitcnt lgkmcnt(1)
	v_mov_b32_e32 v24, v14
	v_mov_b32_e32 v25, v16
	v_pk_add_f32 v[26:27], v[22:23], v[24:25] neg_lo:[0,1] neg_hi:[0,1]
	v_mov_b32_e32 v16, v15
	v_add_u32_e32 v126, v199, v200
	v_pk_mul_f32 v[14:15], v[16:17], v[26:27]
	v_lshlrev_b32_e32 v31, 16, v28
	v_lshlrev_b32_e32 v30, 16, v29
	ds_read_b128 v[26:29], v126 offset:8704
	s_waitcnt lgkmcnt(1)
	v_mov_b32_e32 v32, v18
	v_mov_b32_e32 v33, v20
	v_pk_add_f32 v[34:35], v[30:31], v[32:33] neg_lo:[0,1] neg_hi:[0,1]
	ds_read_b128 v[30:33], v126 offset:8768
	v_mov_b32_e32 v20, v19
	s_waitcnt lgkmcnt(1)
	v_mfma_f32_16x16x32_bf16 v[26:29], v[2:5], v[26:29], 0
	v_mul_f32_e64 v34, v20, v34
	v_mul_f32_e64 v35, v21, v35
	ds_read_b128 v[18:21], v126 offset:13056
	v_lshlrev_b32_e32 v46, 16, v38
	ds_read_b128 v[38:41], v126 offset:17408
	ds_read_b128 v[42:45], v126 offset:17472
	s_waitcnt lgkmcnt(3)
	v_mfma_f32_16x16x32_bf16 v[26:29], v[6:9], v[30:33], v[26:29]
	v_fma_f32 v92, v98, v34, v100
	v_fma_f32 v93, v99, v35, v101
	v_lshlrev_b32_e32 v47, 16, v36
	ds_read_b128 v[30:33], v126 offset:13120
	ds_read_b128 v[34:37], v197
	s_waitcnt lgkmcnt(4)
	v_mfma_f32_16x16x32_bf16 v[18:21], v[2:5], v[18:21], 0
	v_fma_f32 v88, v98, v14, v100
	v_fma_f32 v89, v99, v15, v101
	ds_read_b128 v[22:25], v126
	ds_read_b128 v[14:17], v126 offset:4352
	s_waitcnt lgkmcnt(5)
	v_mfma_f32_16x16x32_bf16 v[38:41], v[2:5], v[38:41], 0
	s_lshl_b64 s[4:5], s[70:71], 11
	s_mov_b64 s[8:9], 0x2300000
	v_readlane_b32 s16, v249, 1
	s_waitcnt lgkmcnt(3)
	v_mfma_f32_16x16x32_bf16 v[18:21], v[6:9], v[30:33], v[18:21]
	ds_read_b128 v[30:33], v198
	s_waitcnt lgkmcnt(3)
	v_mov_b32_e32 v48, v34
	v_mov_b32_e32 v49, v36
	v_pk_add_f32 v[90:91], v[46:47], v[48:49] neg_lo:[0,1] neg_hi:[0,1]
	v_mov_b32_e32 v36, v35
	ds_read_b128 v[46:49], v126 offset:17536
	v_mfma_f32_16x16x32_bf16 v[38:41], v[6:9], v[42:45], v[38:41]
	v_mul_f32_e64 v42, v36, v90
	v_mul_f32_e64 v43, v37, v91
	ds_read_b128 v[34:37], v126 offset:21760
	v_pk_fma_f32 v[122:123], v[98:99], v[42:43], v[100:101]
	ds_read_b128 v[42:45], v126 offset:21824
	s_waitcnt lgkmcnt(1)
	v_mfma_f32_16x16x32_bf16 v[34:37], v[2:5], v[34:37], 0
	v_lshlrev_b32_e32 v91, 16, v113
	v_lshlrev_b32_e32 v90, 16, v121
	v_mov_b32_e32 v124, v30
	v_mfma_f32_16x16x32_bf16 v[38:41], v[10:13], v[46:49], v[38:41]
	ds_read_b128 v[46:49], v126 offset:21888
	v_mov_b32_e32 v125, v32
	v_pk_add_f32 v[90:91], v[90:91], v[124:125] neg_lo:[0,1] neg_hi:[0,1]
	s_waitcnt lgkmcnt(1)
	v_mfma_f32_16x16x32_bf16 v[34:37], v[6:9], v[42:45], v[34:37]
	ds_read_b128 v[42:45], v126 offset:26112
	v_mov_b32_e32 v32, v31
	v_readlane_b32 s17, v249, 2
	s_waitcnt lgkmcnt(1)
	v_mfma_f32_16x16x32_bf16 v[34:37], v[10:13], v[46:49], v[34:37]
	v_mul_f32_e64 v46, v32, v90
	v_mul_f32_e64 v47, v33, v91
	ds_read_b128 v[30:33], v126 offset:26176
	v_pk_fma_f32 v[98:99], v[98:99], v[46:47], v[100:101]
	s_waitcnt lgkmcnt(1)
	v_mfma_f32_16x16x32_bf16 v[42:45], v[2:5], v[42:45], 0
	v_cvt_pk_bf16_f32 v46, v88, v89
	ds_read_b128 v[88:91], v126 offset:26240
	v_cvt_pk_bf16_f32 v47, v92, v93
	s_waitcnt lgkmcnt(1)
	v_mfma_f32_16x16x32_bf16 v[30:33], v[6:9], v[30:33], v[42:45]
	v_cvt_pk_bf16_f32 v48, v122, v123
	v_cvt_pk_bf16_f32 v49, v98, v99
	v_readlane_b32 s18, v249, 3
	ds_read_b128 v[42:45], v126 offset:26304
	s_waitcnt lgkmcnt(1)
	v_mfma_f32_16x16x32_bf16 v[30:33], v[10:13], v[88:91], v[30:33]
	v_readlane_b32 s19, v249, 4
	v_readlane_b32 s20, v249, 5
	v_readlane_b32 s21, v249, 6
	s_waitcnt lgkmcnt(0)
	v_mfma_f32_16x16x32_bf16 v[30:33], v[46:49], v[42:45], v[30:33]
	ds_read_b128 v[42:45], v126 offset:30464
	ds_read_b128 v[88:91], v126 offset:30528
	v_readlane_b32 s22, v249, 7
	v_readlane_b32 s23, v249, 8
	v_mfma_f32_16x16x32_bf16 v[22:25], v[2:5], v[22:25], 0
	v_readlane_b32 s24, v249, 9
	v_readlane_b32 s25, v249, 10
	v_readlane_b32 s26, v249, 11
	v_mfma_f32_16x16x32_bf16 v[14:17], v[2:5], v[14:17], 0
	v_readlane_b32 s27, v249, 12
	v_readlane_b32 s28, v249, 13
	v_readlane_b32 s29, v249, 14
	s_waitcnt lgkmcnt(1)
	v_mfma_f32_16x16x32_bf16 v[2:5], v[2:5], v[42:45], 0
	v_readlane_b32 s30, v249, 15
	v_readlane_b32 s31, v249, 16
	s_mov_b64 s[14:15], s[22:23]
	s_waitcnt lgkmcnt(0)
	v_mfma_f32_16x16x32_bf16 v[2:5], v[6:9], v[88:91], v[2:5]
	ds_read_b128 v[6:9], v126 offset:30592
	ds_read_b128 v[42:45], v126 offset:30656
	s_waitcnt vmcnt(17)
	s_waitcnt vmcnt(16)
	s_waitcnt lgkmcnt(1)
	v_mfma_f32_16x16x32_bf16 v[2:5], v[10:13], v[6:9], v[2:5]
	v_lshlrev_b32_e32 v6, 16, v110
	v_add_f32_e32 v7, v161, v22
	v_mul_f32_e32 v6, v7, v6
	v_and_b32_e32 v7, 0xffff0000, v110
	v_add_f32_e32 v8, v161, v23
	v_mul_f32_e32 v7, v8, v7
	v_med3_f32 v6, v6, s1, v128
	v_med3_f32 v7, v7, s1, v128
	v_mov_b32_e32 v11, 0
	v_lshlrev_b32_e32 v8, 16, v111
	v_add_f32_e32 v9, v161, v24
	v_cvt_pk_fp8_f32 v11, v6, v7
	v_mul_f32_e32 v8, v9, v8
	v_and_b32_e32 v9, 0xffff0000, v111
	v_add_f32_e32 v10, v161, v25
	v_mul_f32_e32 v6, v10, v9
	v_med3_f32 v7, v8, s1, v128
	v_med3_f32 v6, v6, s1, v128
	v_cvt_pk_fp8_f32 v11, v7, v6 op_sel:[0,0,1]
	v_lshlrev_b32_e32 v8, 16, v118
	v_add_f32_e32 v9, v160, v14
	v_mul_f32_e32 v8, v9, v8
	v_and_b32_e32 v9, 0xffff0000, v118
	v_add_f32_e32 v10, v160, v15
	v_lshlrev_b64 v[6:7], 11, v[116:117]
	v_and_b32_e32 v231, 0x7f, v116
	v_and_b32_e32 v232, 0xffffff80, v116
	s_movk_i32 s88, 0x90
	v_mad_u32_u24 v233, v231, s88, v230
	v_add_u32_e32 v233, 0x12000, v233
	v_mul_f32_e32 v9, v10, v9
	v_lshl_add_u64 v[6:7], v[142:143], 0, v[6:7]
	v_med3_f32 v8, v8, s1, v128
	v_med3_f32 v9, v9, s1, v128
	v_mov_b32_e32 v13, 0
	s_waitcnt vmcnt(15)
; __device__ __forceinline__ float bf_lo(unsigned w) { return __uint_as_float(w << 16); }
; __device__ __forceinline__ unsigned pk4f8(float a, float b, float c, float d) { int p = __builtin_amdgcn_cvt_pk_fp8_f32(sat8(a), sat8(b), 0, false); p = __builtin_amdgcn_cvt_pk_fp8_f32(sat8(c), sat8(d), p, true); return (unsigned)p; }
; __device__ __forceinline__ float bf_hi(unsigned w) { return __uint_as_float(w & 0xffff0000u); }
; __device__ __forceinline__ void gmlp_compute(GmlpRegs& R, const Args& a, const Ctx& C, int c, int hd) {
;     ...
; #pragma unroll
;     for (int nt = 0; nt < 8; ++nt) { const size_t row = T0 + 16 * nt + fr; const float bs = R.bsv[nt];
;         const float o0 = bf_lo(R.uq[nt].x) * (acc[nt][0] + bs), o1 = bf_hi(R.uq[nt].x) * (acc[nt][1] + bs);
;         const float o2 = bf_lo(R.uq[nt].y) * (acc[nt][2] + bs), o3 = bf_hi(R.uq[nt].y) * (acc[nt][3] + bs);
;         *(unsigned*)((unsigned char*)Y + row * DM + chs) = pk4f8(o0, o1, o2, o3); }
	s_waitcnt vmcnt(14)
	s_waitcnt vmcnt(13)
	s_waitcnt vmcnt(12)
	s_waitcnt vmcnt(11)
	s_waitcnt vmcnt(10)
	ds_write_b32 v233, v11
	v_lshlrev_b32_e32 v10, 16, v119
	v_add_f32_e32 v11, v160, v16
	v_cvt_pk_fp8_f32 v13, v8, v9
	v_mul_f32_e32 v10, v11, v10
	v_and_b32_e32 v11, 0xffff0000, v119
	v_add_f32_e32 v12, v160, v17
	v_mul_f32_e32 v8, v12, v11
	v_med3_f32 v9, v10, s1, v128
	v_med3_f32 v8, v8, s1, v128
	v_cvt_pk_fp8_f32 v13, v9, v8 op_sel:[0,0,1]
	v_add_co_u32_e32 v8, vcc, s2, v6
	v_add_f32_e32 v10, v159, v27
	s_nop 0
	v_addc_co_u32_e32 v9, vcc, 0, v7, vcc
	ds_write_b32 v233, v13 offset:2304
	v_lshlrev_b32_e32 v8, 16, v114
	v_add_f32_e32 v9, v159, v26
	v_mul_f32_e32 v8, v9, v8
	v_and_b32_e32 v9, 0xffff0000, v114
	v_mul_f32_e32 v9, v10, v9
	v_med3_f32 v8, v8, s1, v128
	v_med3_f32 v9, v9, s1, v128
	v_mov_b32_e32 v13, 0
	v_lshlrev_b32_e32 v10, 16, v115
	v_add_f32_e32 v11, v159, v28
	v_cvt_pk_fp8_f32 v13, v8, v9
	v_mul_f32_e32 v10, v11, v10
	v_and_b32_e32 v11, 0xffff0000, v115
	v_add_f32_e32 v12, v159, v29
	v_mul_f32_e32 v8, v12, v11
	v_med3_f32 v9, v10, s1, v128
	v_med3_f32 v8, v8, s1, v128
	v_cvt_pk_fp8_f32 v13, v9, v8 op_sel:[0,0,1]
	v_add_co_u32_e32 v8, vcc, s33, v6
	v_add_f32_e32 v10, v156, v19
	s_nop 0
	v_addc_co_u32_e32 v9, vcc, 0, v7, vcc
	ds_write_b32 v233, v13 offset:4608
	v_lshlrev_b32_e32 v8, 16, v108
	v_add_f32_e32 v9, v156, v18
	v_mul_f32_e32 v8, v9, v8
	v_and_b32_e32 v9, 0xffff0000, v108
	v_mul_f32_e32 v9, v10, v9
	v_med3_f32 v8, v8, s1, v128
	v_med3_f32 v9, v9, s1, v128
	v_mov_b32_e32 v13, 0
	v_lshlrev_b32_e32 v10, 16, v109
	v_add_f32_e32 v11, v156, v20
	v_cvt_pk_fp8_f32 v13, v8, v9
	v_mul_f32_e32 v10, v11, v10
	v_and_b32_e32 v11, 0xffff0000, v109
	v_add_f32_e32 v12, v156, v21
	v_mul_f32_e32 v8, v12, v11
	v_med3_f32 v9, v10, s1, v128
	v_med3_f32 v8, v8, s1, v128
	v_cvt_pk_fp8_f32 v13, v9, v8 op_sel:[0,0,1]
	v_add_co_u32_e32 v8, vcc, s74, v6
	v_add_f32_e32 v10, v154, v39
	s_nop 0
	v_addc_co_u32_e32 v9, vcc, 0, v7, vcc
	ds_write_b32 v233, v13 offset:6912
	v_lshlrev_b32_e32 v8, 16, v106
	v_add_f32_e32 v9, v154, v38
	v_mul_f32_e32 v8, v9, v8
	v_and_b32_e32 v9, 0xffff0000, v106
	v_mul_f32_e32 v9, v10, v9
	v_med3_f32 v8, v8, s1, v128
	v_med3_f32 v9, v9, s1, v128
	v_mov_b32_e32 v13, 0
	v_lshlrev_b32_e32 v10, 16, v107
	v_add_f32_e32 v11, v154, v40
	v_cvt_pk_fp8_f32 v13, v8, v9
	v_mul_f32_e32 v10, v11, v10
	v_and_b32_e32 v11, 0xffff0000, v107
	v_add_f32_e32 v12, v154, v41
	v_mul_f32_e32 v8, v12, v11
	v_med3_f32 v9, v10, s1, v128
	v_med3_f32 v8, v8, s1, v128
	v_cvt_pk_fp8_f32 v13, v9, v8 op_sel:[0,0,1]
	v_add_co_u32_e32 v8, vcc, s75, v6
	v_add_f32_e32 v10, v152, v35
	s_nop 0
	v_addc_co_u32_e32 v9, vcc, 0, v7, vcc
	ds_write_b32 v233, v13 offset:9216
	v_lshlrev_b32_e32 v8, 16, v104
	v_add_f32_e32 v9, v152, v34
	v_mul_f32_e32 v8, v9, v8
	v_and_b32_e32 v9, 0xffff0000, v104
	v_mul_f32_e32 v9, v10, v9
	v_med3_f32 v8, v8, s1, v128
	v_med3_f32 v9, v9, s1, v128
	v_mov_b32_e32 v13, 0
	v_lshlrev_b32_e32 v10, 16, v105
	v_add_f32_e32 v11, v152, v36
	v_cvt_pk_fp8_f32 v13, v8, v9
	v_mul_f32_e32 v10, v11, v10
	v_and_b32_e32 v11, 0xffff0000, v105
	v_add_f32_e32 v12, v152, v37
	v_mul_f32_e32 v8, v12, v11
	v_med3_f32 v9, v10, s1, v128
	v_med3_f32 v8, v8, s1, v128
	v_cvt_pk_fp8_f32 v13, v9, v8 op_sel:[0,0,1]
	v_add_co_u32_e32 v8, vcc, s76, v6
	v_add_f32_e32 v10, v151, v31
	s_nop 0
	v_addc_co_u32_e32 v9, vcc, 0, v7, vcc
	ds_write_b32 v233, v13 offset:11520
	v_lshlrev_b32_e32 v8, 16, v102
	v_add_f32_e32 v9, v151, v30
	v_mul_f32_e32 v8, v9, v8
	v_and_b32_e32 v9, 0xffff0000, v102
	v_mul_f32_e32 v9, v10, v9
	v_med3_f32 v8, v8, s1, v128
	v_med3_f32 v9, v9, s1, v128
	v_mov_b32_e32 v13, 0
	v_lshlrev_b32_e32 v10, 16, v103
	v_add_f32_e32 v11, v151, v32
	v_cvt_pk_fp8_f32 v13, v8, v9
	v_mul_f32_e32 v10, v11, v10
	v_and_b32_e32 v11, 0xffff0000, v103
	v_add_f32_e32 v12, v151, v33
	v_mul_f32_e32 v8, v12, v11
	v_med3_f32 v9, v10, s1, v128
	v_med3_f32 v8, v8, s1, v128
	s_waitcnt lgkmcnt(0)
	v_mfma_f32_16x16x32_bf16 v[2:5], v[46:49], v[42:45], v[2:5]
	v_cvt_pk_fp8_f32 v13, v9, v8 op_sel:[0,0,1]
	v_add_co_u32_e32 v8, vcc, s77, v6
	v_mov_b32_e32 v111, 0
	s_nop 0
	v_addc_co_u32_e32 v9, vcc, 0, v7, vcc
	ds_write_b32 v233, v13 offset:13824
	v_lshlrev_b32_e32 v8, 16, v96
	s_nop 0
	v_add_f32_e32 v2, v150, v2
	v_mul_f32_e32 v2, v2, v8
	v_and_b32_e32 v8, 0xffff0000, v96
	v_add_f32_e32 v3, v150, v3
	v_mul_f32_e32 v3, v3, v8
	v_lshlrev_b32_e32 v8, 16, v97
	v_add_f32_e32 v4, v150, v4
	v_mul_f32_e32 v4, v4, v8
	v_and_b32_e32 v8, 0xffff0000, v97
	v_add_f32_e32 v5, v150, v5
	v_med3_f32 v2, v2, s1, v128
	v_med3_f32 v3, v3, s1, v128
	v_mov_b32_e32 v9, 0
	v_cvt_pk_fp8_f32 v9, v2, v3
	v_mul_f32_e32 v2, v5, v8
	v_med3_f32 v3, v4, s1, v128
	v_med3_f32 v2, v2, s1, v128
	s_mul_i32 s1, s0, 0x2100
	s_add_u32 s4, s1, s4
	s_addc_u32 s5, 0, s5
	s_lshl_b64 s[4:5], s[4:5], 5
	s_lshl_b32 s1, s0, 9
	s_lshl_b32 s2, s0, 12
	s_add_u32 s6, s94, s1
	v_cvt_pk_fp8_f32 v9, v3, v2 op_sel:[0,0,1]
	v_add_co_u32_e32 v2, vcc, s78, v6
	v_lshlrev_b32_e32 v110, 2, v153
	s_addc_u32 s7, s95, 0
	v_addc_co_u32_e32 v3, vcc, 0, v7, vcc
	v_lshl_add_u64 v[18:19], s[6:7], 0, v[110:111]
	s_mov_b32 s1, 0x2300000
	v_lshl_add_u64 v[20:21], v[18:19], 0, s[8:9]
	v_add_co_u32_e32 v18, vcc, s1, v18
	ds_write_b32 v233, v9 offset:16128
	s_waitcnt lgkmcnt(0)
	s_barrier
; #define LAS __attribute__((address_space(3)))
; __device__ __forceinline__ void s5_load_consts(S5C& K, const Args& a, int g, int lane) {
;     const int fr = lane & 15, q = lane >> 4;
;     const float* ABAR = (const float*)(a.ws + WS_S5C + S5C_ABAR) + (size_t)g * 128;
;     const bf16* BBAR = (const bf16*)(a.ws + WS_S5C + S5C_BBAR) + (size_t)g * 2048;
; #pragma unroll
;     for (int j = 0; j < 4; ++j) { const f32x4 x0 = *(const f32x4*)(ABAR + 2 * (16 * j + 4 * q)), x1 = *(const f32x4*)(ABAR + 2 * (16 * j + 4 * q) + 4);
;         K.ar[j] = (f32x4){x0[0], x0[2], x1[0], x1[2]}; K.ai[j] = (f32x4){x0[1], x0[3], x1[1], x1[3]}; }
; #pragma unroll
;     for (int mt = 0; mt < 8; ++mt) K.Bf[mt] = *(const v2u*)(BBAR + (mt * 16 + fr) * 16 + 4 * q);
;     const float* cre = a.in[I_CRE] + ((size_t)g * 16 + fr) * 64; const float* cim = a.in[I_CIM] + ((size_t)g * 16 + fr) * 64;
; #pragma unroll
;     for (int j = 0; j < 4; ++j) { const f32x4 r4 = *(const f32x4*)(cre + 16 * j + 4 * q), i4 = *(const f32x4*)(cim + 16 * j + 4 * q); K.Cf[j] = pack8(r4, -i4); }
;     const float* wg = a.in[I_WGLU] + (size_t)g * 512;
;     { f32x4 v, gt;
; #pragma unroll
;       for (int e = 0; e < 4; ++e) { v[e] = wg[(4 * q + e) * 32 + fr]; gt[e] = wg[(4 * q + e) * 32 + 16 + fr]; }
;       K.Wv = (v2u){pk2(v[0], v[1]), pk2(v[2], v[3])}; K.Wg = (v2u){pk2(gt[0], gt[1]), pk2(gt[2], gt[3])}; }
;     K.dsk = *(const f32x4*)(a.in[I_DSKIP] + g * 16 + 4 * q);
;     K.bv = *(const f32x4*)(a.in[I_BGLU] + g * 32 + 4 * q); K.bg = *(const f32x4*)(a.in[I_BGLU] + g * 32 + 16 + 4 * q);
; __device__ __forceinline__ void s5_prompt_task(const Args& a, const Ctx& C, int b, int g, v4u (&xv)[8]) {
;     ...
;     __syncthreads();
; #pragma unroll
;     for (int i = 0; i < 8; ++i) PIN(xv[i]);
; #pragma unroll
;     for (int i = 0; i < 8; ++i) { const int idx = C.tid + 512 * i, tok = idx >> 1; *(LAS v4u*)(XS + tok * 32 + (tok >> 4) * 16 + (idx & 1) * 16) = xv[i]; }
;     S5C K; s5_load_consts(K, a, g, lane);
;     __syncthreads();
;     const int chunk = 16 * w + n;
;     f32x4 hre[4], him[4];
; #pragma unroll
;     for (int j = 0; j < 4; ++j) { hre[j] = (f32x4){0.f, 0.f, 0.f, 0.f}; him[j] = (f32x4){0.f, 0.f, 0.f, 0.f}; }
;     const LAS unsigned char* xsl = XS + chunk * 528 + q * 8;
;     for (int t = 0; t < 16; ++t) { const v2u xq = *(const LAS v2u*)(xsl + t * 32); S5_UPDATE(K, hre, him, xq); }
; #pragma unroll
	v_lshrrev_b32_e32 v234, 3, v0
	v_and_b32_e32 v236, 7, v0
	v_lshlrev_b32_e32 v236, 4, v236
	s_movk_i32 s88, 0x90
	v_mad_u32_u24 v221, v234, s88, v236
	v_add_u32_e32 v221, 0x12000, v221
	ds_read_b128 v[238:241], v221
	ds_read_b128 v[242:245], v221 offset:9216
	v_add_u32_e32 v234, v232, v234
	v_mov_b32_e32 v235, 0
	v_mov_b32_e32 v237, 0
	v_lshlrev_b64 v[246:247], 11, v[234:235]
	v_lshl_add_u64 v[246:247], v[228:229], 0, v[246:247]
	v_lshl_add_u64 v[246:247], v[246:247], 0, v[236:237]
	v_mov_b32_e32 v236, 0x20000
	v_lshl_add_u64 v[212:213], v[246:247], 0, v[236:237]
	s_waitcnt lgkmcnt(0)
	global_store_dwordx4 v[246:247], v[238:241], off
	global_store_dwordx4 v[212:213], v[242:245], off
	s_nop 0
	v_addc_co_u32_e32 v19, vcc, 0, v19, vcc
	s_barrier
	s_waitcnt vmcnt(9)
	s_waitcnt vmcnt(8)
	s_waitcnt vmcnt(7)
	s_waitcnt vmcnt(6)
	s_waitcnt vmcnt(5)
	s_waitcnt vmcnt(4)
	s_waitcnt vmcnt(3)
	s_waitcnt vmcnt(2)
	global_load_dwordx4 v[2:5], v[20:21], off offset:16
	global_load_dwordx4 v[6:9], v[20:21], off offset:144
	global_load_dwordx4 v[10:13], v[20:21], off offset:272
	global_load_dwordx4 v[14:17], v[20:21], off offset:400
	global_load_dwordx4 v[30:33], v[18:19], off
	v_and_b32_e32 v18, 0x1fe0, v94
	v_lshrrev_b32_e32 v19, 1, v0
	v_add_u32_e32 v18, 0, v18
	v_and_b32_e32 v19, 0xf0, v19
	v_and_b32_e32 v24, 16, v94
	v_add3_u32 v18, v18, v19, v24
	ds_write_b128 v18, v[74:77]
	v_and_b32_e32 v18, 0x3fe0, v87
	v_lshrrev_b32_e32 v19, 1, v146
	v_add_u32_e32 v18, 0, v18
	v_and_b32_e32 v19, 0x1f0, v19
	v_add3_u32 v18, v18, v19, v24
	ds_write_b128 v18, v[78:81]
	v_and_b32_e32 v18, 0x7fe0, v148
	v_lshrrev_b32_e32 v19, 1, v147
	v_add_u32_e32 v18, 0, v18
	v_and_b32_e32 v19, 0x3f0, v19
	v_add3_u32 v18, v18, v19, v24
	ds_write_b128 v18, v[70:73]
	v_and_b32_e32 v18, 0x7fe0, v86
	v_lshrrev_b32_e32 v19, 1, v95
	v_add_u32_e32 v18, 0, v18
	v_and_b32_e32 v19, 0x3f0, v19
	v_add3_u32 v18, v18, v19, v24
	ds_write_b128 v18, v[66:69]
	v_and_b32_e32 v18, 0xbfe0, v85
	v_lshrrev_b32_e32 v19, 1, v120
	v_add_u32_e32 v18, 0, v18
	v_and_b32_e32 v19, 0x5f0, v19
	v_add3_u32 v18, v18, v19, v24
	ds_write_b128 v18, v[58:61]
	v_and_b32_e32 v18, 0xffe0, v84
	v_lshrrev_b32_e32 v19, 1, v157
	v_add_u32_e32 v18, 0, v18
	v_and_b32_e32 v19, 0x7f0, v19
	v_add3_u32 v18, v18, v19, v24
	ds_write_b128 v18, v[62:65]
	v_and_b32_e32 v18, 0xffe0, v83
	v_lshrrev_b32_e32 v19, 1, v158
	s_add_u32 s8, s94, s2
	v_add_u32_e32 v18, 0, v18
	v_and_b32_e32 v19, 0x7f0, v19
	s_addc_u32 s9, s95, 0
	v_lshlrev_b32_e32 v110, 1, v112
	v_add3_u32 v25, v18, v19, v24
	v_lshl_add_u64 v[18:19], s[8:9], 0, v[110:111]
	v_lshlrev_b32_e32 v22, 5, v149
	v_mov_b32_e32 v23, v111
	v_lshl_add_u64 v[18:19], v[18:19], 0, v[22:23]
	s_mov_b32 s1, 0x2320000
	v_add_co_u32_e32 v22, vcc, s1, v18
	s_mov_b64 s[8:9], 0x2320000
	s_nop 0
	v_addc_co_u32_e32 v23, vcc, 0, v19, vcc
	global_load_dwordx2 v[114:115], v[22:23], off
	v_lshl_add_u64 v[18:19], v[18:19], 0, s[8:9]
	global_load_dwordx2 v[116:117], v[18:19], off offset:512
	global_load_dwordx4 v[70:73], v[20:21], off offset:128
	v_and_b32_e32 v22, 0xffe0, v82
	v_lshrrev_b32_e32 v23, 1, v155
	global_load_dwordx4 v[74:77], v[20:21], off offset:256
	global_load_dwordx4 v[66:69], v[20:21], off offset:384
	v_add_u32_e32 v22, 0, v22
	v_and_b32_e32 v23, 0x7f0, v23
	v_add3_u32 v22, v22, v23, v24
	ds_write_b128 v25, v[50:53]
	ds_write_b128 v22, v[54:57]
	global_load_dwordx2 v[126:127], v[18:19], off offset:1024
	global_load_dwordx2 v[128:129], v[18:19], off offset:1536
	global_load_dwordx2 v[130:131], v[18:19], off offset:2048
	global_load_dwordx2 v[132:133], v[18:19], off offset:2560
	global_load_dwordx2 v[134:135], v[18:19], off offset:3072
	global_load_dwordx2 v[136:137], v[18:19], off offset:3584
	v_lshl_or_b32 v18, v149, 8, s2
	v_mov_b32_e32 v19, v111
	s_mov_b64 s[16:17], s[24:25]
	v_lshl_add_u64 v[20:21], s[14:15], 0, v[18:19]
	v_lshl_add_u64 v[18:19], s[16:17], 0, v[18:19]
	v_lshlrev_b32_e32 v78, 2, v112
	v_mov_b32_e32 v79, v111
	s_mov_b64 s[20:21], s[28:29]
	v_lshl_add_u64 v[20:21], v[20:21], 0, v[78:79]
	v_lshl_add_u64 v[18:19], v[18:19], 0, v[78:79]
	s_lshl_b32 s1, s0, 11
	global_load_dwordx4 v[58:61], v[20:21], off
	global_load_dwordx4 v[50:53], v[20:21], off offset:64
	global_load_dwordx4 v[62:65], v[18:19], off
	global_load_dwordx4 v[54:57], v[18:19], off offset:64
	global_load_dwordx4 v[42:45], v[20:21], off offset:128
	global_load_dwordx4 v[34:37], v[20:21], off offset:192
	global_load_dwordx4 v[46:49], v[18:19], off offset:128
	global_load_dwordx4 v[38:41], v[18:19], off offset:192
	s_add_u32 s8, s20, s1
	v_lshlrev_b32_e32 v18, 2, v149
	s_mov_b64 s[18:19], s[26:27]
	s_addc_u32 s9, s21, 0
	v_lshl_or_b32 v18, v145, 9, v18
	s_lshl_b32 s1, s0, 4
	s_lshl_b32 s2, s0, 6
	global_load_dword v191, v18, s[8:9]
	global_load_dword v161, v18, s[8:9] offset:64
	global_load_dword v193, v18, s[8:9] offset:128
	global_load_dword v190, v18, s[8:9] offset:192
	global_load_dword v195, v18, s[8:9] offset:256
	global_load_dword v192, v18, s[8:9] offset:320
	global_load_dword v196, v18, s[8:9] offset:384
	global_load_dword v194, v18, s[8:9] offset:448
	s_add_u32 s8, s18, s2
	s_mov_b64 s[22:23], s[30:31]
	s_addc_u32 s9, s19, 0
	s_lshl_b32 s2, s0, 7
	s_add_u32 s10, s22, s2
	s_movk_i32 s2, 0x210
	v_mul_lo_u32 v102, v144, s2
	v_add3_u32 v163, 0, v102, v153
	s_addc_u32 s11, s23, 0
	global_load_dwordx4 v[18:21], v78, s[8:9]
	global_load_dwordx4 v[22:25], v78, s[10:11]
	global_load_dwordx4 v[26:29], v78, s[10:11] offset:64
	v_readlane_b32 s36, v249, 0
	s_and_b32 s36, s36, 63
	s_lshl_b32 s36, s36, 9
	s_add_u32 s36, s36, 0x2308000
	s_add_u32 s36, s94, s36
	s_addc_u32 s37, s95, 0
	s_add_u32 s38, s36, 0x8000
	s_addc_u32 s39, s37, 0
	v_lshlrev_b32_e32 v238, 3, v162
	s_nop 1
	global_load_dwordx2 v[234:235], v238, s[36:37]
	global_load_dwordx2 v[236:237], v238, s[38:39]
	s_waitcnt lgkmcnt(0)
	s_barrier
; #define LAS __attribute__((address_space(3)))
; #define S5_UPDATE(K, hre, him, xq) do { const v2u xb_ = (xq); \
;     _Pragma("unroll") for (int j = 0; j < 4; ++j) { const f32x4 cre_ = K.ar[j] * hre[j] - K.ai[j] * him[j], cim_ = K.ar[j] * him[j] + K.ai[j] * hre[j]; \
;         hre[j] = MFMA16K16(K.Bf[2 * j], xb_, cre_); him[j] = MFMA16K16(K.Bf[2 * j + 1], xb_, cim_); } } while (0)
; __device__ __forceinline__ void s5_prompt_task(const Args& a, const Ctx& C, int b, int g, v4u (&xv)[8]) {
;     ...
;     f32x4 hre[4], him[4];
; #pragma unroll
;     for (int j = 0; j < 4; ++j) { hre[j] = (f32x4){0.f, 0.f, 0.f, 0.f}; him[j] = (f32x4){0.f, 0.f, 0.f, 0.f}; }
;     const LAS unsigned char* xsl = XS + chunk * 528 + q * 8;
;     for (int t = 0; t < 16; ++t) { const v2u xq = *(const LAS v2u*)(xsl + t * 32); S5_UPDATE(K, hre, him, xq); }
	ds_read2_b64 v[104:107], v163 offset1:4
	s_waitcnt vmcnt(32)
	v_mov_b32_e32 v78, v30
	v_mov_b32_e32 v79, v32
	v_mov_b32_e32 v80, v2
	v_mov_b32_e32 v81, v4
	v_pk_mul_f32 v[86:87], v[78:79], 0 op_sel_hi:[1,0]
	v_pk_mul_f32 v[90:91], v[80:81], 0 op_sel_hi:[1,0]
	v_xor_b32_e32 v83, 0x80000000, v33
	v_xor_b32_e32 v82, 0x80000000, v31
	v_xor_b32_e32 v85, 0x80000000, v5
	v_xor_b32_e32 v84, 0x80000000, v3
	v_mov_b32_e32 v118, v3
	v_pk_fma_f32 v[82:83], v[82:83], 0, v[86:87] op_sel_hi:[1,0,1]
	v_pk_fma_f32 v[84:85], v[84:85], 0, v[90:91] op_sel_hi:[1,0,1]
	v_mov_b32_e32 v88, v31
	v_mov_b32_e32 v89, v33
	v_mov_b32_e32 v119, v5
	s_waitcnt vmcnt(31) lgkmcnt(0)
	v_mfma_f32_16x16x16_bf16 v[138:141], v[114:115], v[104:105], v[82:85]
	s_nop 2
	v_fma_f32 v82, v88, 0, v86
	v_fma_f32 v83, v89, 0, v87
	v_pk_fma_f32 v[84:85], v[118:119], 0, v[90:91] op_sel_hi:[1,0,1]
	v_mov_b32_e32 v86, v6
	v_mov_b32_e32 v87, v8
	s_waitcnt vmcnt(30)
	v_mfma_f32_16x16x16_bf16 v[146:149], v[116:117], v[104:105], v[82:85]
	v_mul_f32_e64 v94, v86, 0
	v_mul_f32_e64 v95, v87, 0
	v_xor_b32_e32 v91, 0x80000000, v9
	v_xor_b32_e32 v90, 0x80000000, v7
	s_waitcnt vmcnt(29)
	v_mov_b32_e32 v82, v70
	v_mov_b32_e32 v83, v72
	v_mov_b32_e32 v120, v7
	v_pk_mul_f32 v[84:85], v[82:83], 0 op_sel_hi:[1,0]
	v_pk_fma_f32 v[92:93], v[90:91], 0, v[94:95] op_sel_hi:[1,0,1]
	v_xor_b32_e32 v91, 0x80000000, v73
	v_xor_b32_e32 v90, 0x80000000, v71
	v_mov_b32_e32 v121, v9
	v_pk_fma_f32 v[90:91], v[90:91], 0, v[84:85] op_sel_hi:[1,0,1]
	v_pk_fma_f32 v[98:99], v[120:121], 0, v[94:95] op_sel_hi:[1,0,1]
	v_mov_b32_e32 v94, v71
	v_mov_b32_e32 v95, v73
	s_waitcnt vmcnt(26)
	v_mfma_f32_16x16x16_bf16 v[150:153], v[126:127], v[104:105], v[90:93]
	v_fma_f32 v96, v94, 0, v84
	v_fma_f32 v97, v95, 0, v85
	v_mov_b32_e32 v84, v74
	v_mov_b32_e32 v85, v76
	v_mov_b32_e32 v92, v10
	v_mov_b32_e32 v93, v12
	s_waitcnt vmcnt(25)
	v_mfma_f32_16x16x16_bf16 v[154:157], v[128:129], v[104:105], v[96:99]
	v_mul_f32_e64 v100, v92, 0
	v_mul_f32_e64 v101, v93, 0
	v_pk_mul_f32 v[90:91], v[84:85], 0 op_sel_hi:[1,0]
	v_mov_b32_e32 v122, v11
	v_xor_b32_e32 v97, 0x80000000, v13
	v_xor_b32_e32 v96, 0x80000000, v11
	v_pk_fma_f32 v[98:99], v[96:97], 0, v[100:101] op_sel_hi:[1,0,1]
	v_xor_b32_e32 v97, 0x80000000, v77
	v_xor_b32_e32 v96, 0x80000000, v75
	v_pk_fma_f32 v[96:97], v[96:97], 0, v[90:91] op_sel_hi:[1,0,1]
	v_mov_b32_e32 v123, v13
	v_pk_fma_f32 v[166:167], v[122:123], 0, v[100:101] op_sel_hi:[1,0,1]
	s_waitcnt vmcnt(24)
	v_mfma_f32_16x16x16_bf16 v[168:171], v[130:131], v[104:105], v[96:99]
	v_xor_b32_e32 v143, 0x80000000, v17
	v_xor_b32_e32 v142, 0x80000000, v15
	v_mov_b32_e32 v124, v15
	v_mov_b32_e32 v98, v75
	v_mov_b32_e32 v99, v77
	v_mov_b32_e32 v96, v14
	v_mov_b32_e32 v97, v16
	v_pk_fma_f32 v[164:165], v[98:99], 0, v[90:91] op_sel_hi:[1,0,1]
	v_mov_b32_e32 v90, v66
	v_mov_b32_e32 v91, v68
	v_pk_mul_f32 v[100:101], v[96:97], 0 op_sel_hi:[1,0]
	v_pk_mul_f32 v[108:109], v[90:91], 0 op_sel_hi:[1,0]
	v_pk_fma_f32 v[174:175], v[142:143], 0, v[100:101] op_sel_hi:[1,0,1]
	v_xor_b32_e32 v143, 0x80000000, v69
	v_xor_b32_e32 v142, 0x80000000, v67
	v_mov_b32_e32 v125, v17
	v_pk_fma_f32 v[172:173], v[142:143], 0, v[108:109] op_sel_hi:[1,0,1]
	v_pk_fma_f32 v[176:177], v[124:125], 0, v[100:101] op_sel_hi:[1,0,1]
	v_mov_b32_e32 v100, v67
	v_mov_b32_e32 v101, v69
	s_waitcnt vmcnt(22)
	v_mfma_f32_16x16x16_bf16 v[178:181], v[134:135], v[104:105], v[172:175]
	s_add_i32 s8, 0, 0x10800
	v_add_u32_e32 v3, s8, v102
	v_lshlrev_b32_e32 v7, 5, v145
	v_pk_fma_f32 v[174:175], v[100:101], 0, v[108:109] op_sel_hi:[1,0,1]
	v_mfma_f32_16x16x16_bf16 v[164:167], v[132:133], v[104:105], v[164:167]
	v_mul_f32_e64 v108, v88, v146
	v_mul_f32_e64 v109, v89, v147
	v_add_u32_e32 v3, v3, v7
	v_pk_fma_f32 v[182:183], v[78:79], v[138:139], v[108:109] neg_lo:[0,0,1] neg_hi:[0,0,1]
	s_waitcnt vmcnt(21)
	v_mfma_f32_16x16x16_bf16 v[172:175], v[136:137], v[104:105], v[174:177]
	v_mul_f32_e64 v104, v118, v148
	v_mul_f32_e64 v105, v119, v149
	v_pk_mul_f32 v[108:109], v[78:79], v[146:147]
	v_pk_fma_f32 v[184:185], v[80:81], v[140:141], v[104:105] neg_lo:[0,0,1] neg_hi:[0,0,1]
	v_pk_mul_f32 v[104:105], v[80:81], v[148:149]
	v_pk_fma_f32 v[138:139], v[88:89], v[138:139], v[108:109]
	v_pk_fma_f32 v[140:141], v[118:119], v[140:141], v[104:105]
	v_pk_mul_f32 v[104:105], v[120:121], v[156:157]
	v_pk_mul_f32 v[108:109], v[94:95], v[154:155]
	v_pk_fma_f32 v[148:149], v[86:87], v[152:153], v[104:105] neg_lo:[0,0,1] neg_hi:[0,0,1]
	v_pk_fma_f32 v[146:147], v[82:83], v[150:151], v[108:109] neg_lo:[0,0,1] neg_hi:[0,0,1]
	v_pk_mul_f32 v[104:105], v[86:87], v[156:157]
	v_pk_mul_f32 v[108:109], v[82:83], v[154:155]
	v_pk_fma_f32 v[152:153], v[120:121], v[152:153], v[104:105]
	v_pk_fma_f32 v[150:151], v[94:95], v[150:151], v[108:109]
	v_pk_mul_f32 v[104:105], v[122:123], v[166:167]
	v_pk_mul_f32 v[108:109], v[98:99], v[164:165]
	v_pk_fma_f32 v[156:157], v[92:93], v[170:171], v[104:105] neg_lo:[0,0,1] neg_hi:[0,0,1]
	v_pk_fma_f32 v[154:155], v[84:85], v[168:169], v[108:109] neg_lo:[0,0,1] neg_hi:[0,0,1]
	v_pk_mul_f32 v[104:105], v[92:93], v[166:167]
	v_pk_mul_f32 v[108:109], v[84:85], v[164:165]
	v_pk_fma_f32 v[166:167], v[122:123], v[170:171], v[104:105]
	v_pk_fma_f32 v[164:165], v[98:99], v[168:169], v[108:109]
	v_pk_mul_f32 v[104:105], v[124:125], v[174:175]
	v_pk_mul_f32 v[108:109], v[100:101], v[172:173]
	v_pk_fma_f32 v[170:171], v[96:97], v[180:181], v[104:105] neg_lo:[0,0,1] neg_hi:[0,0,1]
	v_pk_fma_f32 v[168:169], v[90:91], v[178:179], v[108:109] neg_lo:[0,0,1] neg_hi:[0,0,1]
	v_pk_mul_f32 v[104:105], v[96:97], v[174:175]
	v_pk_mul_f32 v[108:109], v[90:91], v[172:173]
	v_mfma_f32_16x16x16_bf16 v[138:141], v[116:117], v[106:107], v[138:141]
	v_fma_f32 v174, v124, v180, v104
	v_fma_f32 v175, v125, v181, v105
	v_pk_fma_f32 v[172:173], v[100:101], v[178:179], v[108:109]
	s_add_u32 s4, s94, s4
	v_mfma_f32_16x16x16_bf16 v[182:185], v[114:115], v[106:107], v[182:185]
	s_addc_u32 s5, s95, s5
	s_nop 1
	v_pk_mul_f32 v[108:109], v[118:119], v[140:141]
	v_pk_mul_f32 v[142:143], v[88:89], v[138:139]
	v_mfma_f32_16x16x16_bf16 v[146:149], v[126:127], v[106:107], v[146:149]
	v_mul_f32_e64 v138, v78, v138
	v_mul_f32_e64 v139, v79, v139
	v_pk_fma_f32 v[178:179], v[80:81], v[184:185], v[108:109] neg_lo:[0,0,1] neg_hi:[0,0,1]
	v_pk_fma_f32 v[176:177], v[78:79], v[182:183], v[142:143] neg_lo:[0,0,1] neg_hi:[0,0,1]
	v_mfma_f32_16x16x16_bf16 v[150:153], v[128:129], v[106:107], v[150:153]
	v_mul_f32_e64 v108, v80, v140
	v_mul_f32_e64 v109, v81, v141
	v_lshlrev_b32_e32 v7, 4, v144
	s_mov_b32 s2, 0x2308000
	v_mfma_f32_16x16x16_bf16 v[154:157], v[130:131], v[106:107], v[154:157]
	v_mov_b32_e32 v160, v111
	v_mfma_f32_16x16x16_bf16 v[164:167], v[132:133], v[106:107], v[164:167]
	v_mfma_f32_16x16x16_bf16 v[168:171], v[134:135], v[106:107], v[168:171]
	v_mfma_f32_16x16x16_bf16 v[104:107], v[136:137], v[106:107], v[172:175]
	s_nop 2
	ds_read2_b64 v[172:175], v163 offset0:8 offset1:12
	s_waitcnt lgkmcnt(0)
; #define LAS __attribute__((address_space(3)))
; #define S5_UPDATE(K, hre, him, xq) do { const v2u xb_ = (xq); \
;     _Pragma("unroll") for (int j = 0; j < 4; ++j) { const f32x4 cre_ = K.ar[j] * hre[j] - K.ai[j] * him[j], cim_ = K.ar[j] * him[j] + K.ai[j] * hre[j]; \
;         hre[j] = MFMA16K16(K.Bf[2 * j], xb_, cre_); him[j] = MFMA16K16(K.Bf[2 * j + 1], xb_, cim_); } } while (0)
; __device__ __forceinline__ void s5_prompt_task(const Args& a, const Ctx& C, int b, int g, v4u (&xv)[8]) {
;     ...
;     f32x4 hre[4], him[4];
; #pragma unroll
;     for (int j = 0; j < 4; ++j) { hre[j] = (f32x4){0.f, 0.f, 0.f, 0.f}; him[j] = (f32x4){0.f, 0.f, 0.f, 0.f}; }
;     const LAS unsigned char* xsl = XS + chunk * 528 + q * 8;
;     for (int t = 0; t < 16; ++t) { const v2u xq = *(const LAS v2u*)(xsl + t * 32); S5_UPDATE(K, hre, him, xq); }
	v_mfma_f32_16x16x16_bf16 v[140:143], v[114:115], v[172:173], v[176:179]
	s_nop 2
	v_fma_f32 v178, v118, v184, v108
	v_fma_f32 v179, v119, v185, v109
	v_pk_fma_f32 v[176:177], v[88:89], v[182:183], v[138:139]
	v_pk_mul_f32 v[108:109], v[120:121], v[152:153]
	v_pk_mul_f32 v[138:139], v[94:95], v[150:151]
	v_pk_fma_f32 v[182:183], v[86:87], v[148:149], v[108:109] neg_lo:[0,0,1] neg_hi:[0,0,1]
	v_pk_fma_f32 v[180:181], v[82:83], v[146:147], v[138:139] neg_lo:[0,0,1] neg_hi:[0,0,1]
	v_pk_mul_f32 v[108:109], v[86:87], v[152:153]
	v_pk_mul_f32 v[138:139], v[82:83], v[150:151]
	v_mfma_f32_16x16x16_bf16 v[176:179], v[116:117], v[172:173], v[176:179]
	v_fma_f32 v148, v120, v148, v108
	v_fma_f32 v149, v121, v149, v109
	v_pk_fma_f32 v[146:147], v[94:95], v[146:147], v[138:139]
	v_pk_mul_f32 v[108:109], v[122:123], v[166:167]
	v_pk_mul_f32 v[138:139], v[98:99], v[164:165]
	v_pk_fma_f32 v[152:153], v[92:93], v[156:157], v[108:109] neg_lo:[0,0,1] neg_hi:[0,0,1]
	v_pk_fma_f32 v[150:151], v[84:85], v[154:155], v[138:139] neg_lo:[0,0,1] neg_hi:[0,0,1]
	v_pk_mul_f32 v[108:109], v[92:93], v[166:167]
	v_pk_mul_f32 v[138:139], v[84:85], v[164:165]
	v_pk_fma_f32 v[156:157], v[122:123], v[156:157], v[108:109]
	v_pk_fma_f32 v[154:155], v[98:99], v[154:155], v[138:139]
	v_pk_mul_f32 v[108:109], v[124:125], v[106:107]
	v_pk_mul_f32 v[138:139], v[100:101], v[104:105]
	v_mfma_f32_16x16x16_bf16 v[146:149], v[128:129], v[172:173], v[146:149]
	v_fma_f32 v166, v96, v170, -v108
	v_fma_f32 v167, v97, v171, -v109
	v_pk_fma_f32 v[164:165], v[90:91], v[168:169], v[138:139] neg_lo:[0,0,1] neg_hi:[0,0,1]
	v_pk_mul_f32 v[138:139], v[96:97], v[106:107]
	v_pk_mul_f32 v[104:105], v[90:91], v[104:105]
	v_mfma_f32_16x16x16_bf16 v[180:183], v[126:127], v[172:173], v[180:183]
	v_mfma_f32_16x16x16_bf16 v[106:109], v[134:135], v[172:173], v[164:167]
	s_nop 2
	v_fma_f32 v166, v124, v170, v138
	v_fma_f32 v167, v125, v171, v139
	v_pk_fma_f32 v[164:165], v[100:101], v[168:169], v[104:105]
	v_pk_mul_f32 v[104:105], v[118:119], v[178:179]
	v_pk_mul_f32 v[138:139], v[88:89], v[176:177]
	v_mfma_f32_16x16x16_bf16 v[154:157], v[132:133], v[172:173], v[154:157]
	v_fma_f32 v170, v80, v142, -v104
	v_fma_f32 v171, v81, v143, -v105
	v_pk_fma_f32 v[168:169], v[78:79], v[140:141], v[138:139] neg_lo:[0,0,1] neg_hi:[0,0,1]
	v_pk_mul_f32 v[104:105], v[80:81], v[178:179]
	v_pk_mul_f32 v[138:139], v[78:79], v[176:177]
	v_mfma_f32_16x16x16_bf16 v[150:153], v[130:131], v[172:173], v[150:153]
	v_fma_f32 v142, v118, v142, v104
	v_fma_f32 v143, v119, v143, v105
	v_pk_fma_f32 v[140:141], v[88:89], v[140:141], v[138:139]
	v_pk_mul_f32 v[104:105], v[120:121], v[148:149]
	v_mfma_f32_16x16x16_bf16 v[164:167], v[136:137], v[172:173], v[164:167]
	v_fma_f32 v178, v86, v182, -v104
	v_fma_f32 v179, v87, v183, -v105
	v_pk_mul_f32 v[104:105], v[86:87], v[148:149]
	v_mfma_f32_16x16x16_bf16 v[138:141], v[116:117], v[174:175], v[140:143]
	v_fma_f32 v148, v120, v182, v104
	v_fma_f32 v149, v121, v183, v105
	v_pk_mul_f32 v[104:105], v[122:123], v[156:157]
	v_pk_mul_f32 v[142:143], v[94:95], v[146:147]
	v_pk_fma_f32 v[182:183], v[92:93], v[152:153], v[104:105] neg_lo:[0,0,1] neg_hi:[0,0,1]
	v_pk_fma_f32 v[176:177], v[82:83], v[180:181], v[142:143] neg_lo:[0,0,1] neg_hi:[0,0,1]
	v_pk_mul_f32 v[142:143], v[82:83], v[146:147]
	v_pk_mul_f32 v[104:105], v[92:93], v[156:157]
	v_pk_fma_f32 v[146:147], v[94:95], v[180:181], v[142:143]
	v_pk_mul_f32 v[142:143], v[98:99], v[154:155]
	v_mfma_f32_16x16x16_bf16 v[168:171], v[114:115], v[174:175], v[168:171]
	v_fma_f32 v180, v84, v150, -v142
	v_fma_f32 v181, v85, v151, -v143
	v_pk_mul_f32 v[142:143], v[84:85], v[154:155]
	v_pk_fma_f32 v[152:153], v[122:123], v[152:153], v[104:105]
	v_pk_fma_f32 v[150:151], v[98:99], v[150:151], v[142:143]
	v_pk_mul_f32 v[104:105], v[124:125], v[166:167]
	v_pk_mul_f32 v[142:143], v[100:101], v[164:165]
	v_mfma_f32_16x16x16_bf16 v[146:149], v[128:129], v[174:175], v[146:149]
	v_mfma_f32_16x16x16_bf16 v[156:159], v[130:131], v[174:175], v[180:183]
	s_nop 2
	v_fma_f32 v182, v96, v108, -v104
	v_fma_f32 v183, v97, v109, -v105
	v_pk_fma_f32 v[180:181], v[90:91], v[106:107], v[142:143] neg_lo:[0,0,1] neg_hi:[0,0,1]
	v_pk_mul_f32 v[104:105], v[96:97], v[166:167]
	v_pk_mul_f32 v[142:143], v[90:91], v[164:165]
	ds_read2_b64 v[164:167], v163 offset0:16 offset1:20
	v_mfma_f32_16x16x16_bf16 v[176:179], v[126:127], v[174:175], v[176:179]
	v_fma_f32 v108, v124, v108, v104
	v_fma_f32 v109, v125, v109, v105
	v_pk_fma_f32 v[106:107], v[100:101], v[106:107], v[142:143]
	v_pk_mul_f32 v[142:143], v[88:89], v[138:139]
	v_mfma_f32_16x16x16_bf16 v[150:153], v[132:133], v[174:175], v[150:153]
	v_mul_f32_e64 v138, v78, v138
	v_mul_f32_e64 v139, v79, v139
	v_pk_fma_f32 v[172:173], v[78:79], v[168:169], v[142:143] neg_lo:[0,0,1] neg_hi:[0,0,1]
	v_pk_fma_f32 v[168:169], v[88:89], v[168:169], v[138:139]
	v_mfma_f32_16x16x16_bf16 v[104:107], v[136:137], v[174:175], v[106:109]
	v_mul_f32_e64 v138, v94, v146
	v_mul_f32_e64 v139, v95, v147
	s_nop 0
	v_pk_mul_f32 v[108:109], v[118:119], v[140:141]
	v_mfma_f32_16x16x16_bf16 v[180:183], v[134:135], v[174:175], v[180:183]
	v_fma_f32 v174, v80, v170, -v108
	v_fma_f32 v175, v81, v171, -v109
	v_pk_mul_f32 v[108:109], v[80:81], v[140:141]
	s_nop 0
	v_pk_fma_f32 v[170:171], v[118:119], v[170:171], v[108:109]
	v_pk_mul_f32 v[108:109], v[120:121], v[148:149]
	s_waitcnt lgkmcnt(0)
; #define LAS __attribute__((address_space(3)))
; #define S5_UPDATE(K, hre, him, xq) do { const v2u xb_ = (xq); \
;     _Pragma("unroll") for (int j = 0; j < 4; ++j) { const f32x4 cre_ = K.ar[j] * hre[j] - K.ai[j] * him[j], cim_ = K.ar[j] * him[j] + K.ai[j] * hre[j]; \
;         hre[j] = MFMA16K16(K.Bf[2 * j], xb_, cre_); him[j] = MFMA16K16(K.Bf[2 * j + 1], xb_, cim_); } } while (0)
; __device__ __forceinline__ void s5_prompt_task(const Args& a, const Ctx& C, int b, int g, v4u (&xv)[8]) {
;     ...
;     f32x4 hre[4], him[4];
; #pragma unroll
;     for (int j = 0; j < 4; ++j) { hre[j] = (f32x4){0.f, 0.f, 0.f, 0.f}; him[j] = (f32x4){0.f, 0.f, 0.f, 0.f}; }
;     const LAS unsigned char* xsl = XS + chunk * 528 + q * 8;
;     for (int t = 0; t < 16; ++t) { const v2u xq = *(const LAS v2u*)(xsl + t * 32); S5_UPDATE(K, hre, him, xq); }
	v_mfma_f32_16x16x16_bf16 v[140:143], v[114:115], v[164:165], v[172:175]
	s_nop 2
	v_fma_f32 v174, v86, v178, -v108
	v_fma_f32 v175, v87, v179, -v109
	v_pk_fma_f32 v[172:173], v[82:83], v[176:177], v[138:139] neg_lo:[0,0,1] neg_hi:[0,0,1]
	v_pk_mul_f32 v[108:109], v[86:87], v[148:149]
	v_pk_mul_f32 v[138:139], v[82:83], v[146:147]
	v_mfma_f32_16x16x16_bf16 v[168:171], v[116:117], v[164:165], v[168:171]
	v_fma_f32 v148, v120, v178, v108
	v_fma_f32 v149, v121, v179, v109
	v_pk_fma_f32 v[146:147], v[94:95], v[176:177], v[138:139]
	v_pk_mul_f32 v[108:109], v[122:123], v[152:153]
	v_pk_mul_f32 v[138:139], v[98:99], v[150:151]
	v_pk_fma_f32 v[178:179], v[92:93], v[158:159], v[108:109] neg_lo:[0,0,1] neg_hi:[0,0,1]
	v_pk_fma_f32 v[176:177], v[84:85], v[156:157], v[138:139] neg_lo:[0,0,1] neg_hi:[0,0,1]
	v_pk_mul_f32 v[108:109], v[92:93], v[152:153]
	v_pk_mul_f32 v[138:139], v[84:85], v[150:151]
	v_pk_fma_f32 v[158:159], v[122:123], v[158:159], v[108:109]
	v_pk_fma_f32 v[156:157], v[98:99], v[156:157], v[138:139]
	v_pk_mul_f32 v[108:109], v[124:125], v[106:107]
	v_pk_mul_f32 v[138:139], v[100:101], v[104:105]
	v_mfma_f32_16x16x16_bf16 v[146:149], v[128:129], v[164:165], v[146:149]
	v_mul_f32_e64 v104, v90, v104
	v_mul_f32_e64 v105, v91, v105
	v_mfma_f32_16x16x16_bf16 v[152:155], v[130:131], v[164:165], v[176:179]
	s_nop 2
	v_fma_f32 v178, v96, v182, -v108
	v_fma_f32 v179, v97, v183, -v109
	v_pk_fma_f32 v[176:177], v[90:91], v[180:181], v[138:139] neg_lo:[0,0,1] neg_hi:[0,0,1]
	v_pk_mul_f32 v[138:139], v[96:97], v[106:107]
	v_mfma_f32_16x16x16_bf16 v[172:175], v[126:127], v[164:165], v[172:175]
	v_mfma_f32_16x16x16_bf16 v[106:109], v[134:135], v[164:165], v[176:179]
	s_nop 2
	v_fma_f32 v178, v124, v182, v138
	v_fma_f32 v179, v125, v183, v139
	v_pk_fma_f32 v[176:177], v[100:101], v[180:181], v[104:105]
	v_pk_mul_f32 v[104:105], v[118:119], v[170:171]
	v_pk_mul_f32 v[138:139], v[88:89], v[168:169]
	v_mfma_f32_16x16x16_bf16 v[156:159], v[132:133], v[164:165], v[156:159]
	v_fma_f32 v182, v80, v142, -v104
	v_fma_f32 v183, v81, v143, -v105
	v_pk_fma_f32 v[180:181], v[78:79], v[140:141], v[138:139] neg_lo:[0,0,1] neg_hi:[0,0,1]
	v_pk_mul_f32 v[104:105], v[80:81], v[170:171]
	v_pk_mul_f32 v[138:139], v[78:79], v[168:169]
	v_pk_fma_f32 v[142:143], v[118:119], v[142:143], v[104:105]
	v_pk_fma_f32 v[140:141], v[88:89], v[140:141], v[138:139]
	v_mfma_f32_16x16x16_bf16 v[176:179], v[136:137], v[164:165], v[176:179]
	v_mul_f32_e64 v104, v120, v148
	v_mul_f32_e64 v105, v121, v149
	v_pk_fma_f32 v[170:171], v[86:87], v[174:175], v[104:105] neg_lo:[0,0,1] neg_hi:[0,0,1]
	v_mfma_f32_16x16x16_bf16 v[138:141], v[116:117], v[166:167], v[140:143]
	v_mul_f32_e64 v104, v86, v148
	v_mul_f32_e64 v105, v87, v149
	s_nop 0
	v_pk_mul_f32 v[142:143], v[94:95], v[146:147]
	v_mfma_f32_16x16x16_bf16 v[180:183], v[114:115], v[166:167], v[180:183]
	v_fma_f32 v168, v82, v172, -v142
	v_fma_f32 v169, v83, v173, -v143
	v_pk_mul_f32 v[142:143], v[82:83], v[146:147]
	s_nop 0
	v_mfma_f32_16x16x16_bf16 v[148:151], v[126:127], v[166:167], v[168:171]
	s_nop 2
	v_fma_f32 v170, v120, v174, v104
	v_fma_f32 v171, v121, v175, v105
	v_pk_fma_f32 v[168:169], v[94:95], v[172:173], v[142:143]
	v_pk_mul_f32 v[104:105], v[122:123], v[158:159]
	v_pk_mul_f32 v[142:143], v[98:99], v[156:157]
	v_pk_fma_f32 v[174:175], v[92:93], v[154:155], v[104:105] neg_lo:[0,0,1] neg_hi:[0,0,1]
	v_pk_fma_f32 v[172:173], v[84:85], v[152:153], v[142:143] neg_lo:[0,0,1] neg_hi:[0,0,1]
	v_pk_mul_f32 v[104:105], v[92:93], v[158:159]
	v_pk_mul_f32 v[142:143], v[84:85], v[156:157]
	v_pk_fma_f32 v[154:155], v[122:123], v[154:155], v[104:105]
	v_pk_fma_f32 v[152:153], v[98:99], v[152:153], v[142:143]
	v_pk_mul_f32 v[104:105], v[124:125], v[178:179]
	v_pk_mul_f32 v[142:143], v[100:101], v[176:177]
	v_pk_fma_f32 v[158:159], v[96:97], v[108:109], v[104:105] neg_lo:[0,0,1] neg_hi:[0,0,1]
	v_pk_fma_f32 v[156:157], v[90:91], v[106:107], v[142:143] neg_lo:[0,0,1] neg_hi:[0,0,1]
	v_pk_mul_f32 v[104:105], v[96:97], v[178:179]
	v_pk_mul_f32 v[142:143], v[90:91], v[176:177]
	v_pk_fma_f32 v[108:109], v[124:125], v[108:109], v[104:105]
	v_pk_fma_f32 v[106:107], v[100:101], v[106:107], v[142:143]
	v_mfma_f32_16x16x16_bf16 v[168:171], v[128:129], v[166:167], v[168:171]
	v_mul_f32_e64 v142, v88, v138
	v_mul_f32_e64 v143, v89, v139
	v_pk_mul_f32 v[138:139], v[78:79], v[138:139]
	v_pk_fma_f32 v[176:177], v[78:79], v[180:181], v[142:143] neg_lo:[0,0,1] neg_hi:[0,0,1]
	v_mfma_f32_16x16x16_bf16 v[172:175], v[130:131], v[166:167], v[172:175]
	v_mfma_f32_16x16x16_bf16 v[152:155], v[132:133], v[166:167], v[152:155]
	v_mfma_f32_16x16x16_bf16 v[156:159], v[134:135], v[166:167], v[156:159]
	v_mfma_f32_16x16x16_bf16 v[104:107], v[136:137], v[166:167], v[106:109]
	ds_read2_b64 v[164:167], v163 offset0:24 offset1:28
	s_nop 1
	v_pk_mul_f32 v[108:109], v[118:119], v[140:141]
	s_nop 0
	v_pk_fma_f32 v[178:179], v[80:81], v[182:183], v[108:109] neg_lo:[0,0,1] neg_hi:[0,0,1]
	v_pk_mul_f32 v[108:109], v[80:81], v[140:141]
	s_waitcnt lgkmcnt(0)
; #define LAS __attribute__((address_space(3)))
; #define S5_UPDATE(K, hre, him, xq) do { const v2u xb_ = (xq); \
;     _Pragma("unroll") for (int j = 0; j < 4; ++j) { const f32x4 cre_ = K.ar[j] * hre[j] - K.ai[j] * him[j], cim_ = K.ar[j] * him[j] + K.ai[j] * hre[j]; \
;         hre[j] = MFMA16K16(K.Bf[2 * j], xb_, cre_); him[j] = MFMA16K16(K.Bf[2 * j + 1], xb_, cim_); } } while (0)
; __device__ __forceinline__ void s5_prompt_task(const Args& a, const Ctx& C, int b, int g, v4u (&xv)[8]) {
;     ...
;     f32x4 hre[4], him[4];
; #pragma unroll
;     for (int j = 0; j < 4; ++j) { hre[j] = (f32x4){0.f, 0.f, 0.f, 0.f}; him[j] = (f32x4){0.f, 0.f, 0.f, 0.f}; }
;     const LAS unsigned char* xsl = XS + chunk * 528 + q * 8;
;     for (int t = 0; t < 16; ++t) { const v2u xq = *(const LAS v2u*)(xsl + t * 32); S5_UPDATE(K, hre, him, xq); }
	v_mfma_f32_16x16x16_bf16 v[140:143], v[114:115], v[164:165], v[176:179]
	s_nop 2
	v_fma_f32 v176, v88, v180, v138
	v_fma_f32 v177, v89, v181, v139
	v_pk_mul_f32 v[138:139], v[94:95], v[168:169]
	v_pk_fma_f32 v[178:179], v[118:119], v[182:183], v[108:109]
	v_pk_mul_f32 v[108:109], v[120:121], v[170:171]
	v_pk_fma_f32 v[180:181], v[82:83], v[148:149], v[138:139] neg_lo:[0,0,1] neg_hi:[0,0,1]
	v_pk_mul_f32 v[138:139], v[82:83], v[168:169]
	v_mfma_f32_16x16x16_bf16 v[176:179], v[116:117], v[164:165], v[176:179]
	v_fma_f32 v182, v86, v150, -v108
	v_fma_f32 v183, v87, v151, -v109
	v_pk_mul_f32 v[108:109], v[86:87], v[170:171]
	v_pk_fma_f32 v[148:149], v[94:95], v[148:149], v[138:139]
	v_pk_mul_f32 v[138:139], v[98:99], v[152:153]
	v_pk_fma_f32 v[150:151], v[120:121], v[150:151], v[108:109]
	v_pk_mul_f32 v[108:109], v[122:123], v[154:155]
	v_pk_fma_f32 v[168:169], v[84:85], v[172:173], v[138:139] neg_lo:[0,0,1] neg_hi:[0,0,1]
	v_pk_mul_f32 v[138:139], v[84:85], v[152:153]
	v_mfma_f32_16x16x16_bf16 v[146:149], v[128:129], v[164:165], v[148:151]
	v_fma_f32 v170, v92, v174, -v108
	v_fma_f32 v171, v93, v175, -v109
	v_pk_mul_f32 v[108:109], v[92:93], v[154:155]
	v_pk_fma_f32 v[150:151], v[98:99], v[172:173], v[138:139]
	v_pk_mul_f32 v[138:139], v[100:101], v[104:105]
	v_pk_fma_f32 v[152:153], v[122:123], v[174:175], v[108:109]
	v_pk_mul_f32 v[108:109], v[124:125], v[106:107]
	v_pk_fma_f32 v[172:173], v[90:91], v[156:157], v[138:139] neg_lo:[0,0,1] neg_hi:[0,0,1]
	v_pk_mul_f32 v[138:139], v[96:97], v[106:107]
	v_pk_mul_f32 v[104:105], v[90:91], v[104:105]
	v_mfma_f32_16x16x16_bf16 v[180:183], v[126:127], v[164:165], v[180:183]
	v_fma_f32 v174, v96, v158, -v108
	v_fma_f32 v175, v97, v159, -v109
	v_pk_fma_f32 v[158:159], v[124:125], v[158:159], v[138:139]
	v_pk_fma_f32 v[156:157], v[100:101], v[156:157], v[104:105]
	v_pk_mul_f32 v[104:105], v[118:119], v[178:179]
	v_pk_mul_f32 v[138:139], v[88:89], v[176:177]
	v_mfma_f32_16x16x16_bf16 v[150:153], v[132:133], v[164:165], v[150:153]
	v_mfma_f32_16x16x16_bf16 v[106:109], v[134:135], v[164:165], v[172:175]
	s_nop 2
	v_fma_f32 v174, v80, v142, -v104
	v_fma_f32 v175, v81, v143, -v105
	v_pk_fma_f32 v[172:173], v[78:79], v[140:141], v[138:139] neg_lo:[0,0,1] neg_hi:[0,0,1]
	v_pk_mul_f32 v[104:105], v[80:81], v[178:179]
	v_pk_mul_f32 v[138:139], v[78:79], v[176:177]
	v_mfma_f32_16x16x16_bf16 v[168:171], v[130:131], v[164:165], v[168:171]
	v_fma_f32 v142, v118, v142, v104
	v_fma_f32 v143, v119, v143, v105
	v_pk_fma_f32 v[140:141], v[88:89], v[140:141], v[138:139]
	v_pk_mul_f32 v[104:105], v[120:121], v[148:149]
	v_mfma_f32_16x16x16_bf16 v[154:157], v[136:137], v[164:165], v[156:159]
	v_fma_f32 v178, v86, v182, -v104
	v_fma_f32 v179, v87, v183, -v105
	v_pk_mul_f32 v[104:105], v[86:87], v[148:149]
	v_mfma_f32_16x16x16_bf16 v[138:141], v[116:117], v[166:167], v[140:143]
	v_fma_f32 v148, v120, v182, v104
	v_fma_f32 v149, v121, v183, v105
	v_pk_mul_f32 v[104:105], v[122:123], v[152:153]
	v_pk_mul_f32 v[142:143], v[94:95], v[146:147]
	v_pk_fma_f32 v[182:183], v[92:93], v[170:171], v[104:105] neg_lo:[0,0,1] neg_hi:[0,0,1]
	v_pk_fma_f32 v[176:177], v[82:83], v[180:181], v[142:143] neg_lo:[0,0,1] neg_hi:[0,0,1]
	v_pk_mul_f32 v[142:143], v[82:83], v[146:147]
	v_pk_mul_f32 v[104:105], v[92:93], v[152:153]
	v_pk_fma_f32 v[146:147], v[94:95], v[180:181], v[142:143]
	v_pk_mul_f32 v[142:143], v[98:99], v[150:151]
	v_pk_fma_f32 v[152:153], v[122:123], v[170:171], v[104:105]
	v_pk_fma_f32 v[180:181], v[84:85], v[168:169], v[142:143] neg_lo:[0,0,1] neg_hi:[0,0,1]
	v_pk_mul_f32 v[142:143], v[84:85], v[150:151]
	v_pk_mul_f32 v[104:105], v[124:125], v[156:157]
	v_pk_fma_f32 v[150:151], v[98:99], v[168:169], v[142:143]
	v_pk_mul_f32 v[142:143], v[100:101], v[154:155]
	v_pk_fma_f32 v[170:171], v[96:97], v[108:109], v[104:105] neg_lo:[0,0,1] neg_hi:[0,0,1]
	v_pk_fma_f32 v[168:169], v[90:91], v[106:107], v[142:143] neg_lo:[0,0,1] neg_hi:[0,0,1]
	v_pk_mul_f32 v[104:105], v[96:97], v[156:157]
	v_pk_mul_f32 v[142:143], v[90:91], v[154:155]
	v_pk_fma_f32 v[108:109], v[124:125], v[108:109], v[104:105]
	v_pk_fma_f32 v[106:107], v[100:101], v[106:107], v[142:143]
	v_mfma_f32_16x16x16_bf16 v[172:175], v[114:115], v[166:167], v[172:175]
	v_mul_f32_e64 v142, v88, v138
	v_mul_f32_e64 v143, v89, v139
	v_pk_mul_f32 v[138:139], v[78:79], v[138:139]
	v_mfma_f32_16x16x16_bf16 v[176:179], v[126:127], v[166:167], v[176:179]
	v_mfma_f32_16x16x16_bf16 v[146:149], v[128:129], v[166:167], v[146:149]
	v_mfma_f32_16x16x16_bf16 v[180:183], v[130:131], v[166:167], v[180:183]
	v_mfma_f32_16x16x16_bf16 v[150:153], v[132:133], v[166:167], v[150:153]
	v_mfma_f32_16x16x16_bf16 v[156:159], v[134:135], v[166:167], v[168:171]
	v_mfma_f32_16x16x16_bf16 v[104:107], v[136:137], v[166:167], v[106:109]
	ds_read2_b64 v[164:167], v163 offset0:32 offset1:36
	s_nop 0
	v_pk_fma_f32 v[168:169], v[78:79], v[172:173], v[142:143] neg_lo:[0,0,1] neg_hi:[0,0,1]
	v_pk_mul_f32 v[108:109], v[118:119], v[140:141]
	s_nop 0
	v_pk_fma_f32 v[170:171], v[80:81], v[174:175], v[108:109] neg_lo:[0,0,1] neg_hi:[0,0,1]
	v_pk_mul_f32 v[108:109], v[80:81], v[140:141]
	s_waitcnt lgkmcnt(0)
; #define LAS __attribute__((address_space(3)))
; #define S5_UPDATE(K, hre, him, xq) do { const v2u xb_ = (xq); \
;     _Pragma("unroll") for (int j = 0; j < 4; ++j) { const f32x4 cre_ = K.ar[j] * hre[j] - K.ai[j] * him[j], cim_ = K.ar[j] * him[j] + K.ai[j] * hre[j]; \
;         hre[j] = MFMA16K16(K.Bf[2 * j], xb_, cre_); him[j] = MFMA16K16(K.Bf[2 * j + 1], xb_, cim_); } } while (0)
; __device__ __forceinline__ void s5_prompt_task(const Args& a, const Ctx& C, int b, int g, v4u (&xv)[8]) {
;     ...
;     f32x4 hre[4], him[4];
; #pragma unroll
;     for (int j = 0; j < 4; ++j) { hre[j] = (f32x4){0.f, 0.f, 0.f, 0.f}; him[j] = (f32x4){0.f, 0.f, 0.f, 0.f}; }
;     const LAS unsigned char* xsl = XS + chunk * 528 + q * 8;
;     for (int t = 0; t < 16; ++t) { const v2u xq = *(const LAS v2u*)(xsl + t * 32); S5_UPDATE(K, hre, him, xq); }
	v_mfma_f32_16x16x16_bf16 v[140:143], v[114:115], v[164:165], v[168:171]
	s_nop 2
	v_fma_f32 v170, v118, v174, v108
	v_fma_f32 v171, v119, v175, v109
	v_pk_fma_f32 v[168:169], v[88:89], v[172:173], v[138:139]
	v_pk_mul_f32 v[108:109], v[120:121], v[148:149]
	v_pk_mul_f32 v[138:139], v[94:95], v[146:147]
	v_pk_fma_f32 v[174:175], v[86:87], v[178:179], v[108:109] neg_lo:[0,0,1] neg_hi:[0,0,1]
	v_pk_fma_f32 v[172:173], v[82:83], v[176:177], v[138:139] neg_lo:[0,0,1] neg_hi:[0,0,1]
	v_pk_mul_f32 v[108:109], v[86:87], v[148:149]
	v_pk_mul_f32 v[138:139], v[82:83], v[146:147]
	v_mfma_f32_16x16x16_bf16 v[168:171], v[116:117], v[164:165], v[168:171]
	v_fma_f32 v148, v120, v178, v108
	v_fma_f32 v149, v121, v179, v109
	v_pk_fma_f32 v[146:147], v[94:95], v[176:177], v[138:139]
	v_pk_mul_f32 v[108:109], v[122:123], v[152:153]
	v_pk_mul_f32 v[138:139], v[98:99], v[150:151]
	v_pk_fma_f32 v[178:179], v[92:93], v[182:183], v[108:109] neg_lo:[0,0,1] neg_hi:[0,0,1]
	v_pk_fma_f32 v[176:177], v[84:85], v[180:181], v[138:139] neg_lo:[0,0,1] neg_hi:[0,0,1]
	v_pk_mul_f32 v[138:139], v[84:85], v[150:151]
	v_pk_mul_f32 v[108:109], v[92:93], v[152:153]
	v_mfma_f32_16x16x16_bf16 v[152:155], v[130:131], v[164:165], v[176:179]
	s_nop 2
	v_fma_f32 v176, v98, v180, v138
	v_fma_f32 v177, v99, v181, v139
	v_pk_mul_f32 v[138:139], v[100:101], v[104:105]
	v_mfma_f32_16x16x16_bf16 v[146:149], v[128:129], v[164:165], v[146:149]
	v_fma_f32 v178, v122, v182, v108
	v_fma_f32 v179, v123, v183, v109
	v_pk_mul_f32 v[108:109], v[124:125], v[106:107]
	v_pk_fma_f32 v[180:181], v[90:91], v[156:157], v[138:139] neg_lo:[0,0,1] neg_hi:[0,0,1]
	v_pk_mul_f32 v[138:139], v[96:97], v[106:107]
	v_pk_mul_f32 v[104:105], v[90:91], v[104:105]
	v_mfma_f32_16x16x16_bf16 v[172:175], v[126:127], v[164:165], v[172:175]
	v_fma_f32 v182, v96, v158, -v108
	v_fma_f32 v183, v97, v159, -v109
	v_pk_fma_f32 v[158:159], v[124:125], v[158:159], v[138:139]
	v_pk_fma_f32 v[156:157], v[100:101], v[156:157], v[104:105]
	v_pk_mul_f32 v[104:105], v[118:119], v[170:171]
	v_pk_mul_f32 v[138:139], v[88:89], v[168:169]
	v_mfma_f32_16x16x16_bf16 v[176:179], v[132:133], v[164:165], v[176:179]
	v_mfma_f32_16x16x16_bf16 v[106:109], v[134:135], v[164:165], v[180:183]
	s_nop 2
	v_fma_f32 v182, v80, v142, -v104
	v_fma_f32 v183, v81, v143, -v105
	v_pk_fma_f32 v[180:181], v[78:79], v[140:141], v[138:139] neg_lo:[0,0,1] neg_hi:[0,0,1]
	v_pk_mul_f32 v[104:105], v[80:81], v[170:171]
	v_pk_mul_f32 v[138:139], v[78:79], v[168:169]
	v_pk_fma_f32 v[142:143], v[118:119], v[142:143], v[104:105]
	v_pk_fma_f32 v[140:141], v[88:89], v[140:141], v[138:139]
	v_mfma_f32_16x16x16_bf16 v[156:159], v[136:137], v[164:165], v[156:159]
	v_mul_f32_e64 v104, v120, v148
	v_mul_f32_e64 v105, v121, v149
	v_pk_fma_f32 v[170:171], v[86:87], v[174:175], v[104:105] neg_lo:[0,0,1] neg_hi:[0,0,1]
	v_mfma_f32_16x16x16_bf16 v[138:141], v[116:117], v[166:167], v[140:143]
	v_mul_f32_e64 v104, v86, v148
	v_mul_f32_e64 v105, v87, v149
	s_nop 0
	v_pk_mul_f32 v[142:143], v[94:95], v[146:147]
	v_mfma_f32_16x16x16_bf16 v[180:183], v[114:115], v[166:167], v[180:183]
	v_fma_f32 v168, v82, v172, -v142
	v_fma_f32 v169, v83, v173, -v143
	v_pk_mul_f32 v[142:143], v[82:83], v[146:147]
	s_nop 0
	v_mfma_f32_16x16x16_bf16 v[148:151], v[126:127], v[166:167], v[168:171]
	s_nop 2
	v_fma_f32 v170, v120, v174, v104
	v_fma_f32 v171, v121, v175, v105
	v_pk_fma_f32 v[168:169], v[94:95], v[172:173], v[142:143]
	v_pk_mul_f32 v[104:105], v[122:123], v[178:179]
	v_pk_mul_f32 v[142:143], v[98:99], v[176:177]
	v_pk_fma_f32 v[174:175], v[92:93], v[154:155], v[104:105] neg_lo:[0,0,1] neg_hi:[0,0,1]
	v_pk_fma_f32 v[172:173], v[84:85], v[152:153], v[142:143] neg_lo:[0,0,1] neg_hi:[0,0,1]
	v_pk_mul_f32 v[104:105], v[92:93], v[178:179]
	v_pk_mul_f32 v[142:143], v[84:85], v[176:177]
	v_pk_fma_f32 v[154:155], v[122:123], v[154:155], v[104:105]
	v_pk_fma_f32 v[152:153], v[98:99], v[152:153], v[142:143]
	v_pk_mul_f32 v[104:105], v[124:125], v[158:159]
	v_pk_mul_f32 v[142:143], v[100:101], v[156:157]
	v_pk_fma_f32 v[178:179], v[96:97], v[108:109], v[104:105] neg_lo:[0,0,1] neg_hi:[0,0,1]
	v_pk_fma_f32 v[176:177], v[90:91], v[106:107], v[142:143] neg_lo:[0,0,1] neg_hi:[0,0,1]
	v_pk_mul_f32 v[104:105], v[96:97], v[158:159]
	v_pk_mul_f32 v[142:143], v[90:91], v[156:157]
	ds_read2_b64 v[156:159], v163 offset0:40 offset1:44
	v_mfma_f32_16x16x16_bf16 v[168:171], v[128:129], v[166:167], v[168:171]
	v_fma_f32 v108, v124, v108, v104
	v_fma_f32 v109, v125, v109, v105
	v_pk_fma_f32 v[106:107], v[100:101], v[106:107], v[142:143]
	v_pk_mul_f32 v[142:143], v[88:89], v[138:139]
	v_mfma_f32_16x16x16_bf16 v[152:155], v[132:133], v[166:167], v[152:155]
	v_fma_f32 v164, v78, v180, -v142
	v_fma_f32 v165, v79, v181, -v143
	v_pk_mul_f32 v[138:139], v[78:79], v[138:139]
	v_mfma_f32_16x16x16_bf16 v[104:107], v[136:137], v[166:167], v[106:109]
	s_nop 2
	v_mul_f32_e64 v108, v118, v140
	v_mul_f32_e64 v109, v119, v141
	v_mfma_f32_16x16x16_bf16 v[172:175], v[130:131], v[166:167], v[172:175]
	v_mfma_f32_16x16x16_bf16 v[176:179], v[134:135], v[166:167], v[176:179]
	v_fma_f32 v166, v80, v182, -v108
	v_fma_f32 v167, v81, v183, -v109
	v_pk_mul_f32 v[108:109], v[80:81], v[140:141]
	s_waitcnt lgkmcnt(0)
; #define LAS __attribute__((address_space(3)))
; #define S5_UPDATE(K, hre, him, xq) do { const v2u xb_ = (xq); \
;     _Pragma("unroll") for (int j = 0; j < 4; ++j) { const f32x4 cre_ = K.ar[j] * hre[j] - K.ai[j] * him[j], cim_ = K.ar[j] * him[j] + K.ai[j] * hre[j]; \
;         hre[j] = MFMA16K16(K.Bf[2 * j], xb_, cre_); him[j] = MFMA16K16(K.Bf[2 * j + 1], xb_, cim_); } } while (0)
; __device__ __forceinline__ void s5_prompt_task(const Args& a, const Ctx& C, int b, int g, v4u (&xv)[8]) {
;     ...
;     f32x4 hre[4], him[4];
; #pragma unroll
;     for (int j = 0; j < 4; ++j) { hre[j] = (f32x4){0.f, 0.f, 0.f, 0.f}; him[j] = (f32x4){0.f, 0.f, 0.f, 0.f}; }
;     const LAS unsigned char* xsl = XS + chunk * 528 + q * 8;
;     for (int t = 0; t < 16; ++t) { const v2u xq = *(const LAS v2u*)(xsl + t * 32); S5_UPDATE(K, hre, him, xq); }
	v_mfma_f32_16x16x16_bf16 v[140:143], v[114:115], v[156:157], v[164:167]
	s_nop 2
	v_fma_f32 v166, v118, v182, v108
	v_fma_f32 v167, v119, v183, v109
	v_pk_fma_f32 v[164:165], v[88:89], v[180:181], v[138:139]
	v_pk_mul_f32 v[108:109], v[120:121], v[170:171]
	v_pk_mul_f32 v[138:139], v[94:95], v[168:169]
	v_pk_fma_f32 v[182:183], v[86:87], v[150:151], v[108:109] neg_lo:[0,0,1] neg_hi:[0,0,1]
	v_pk_fma_f32 v[180:181], v[82:83], v[148:149], v[138:139] neg_lo:[0,0,1] neg_hi:[0,0,1]
	v_pk_mul_f32 v[108:109], v[86:87], v[170:171]
	v_pk_mul_f32 v[138:139], v[82:83], v[168:169]
	v_mfma_f32_16x16x16_bf16 v[164:167], v[116:117], v[156:157], v[164:167]
	v_fma_f32 v150, v120, v150, v108
	v_fma_f32 v151, v121, v151, v109
	v_pk_fma_f32 v[148:149], v[94:95], v[148:149], v[138:139]
	v_pk_mul_f32 v[108:109], v[122:123], v[154:155]
	v_pk_mul_f32 v[138:139], v[98:99], v[152:153]
	v_pk_fma_f32 v[170:171], v[92:93], v[174:175], v[108:109] neg_lo:[0,0,1] neg_hi:[0,0,1]
	v_pk_fma_f32 v[168:169], v[84:85], v[172:173], v[138:139] neg_lo:[0,0,1] neg_hi:[0,0,1]
	v_pk_mul_f32 v[108:109], v[92:93], v[154:155]
	v_pk_mul_f32 v[138:139], v[84:85], v[152:153]
	v_mfma_f32_16x16x16_bf16 v[146:149], v[128:129], v[156:157], v[148:151]
	v_fma_f32 v152, v122, v174, v108
	v_fma_f32 v153, v123, v175, v109
	v_pk_mul_f32 v[108:109], v[124:125], v[106:107]
	v_pk_fma_f32 v[150:151], v[98:99], v[172:173], v[138:139]
	v_pk_mul_f32 v[138:139], v[100:101], v[104:105]
	v_pk_fma_f32 v[174:175], v[96:97], v[178:179], v[108:109] neg_lo:[0,0,1] neg_hi:[0,0,1]
	v_pk_fma_f32 v[172:173], v[90:91], v[176:177], v[138:139] neg_lo:[0,0,1] neg_hi:[0,0,1]
	v_pk_mul_f32 v[138:139], v[96:97], v[106:107]
	v_pk_mul_f32 v[104:105], v[90:91], v[104:105]
	v_mfma_f32_16x16x16_bf16 v[180:183], v[126:127], v[156:157], v[180:183]
	v_mfma_f32_16x16x16_bf16 v[106:109], v[134:135], v[156:157], v[172:175]
	s_nop 2
	v_fma_f32 v174, v124, v178, v138
	v_fma_f32 v175, v125, v179, v139
	v_pk_fma_f32 v[172:173], v[100:101], v[176:177], v[104:105]
	v_pk_mul_f32 v[104:105], v[118:119], v[166:167]
	v_pk_mul_f32 v[138:139], v[88:89], v[164:165]
	v_mfma_f32_16x16x16_bf16 v[168:171], v[130:131], v[156:157], v[168:171]
	v_mfma_f32_16x16x16_bf16 v[150:153], v[132:133], v[156:157], v[150:153]
	v_mfma_f32_16x16x16_bf16 v[154:157], v[136:137], v[156:157], v[172:175]
	s_nop 2
	v_fma_f32 v174, v80, v142, -v104
	v_fma_f32 v175, v81, v143, -v105
	v_pk_fma_f32 v[172:173], v[78:79], v[140:141], v[138:139] neg_lo:[0,0,1] neg_hi:[0,0,1]
	v_pk_mul_f32 v[104:105], v[80:81], v[166:167]
	v_pk_mul_f32 v[138:139], v[78:79], v[164:165]
	v_pk_fma_f32 v[142:143], v[118:119], v[142:143], v[104:105]
	v_pk_fma_f32 v[140:141], v[88:89], v[140:141], v[138:139]
	v_pk_mul_f32 v[104:105], v[120:121], v[148:149]
	v_mfma_f32_16x16x16_bf16 v[172:175], v[114:115], v[158:159], v[172:175]
	v_fma_f32 v166, v86, v182, -v104
	v_fma_f32 v167, v87, v183, -v105
	v_pk_mul_f32 v[104:105], v[86:87], v[148:149]
	v_mfma_f32_16x16x16_bf16 v[138:141], v[116:117], v[158:159], v[140:143]
	v_fma_f32 v148, v120, v182, v104
	v_fma_f32 v149, v121, v183, v105
	v_pk_mul_f32 v[104:105], v[122:123], v[152:153]
	v_pk_mul_f32 v[142:143], v[94:95], v[146:147]
	v_pk_fma_f32 v[178:179], v[92:93], v[170:171], v[104:105] neg_lo:[0,0,1] neg_hi:[0,0,1]
	v_pk_fma_f32 v[164:165], v[82:83], v[180:181], v[142:143] neg_lo:[0,0,1] neg_hi:[0,0,1]
	v_pk_mul_f32 v[142:143], v[82:83], v[146:147]
	v_pk_mul_f32 v[104:105], v[92:93], v[152:153]
	v_pk_fma_f32 v[146:147], v[94:95], v[180:181], v[142:143]
	v_pk_mul_f32 v[142:143], v[98:99], v[150:151]
	v_pk_fma_f32 v[152:153], v[122:123], v[170:171], v[104:105]
	v_pk_fma_f32 v[176:177], v[84:85], v[168:169], v[142:143] neg_lo:[0,0,1] neg_hi:[0,0,1]
	v_pk_mul_f32 v[142:143], v[84:85], v[150:151]
	v_pk_mul_f32 v[104:105], v[124:125], v[156:157]
	v_pk_fma_f32 v[150:151], v[98:99], v[168:169], v[142:143]
	v_pk_mul_f32 v[142:143], v[100:101], v[154:155]
	v_mfma_f32_16x16x16_bf16 v[146:149], v[128:129], v[158:159], v[146:149]
	v_fma_f32 v170, v96, v108, -v104
	v_fma_f32 v171, v97, v109, -v105
	v_pk_fma_f32 v[168:169], v[90:91], v[106:107], v[142:143] neg_lo:[0,0,1] neg_hi:[0,0,1]
	v_pk_mul_f32 v[104:105], v[96:97], v[156:157]
	v_pk_mul_f32 v[142:143], v[90:91], v[154:155]
	ds_read2_b64 v[154:157], v163 offset0:48 offset1:52
	v_mfma_f32_16x16x16_bf16 v[164:167], v[126:127], v[158:159], v[164:167]
	v_fma_f32 v108, v124, v108, v104
	v_fma_f32 v109, v125, v109, v105
	v_pk_fma_f32 v[106:107], v[100:101], v[106:107], v[142:143]
	v_pk_mul_f32 v[142:143], v[88:89], v[138:139]
	v_mfma_f32_16x16x16_bf16 v[150:153], v[132:133], v[158:159], v[150:153]
	v_mul_f32_e64 v138, v78, v138
	v_mul_f32_e64 v139, v79, v139
	v_pk_fma_f32 v[180:181], v[78:79], v[172:173], v[142:143] neg_lo:[0,0,1] neg_hi:[0,0,1]
	v_pk_fma_f32 v[172:173], v[88:89], v[172:173], v[138:139]
	v_mfma_f32_16x16x16_bf16 v[176:179], v[130:131], v[158:159], v[176:179]
	v_mul_f32_e64 v138, v94, v146
	v_mul_f32_e64 v139, v95, v147
	v_mfma_f32_16x16x16_bf16 v[104:107], v[136:137], v[158:159], v[106:109]
	s_nop 2
	v_mul_f32_e64 v108, v118, v140
	v_mul_f32_e64 v109, v119, v141
	v_mfma_f32_16x16x16_bf16 v[168:171], v[134:135], v[158:159], v[168:171]
	v_fma_f32 v182, v80, v174, -v108
	v_fma_f32 v183, v81, v175, -v109
	v_pk_mul_f32 v[108:109], v[80:81], v[140:141]
	s_waitcnt lgkmcnt(0)
; #define LAS __attribute__((address_space(3)))
; #define S5_UPDATE(K, hre, him, xq) do { const v2u xb_ = (xq); \
;     _Pragma("unroll") for (int j = 0; j < 4; ++j) { const f32x4 cre_ = K.ar[j] * hre[j] - K.ai[j] * him[j], cim_ = K.ar[j] * him[j] + K.ai[j] * hre[j]; \
;         hre[j] = MFMA16K16(K.Bf[2 * j], xb_, cre_); him[j] = MFMA16K16(K.Bf[2 * j + 1], xb_, cim_); } } while (0)
; __device__ __forceinline__ void s5_prompt_task(const Args& a, const Ctx& C, int b, int g, v4u (&xv)[8]) {
;     ...
;     f32x4 hre[4], him[4];
; #pragma unroll
;     for (int j = 0; j < 4; ++j) { hre[j] = (f32x4){0.f, 0.f, 0.f, 0.f}; him[j] = (f32x4){0.f, 0.f, 0.f, 0.f}; }
;     const LAS unsigned char* xsl = XS + chunk * 528 + q * 8;
;     for (int t = 0; t < 16; ++t) { const v2u xq = *(const LAS v2u*)(xsl + t * 32); S5_UPDATE(K, hre, him, xq); }
	v_mfma_f32_16x16x16_bf16 v[140:143], v[114:115], v[154:155], v[180:183]
	v_fma_f32 v174, v118, v174, v108
	v_fma_f32 v175, v119, v175, v109
	v_pk_mul_f32 v[108:109], v[120:121], v[148:149]
	v_pk_fma_f32 v[180:181], v[82:83], v[164:165], v[138:139] neg_lo:[0,0,1] neg_hi:[0,0,1]
	v_pk_mul_f32 v[138:139], v[82:83], v[146:147]
	v_mfma_f32_16x16x16_bf16 v[172:175], v[116:117], v[154:155], v[172:175]
	v_fma_f32 v182, v86, v166, -v108
	v_fma_f32 v183, v87, v167, -v109
	v_pk_mul_f32 v[108:109], v[86:87], v[148:149]
	v_pk_fma_f32 v[146:147], v[94:95], v[164:165], v[138:139]
	v_pk_mul_f32 v[138:139], v[98:99], v[150:151]
	v_pk_fma_f32 v[148:149], v[120:121], v[166:167], v[108:109]
	v_pk_mul_f32 v[108:109], v[122:123], v[152:153]
	v_pk_fma_f32 v[164:165], v[84:85], v[176:177], v[138:139] neg_lo:[0,0,1] neg_hi:[0,0,1]
	v_pk_mul_f32 v[138:139], v[84:85], v[150:151]
	v_pk_fma_f32 v[166:167], v[92:93], v[178:179], v[108:109] neg_lo:[0,0,1] neg_hi:[0,0,1]
	v_pk_mul_f32 v[108:109], v[92:93], v[152:153]
	v_pk_fma_f32 v[150:151], v[98:99], v[176:177], v[138:139]
	v_pk_mul_f32 v[138:139], v[100:101], v[104:105]
	v_mfma_f32_16x16x16_bf16 v[146:149], v[128:129], v[154:155], v[146:149]
	v_fma_f32 v152, v122, v178, v108
	v_fma_f32 v153, v123, v179, v109
	v_pk_mul_f32 v[108:109], v[124:125], v[106:107]
	v_pk_fma_f32 v[176:177], v[90:91], v[168:169], v[138:139] neg_lo:[0,0,1] neg_hi:[0,0,1]
	v_pk_mul_f32 v[138:139], v[96:97], v[106:107]
	v_pk_mul_f32 v[104:105], v[90:91], v[104:105]
	v_mfma_f32_16x16x16_bf16 v[180:183], v[126:127], v[154:155], v[180:183]
	v_fma_f32 v178, v96, v170, -v108
	v_fma_f32 v179, v97, v171, -v109
	v_pk_fma_f32 v[170:171], v[124:125], v[170:171], v[138:139]
	v_pk_fma_f32 v[168:169], v[100:101], v[168:169], v[104:105]
	v_pk_mul_f32 v[104:105], v[118:119], v[174:175]
	v_pk_mul_f32 v[138:139], v[88:89], v[172:173]
	v_mfma_f32_16x16x16_bf16 v[150:153], v[132:133], v[154:155], v[150:153]
	v_mfma_f32_16x16x16_bf16 v[106:109], v[134:135], v[154:155], v[176:179]
	s_nop 2
	v_fma_f32 v178, v80, v142, -v104
	v_fma_f32 v179, v81, v143, -v105
	v_pk_fma_f32 v[176:177], v[78:79], v[140:141], v[138:139] neg_lo:[0,0,1] neg_hi:[0,0,1]
	v_pk_mul_f32 v[104:105], v[80:81], v[174:175]
	v_pk_mul_f32 v[138:139], v[78:79], v[172:173]
	v_mfma_f32_16x16x16_bf16 v[164:167], v[130:131], v[154:155], v[164:167]
	v_fma_f32 v142, v118, v142, v104
	v_fma_f32 v143, v119, v143, v105
	v_pk_fma_f32 v[140:141], v[88:89], v[140:141], v[138:139]
	v_pk_mul_f32 v[104:105], v[120:121], v[148:149]
	v_mfma_f32_16x16x16_bf16 v[168:171], v[136:137], v[154:155], v[168:171]
	v_fma_f32 v186, v86, v182, -v104
	v_fma_f32 v187, v87, v183, -v105
	v_pk_mul_f32 v[104:105], v[86:87], v[148:149]
	v_mfma_f32_16x16x16_bf16 v[138:141], v[116:117], v[156:157], v[140:143]
	v_fma_f32 v148, v120, v182, v104
	v_fma_f32 v149, v121, v183, v105
	v_pk_mul_f32 v[104:105], v[122:123], v[152:153]
	v_pk_mul_f32 v[142:143], v[94:95], v[146:147]
	v_mfma_f32_16x16x16_bf16 v[174:177], v[114:115], v[156:157], v[176:179]
	v_fma_f32 v184, v82, v180, -v142
	v_fma_f32 v185, v83, v181, -v143
	v_pk_mul_f32 v[142:143], v[82:83], v[146:147]
	s_nop 0
	v_pk_fma_f32 v[146:147], v[94:95], v[180:181], v[142:143]
	v_pk_mul_f32 v[142:143], v[98:99], v[150:151]
	v_pk_fma_f32 v[180:181], v[92:93], v[166:167], v[104:105] neg_lo:[0,0,1] neg_hi:[0,0,1]
	v_pk_fma_f32 v[178:179], v[84:85], v[164:165], v[142:143] neg_lo:[0,0,1] neg_hi:[0,0,1]
	v_pk_mul_f32 v[104:105], v[92:93], v[152:153]
	v_pk_mul_f32 v[142:143], v[84:85], v[150:151]
	v_pk_fma_f32 v[166:167], v[122:123], v[166:167], v[104:105]
	v_pk_fma_f32 v[164:165], v[98:99], v[164:165], v[142:143]
	v_pk_mul_f32 v[104:105], v[124:125], v[170:171]
	v_pk_mul_f32 v[142:143], v[100:101], v[168:169]
	v_mfma_f32_16x16x16_bf16 v[152:155], v[130:131], v[156:157], v[178:181]
	s_nop 2
	v_fma_f32 v180, v96, v108, -v104
	v_fma_f32 v181, v97, v109, -v105
	v_pk_fma_f32 v[178:179], v[90:91], v[106:107], v[142:143] neg_lo:[0,0,1] neg_hi:[0,0,1]
	v_pk_mul_f32 v[104:105], v[96:97], v[170:171]
	v_pk_mul_f32 v[142:143], v[90:91], v[168:169]
	v_pk_fma_f32 v[108:109], v[124:125], v[108:109], v[104:105]
	v_pk_fma_f32 v[106:107], v[100:101], v[106:107], v[142:143]
	v_mfma_f32_16x16x16_bf16 v[184:187], v[126:127], v[156:157], v[184:187]
	v_mul_f32_e64 v142, v88, v138
	v_mul_f32_e64 v143, v89, v139
	v_pk_mul_f32 v[138:139], v[78:79], v[138:139]
	v_mfma_f32_16x16x16_bf16 v[146:149], v[128:129], v[156:157], v[146:149]
	v_mfma_f32_16x16x16_bf16 v[164:167], v[132:133], v[156:157], v[164:167]
	v_mfma_f32_16x16x16_bf16 v[170:173], v[134:135], v[156:157], v[178:181]
	v_mfma_f32_16x16x16_bf16 v[104:107], v[136:137], v[156:157], v[106:109]
	ds_read2_b64 v[156:159], v163 offset0:56 offset1:60
	s_nop 0
	v_pk_fma_f32 v[178:179], v[78:79], v[174:175], v[142:143] neg_lo:[0,0,1] neg_hi:[0,0,1]
	v_pk_fma_f32 v[174:175], v[88:89], v[174:175], v[138:139]
	v_pk_mul_f32 v[108:109], v[118:119], v[140:141]
	v_pk_mul_f32 v[138:139], v[94:95], v[146:147]
	v_pk_fma_f32 v[180:181], v[80:81], v[176:177], v[108:109] neg_lo:[0,0,1] neg_hi:[0,0,1]
	v_pk_mul_f32 v[108:109], v[80:81], v[140:141]
	s_nop 0
	v_pk_fma_f32 v[176:177], v[118:119], v[176:177], v[108:109]
	v_pk_mul_f32 v[108:109], v[120:121], v[148:149]
	s_waitcnt lgkmcnt(0)
; #define LAS __attribute__((address_space(3)))
; #define S5_UPDATE(K, hre, him, xq) do { const v2u xb_ = (xq); \
;     _Pragma("unroll") for (int j = 0; j < 4; ++j) { const f32x4 cre_ = K.ar[j] * hre[j] - K.ai[j] * him[j], cim_ = K.ar[j] * him[j] + K.ai[j] * hre[j]; \
;         hre[j] = MFMA16K16(K.Bf[2 * j], xb_, cre_); him[j] = MFMA16K16(K.Bf[2 * j + 1], xb_, cim_); } } while (0)
; __device__ __forceinline__ void s5_prompt_task(const Args& a, const Ctx& C, int b, int g, v4u (&xv)[8]) {
;     ...
;     const LAS unsigned char* xsl = XS + chunk * 528 + q * 8;
;     for (int t = 0; t < 16; ++t) { const v2u xq = *(const LAS v2u*)(xsl + t * 32); S5_UPDATE(K, hre, him, xq); }
; #pragma unroll
;     for (int j = 0; j < 4; ++j) { LAS float* d = SH + chunk * 132 + 2 * (16 * j + 4 * q);
;         *(LAS f32x4*)d = (f32x4){hre[j][0], him[j][0], hre[j][1], him[j][1]}; *(LAS f32x4*)(d + 4) = (f32x4){hre[j][2], him[j][2], hre[j][3], him[j][3]}; }
;     v2u zq[4];
; #pragma unroll
;     for (int t = 0; t < 4; ++t) zq[t] = __builtin_nontemporal_load((const v2u*)(ZBg + (size_t)(16 * chunk + t) * 16 + 4 * q));
	v_mfma_f32_16x16x16_bf16 v[140:143], v[114:115], v[156:157], v[178:181]
	s_nop 2
	v_fma_f32 v180, v86, v186, -v108
	v_fma_f32 v181, v87, v187, -v109
	v_pk_fma_f32 v[178:179], v[82:83], v[184:185], v[138:139] neg_lo:[0,0,1] neg_hi:[0,0,1]
	v_pk_mul_f32 v[138:139], v[82:83], v[146:147]
	v_mfma_f32_16x16x16_bf16 v[174:177], v[116:117], v[156:157], v[174:177]
	v_mul_f32_e64 v108, v86, v148
	v_mul_f32_e64 v109, v87, v149
	v_mfma_f32_16x16x16_bf16 v[148:151], v[126:127], v[156:157], v[178:181]
	s_nop 2
	v_fma_f32 v178, v94, v184, v138
	v_fma_f32 v179, v95, v185, v139
	v_pk_mul_f32 v[138:139], v[98:99], v[164:165]
	v_pk_fma_f32 v[180:181], v[120:121], v[186:187], v[108:109]
	v_pk_mul_f32 v[108:109], v[122:123], v[166:167]
	v_pk_fma_f32 v[182:183], v[84:85], v[152:153], v[138:139] neg_lo:[0,0,1] neg_hi:[0,0,1]
	v_pk_mul_f32 v[138:139], v[84:85], v[164:165]
	v_mfma_f32_16x16x16_bf16 v[178:181], v[128:129], v[156:157], v[178:181]
	v_fma_f32 v184, v92, v154, -v108
	v_fma_f32 v185, v93, v155, -v109
	v_pk_mul_f32 v[108:109], v[92:93], v[166:167]
	v_pk_fma_f32 v[152:153], v[98:99], v[152:153], v[138:139]
	v_pk_mul_f32 v[138:139], v[100:101], v[104:105]
	v_mfma_f32_16x16x16_bf16 v[166:169], v[130:131], v[156:157], v[182:185]
	v_fma_f32 v154, v122, v154, v108
	v_fma_f32 v155, v123, v155, v109
	v_pk_mul_f32 v[108:109], v[124:125], v[106:107]
	v_pk_mul_f32 v[104:105], v[90:91], v[104:105]
	v_pk_fma_f32 v[182:183], v[90:91], v[170:171], v[138:139] neg_lo:[0,0,1] neg_hi:[0,0,1]
	v_pk_mul_f32 v[138:139], v[96:97], v[106:107]
	v_mfma_f32_16x16x16_bf16 v[152:155], v[132:133], v[156:157], v[152:155]
	v_fma_f32 v184, v96, v172, -v108
	v_fma_f32 v185, v97, v173, -v109
	v_pk_fma_f32 v[172:173], v[124:125], v[172:173], v[138:139]
	v_pk_mul_f32 v[138:139], v[88:89], v[174:175]
	v_mfma_f32_16x16x16_bf16 v[106:109], v[134:135], v[156:157], v[182:185]
	v_fma_f32 v170, v100, v170, v104
	v_fma_f32 v171, v101, v171, v105
	v_pk_mul_f32 v[104:105], v[118:119], v[176:177]
	v_pk_fma_f32 v[182:183], v[78:79], v[140:141], v[138:139] neg_lo:[0,0,1] neg_hi:[0,0,1]
	v_pk_mul_f32 v[78:79], v[78:79], v[174:175]
	v_mfma_f32_16x16x16_bf16 v[170:173], v[136:137], v[156:157], v[170:173]
	v_fma_f32 v184, v80, v142, -v104
	v_fma_f32 v185, v81, v143, -v105
	v_pk_fma_f32 v[78:79], v[88:89], v[140:141], v[78:79]
	v_pk_mul_f32 v[88:89], v[120:121], v[180:181]
	v_pk_mul_f32 v[104:105], v[94:95], v[178:179]
	v_pk_fma_f32 v[140:141], v[86:87], v[150:151], v[88:89] neg_lo:[0,0,1] neg_hi:[0,0,1]
	v_pk_fma_f32 v[138:139], v[82:83], v[148:149], v[104:105] neg_lo:[0,0,1] neg_hi:[0,0,1]
	v_pk_mul_f32 v[82:83], v[82:83], v[178:179]
	v_pk_mul_f32 v[80:81], v[80:81], v[176:177]
	v_pk_mul_f32 v[104:105], v[86:87], v[180:181]
	v_mfma_f32_16x16x16_bf16 v[86:89], v[126:127], v[158:159], v[138:141]
	v_fma_f32 v80, v118, v142, v80
	v_fma_f32 v81, v119, v143, v81
	s_nop 0
	v_pk_fma_f32 v[138:139], v[94:95], v[148:149], v[82:83]
	v_pk_mul_f32 v[82:83], v[122:123], v[154:155]
	v_pk_fma_f32 v[140:141], v[120:121], v[150:151], v[104:105]
	v_pk_mul_f32 v[94:95], v[98:99], v[152:153]
	v_pk_fma_f32 v[148:149], v[92:93], v[168:169], v[82:83] neg_lo:[0,0,1] neg_hi:[0,0,1]
	v_pk_mul_f32 v[82:83], v[92:93], v[154:155]
	v_pk_mul_f32 v[104:105], v[84:85], v[152:153]
	v_mfma_f32_16x16x16_bf16 v[182:185], v[114:115], v[158:159], v[182:185]
	v_fma_f32 v146, v84, v166, -v94
	v_fma_f32 v147, v85, v167, -v95
	v_pk_fma_f32 v[84:85], v[122:123], v[168:169], v[82:83]
	v_pk_fma_f32 v[82:83], v[98:99], v[166:167], v[104:105]
	v_mfma_f32_16x16x16_bf16 v[78:81], v[116:117], v[158:159], v[78:81]
	v_mul_f32_e64 v104, v100, v170
	v_mul_f32_e64 v105, v101, v171
	v_pk_mul_f32 v[98:99], v[124:125], v[172:173]
	v_mov_b32_e32 v102, v183
	v_mfma_f32_16x16x16_bf16 v[138:141], v[128:129], v[158:159], v[138:141]
	v_lshlrev_b32_e32 v152, 3, v162
	s_nop 1
	v_mov_b32_e32 v103, v79
	v_mov_b32_e32 v79, v80
	v_mfma_f32_16x16x16_bf16 v[92:95], v[130:131], v[158:159], v[146:149]
	v_mov_b32_e32 v80, v185
	v_mov_b32_e32 v153, v111
	s_nop 0
	v_pk_fma_f32 v[146:147], v[90:91], v[106:107], v[104:105] neg_lo:[0,0,1] neg_hi:[0,0,1]
	v_pk_mul_f32 v[104:105], v[96:97], v[172:173]
	v_pk_mul_f32 v[90:91], v[90:91], v[170:171]
	v_mfma_f32_16x16x16_bf16 v[82:85], v[132:133], v[158:159], v[82:85]
	v_fma_f32 v148, v96, v108, -v98
	v_fma_f32 v149, v97, v109, -v99
	v_pk_fma_f32 v[108:109], v[124:125], v[108:109], v[104:105]
	v_pk_fma_f32 v[106:107], v[100:101], v[106:107], v[90:91]
	v_mfma_f32_16x16x16_bf16 v[96:99], v[134:135], v[158:159], v[146:149]
	v_mov_b32_e32 v101, v78
	v_mov_b32_e32 v78, v184
	ds_write_b128 v3, v[78:81] offset:16
	v_mfma_f32_16x16x16_bf16 v[104:107], v[136:137], v[158:159], v[106:109]
	v_mov_b32_e32 v78, v86
	v_mov_b32_e32 v79, v138
	v_mov_b32_e32 v80, v87
	v_mov_b32_e32 v81, v139
	ds_write_b128 v3, v[78:81] offset:128
	v_mov_b32_e32 v78, v92
	v_mov_b32_e32 v79, v82
	v_mov_b32_e32 v80, v93
	v_mov_b32_e32 v81, v83
	ds_write_b128 v3, v[78:81] offset:256
	v_mov_b32_e32 v78, v96
	v_mov_b32_e32 v79, v104
	v_mov_b32_e32 v80, v97
	v_mov_b32_e32 v81, v105
	v_mov_b32_e32 v138, v88
	v_mov_b32_e32 v139, v140
	v_mov_b32_e32 v140, v89
	v_mov_b32_e32 v82, v94
	v_mov_b32_e32 v83, v84
	v_mov_b32_e32 v84, v95
	ds_write_b128 v3, v[78:81] offset:384
	v_lshl_add_u64 v[78:79], s[4:5], 0, v[110:111]
	s_mov_b64 s[4:5], 0xd400000
	v_mov_b32_e32 v110, v7
	v_mov_b32_e32 v100, v182
	ds_write_b128 v3, v[138:141] offset:144
	ds_write_b128 v3, v[82:85] offset:272
	v_mov_b32_e32 v104, v98
	v_mov_b32_e32 v105, v106
	v_mov_b32_e32 v106, v99
	v_lshl_add_u64 v[138:139], v[78:79], 0, s[4:5]
	v_lshlrev_b64 v[78:79], 5, v[110:111]
	v_or_b32_e32 v80, 1, v7
	v_mov_b32_e32 v81, v111
	v_or_b32_e32 v82, 2, v7
	v_mov_b32_e32 v83, v111
	v_or_b32_e32 v84, 3, v7
	v_mov_b32_e32 v85, v111
	ds_write_b128 v3, v[100:103]
	ds_write_b128 v3, v[104:107] offset:400
	v_lshl_add_u64 v[78:79], v[138:139], 0, v[78:79]
	v_lshlrev_b64 v[80:81], 5, v[80:81]
	v_lshlrev_b64 v[82:83], 5, v[82:83]
	v_lshlrev_b64 v[84:85], 5, v[84:85]
	v_lshl_add_u64 v[80:81], v[138:139], 0, v[80:81]
	v_lshl_add_u64 v[82:83], v[138:139], 0, v[82:83]
	v_lshl_add_u64 v[84:85], v[138:139], 0, v[84:85]
	v_lshrrev_b32_e32 v244, 4, v162
	v_lshlrev_b32_e32 v244, 3, v244
	v_mov_b32_e32 v245, 0
	v_lshl_add_u64 v[78:79], v[78:79], 0, v[244:245]
	v_lshl_add_u64 v[82:83], v[82:83], 0, v[244:245]
	global_load_dwordx4 v[226:229], v[78:79], off nt
	global_load_dwordx4 v[230:233], v[82:83], off nt
	v_lshl_add_u64 v[78:79], s[6:7], 0, v[152:153]
	v_add_co_u32_e32 v80, vcc, s2, v78
	s_waitcnt lgkmcnt(0)
; #define LAS __attribute__((address_space(3)))
; __device__ __forceinline__ void s5_prompt_task(const Args& a, const Ctx& C, int b, int g, v4u (&xv)[8]) {
;     ...
;     { const float* A16 = (const float*)(a.ws + WS_S5C + S5C_A16) + (size_t)g * 128; const float* A256 = (const float*)(a.ws + WS_S5C + S5C_A256) + (size_t)g * 128;
;       const float a16r = A16[2 * lane], a16i = A16[2 * lane + 1], a256r = A256[2 * lane], a256i = A256[2 * lane + 1];
;       v2f sv[16];
; #pragma unroll
;       for (int i = 0; i < 16; ++i) sv[i] = *(const LAS v2f*)(SH + (16 * w + i) * 132 + 2 * lane);
;       float tr = 0.f, ti = 0.f;
; #pragma unroll
;       for (int i = 0; i < 16; ++i) { const float nr = a16r * tr - a16i * ti + sv[i][0], ni = a16r * ti + a16i * tr + sv[i][1]; tr = nr; ti = ni; }
;       TW[w * 128 + 2 * lane] = tr; TW[w * 128 + 2 * lane + 1] = ti;
;       __syncthreads();
	s_mov_b32 s2, 0x2310000
	s_nop 0
	v_addc_co_u32_e32 v81, vcc, 0, v79, vcc
	v_add_co_u32_e32 v78, vcc, s2, v78
	v_add_u32_e32 v7, s8, v152
	s_nop 0
	v_addc_co_u32_e32 v79, vcc, 0, v79, vcc
	s_mul_i32 s4, s82, 0x2100
	v_add_u32_e32 v7, s4, v7
	v_add_u32_e32 v11, 0x800, v7
	ds_read2_b64 v[106:109], v7 offset1:66
	ds_read2_b64 v[102:105], v7 offset0:132 offset1:198
	ds_read2_b64 v[98:101], v11 offset0:8 offset1:74
	ds_read2_b64 v[94:97], v11 offset0:140 offset1:206
	v_add_u32_e32 v11, 0x1000, v7
	ds_read2_b64 v[90:93], v11 offset0:16 offset1:82
	ds_read2_b64 v[86:89], v11 offset0:148 offset1:214
	v_add_u32_e32 v11, 0x1800, v7
	ds_read2_b64 v[82:85], v11 offset0:24 offset1:90
	ds_read2_b64 v[78:81], v11 offset0:156 offset1:222
	s_lshl_b32 s4, s82, 9
	s_add_i32 s4, s4, 0
	s_mov_b32 s2, 0
	s_cmp_lt_u32 s84, 64
	s_waitcnt vmcnt(2)
	v_mov_b32_e32 v148, v234
	v_mov_b32_e32 v149, v235
	v_mov_b32_e32 v150, v236
	v_mov_b32_e32 v151, v237
	v_mul_f32_e32 v11, 0, v148
	v_mul_f32_e32 v155, 0, v149
	v_sub_f32_e32 v154, v11, v155
	v_fmac_f32_e32 v155, 0, v148
	s_waitcnt lgkmcnt(7)
	v_pk_add_f32 v[154:155], v[154:155], v[106:107]
	v_add_u32_e32 v11, s4, v152
	v_pk_mul_f32 v[156:157], v[148:149], v[154:155] op_sel:[1,1] op_sel_hi:[0,1]
	v_pk_fma_f32 v[158:159], v[148:149], v[154:155], v[156:157] op_sel_hi:[1,0,1]
	v_pk_fma_f32 v[156:157], v[148:149], v[154:155], v[156:157] op_sel_hi:[1,0,1] neg_lo:[0,0,1] neg_hi:[0,0,1]
	v_add_u32_e32 v11, 0x21000, v11
	v_mov_b32_e32 v157, v159
	v_pk_add_f32 v[156:157], v[108:109], v[156:157]
	v_mov_b32_e32 v152, v111
	v_pk_mul_f32 v[158:159], v[148:149], v[156:157] op_sel:[1,1] op_sel_hi:[0,1]
	v_pk_fma_f32 v[164:165], v[148:149], v[156:157], v[158:159] op_sel_hi:[1,0,1]
	v_pk_fma_f32 v[158:159], v[148:149], v[156:157], v[158:159] op_sel_hi:[1,0,1] neg_lo:[0,0,1] neg_hi:[0,0,1]
	s_nop 0
	v_mov_b32_e32 v159, v165
	s_waitcnt lgkmcnt(6)
	v_pk_add_f32 v[158:159], v[102:103], v[158:159]
	s_nop 0
	v_pk_mul_f32 v[164:165], v[148:149], v[158:159] op_sel:[1,1] op_sel_hi:[0,1]
	v_pk_fma_f32 v[166:167], v[148:149], v[158:159], v[164:165] op_sel_hi:[1,0,1]
	v_pk_fma_f32 v[164:165], v[148:149], v[158:159], v[164:165] op_sel_hi:[1,0,1] neg_lo:[0,0,1] neg_hi:[0,0,1]
	s_nop 0
	v_mov_b32_e32 v165, v167
	v_pk_add_f32 v[164:165], v[104:105], v[164:165]
	s_nop 0
	v_pk_mul_f32 v[166:167], v[148:149], v[164:165] op_sel:[1,1] op_sel_hi:[0,1]
	v_pk_fma_f32 v[168:169], v[148:149], v[164:165], v[166:167] op_sel_hi:[1,0,1]
	v_pk_fma_f32 v[166:167], v[148:149], v[164:165], v[166:167] op_sel_hi:[1,0,1] neg_lo:[0,0,1] neg_hi:[0,0,1]
	s_nop 0
	v_mov_b32_e32 v167, v169
	s_waitcnt lgkmcnt(5)
	v_pk_add_f32 v[166:167], v[98:99], v[166:167]
	s_nop 0
	v_pk_mul_f32 v[168:169], v[148:149], v[166:167] op_sel:[1,1] op_sel_hi:[0,1]
	v_pk_fma_f32 v[170:171], v[148:149], v[166:167], v[168:169] op_sel_hi:[1,0,1]
	v_pk_fma_f32 v[168:169], v[148:149], v[166:167], v[168:169] op_sel_hi:[1,0,1] neg_lo:[0,0,1] neg_hi:[0,0,1]
	s_nop 0
	v_mov_b32_e32 v169, v171
	v_pk_add_f32 v[168:169], v[100:101], v[168:169]
	s_nop 0
	v_pk_mul_f32 v[170:171], v[148:149], v[168:169] op_sel:[1,1] op_sel_hi:[0,1]
	v_pk_fma_f32 v[172:173], v[148:149], v[168:169], v[170:171] op_sel_hi:[1,0,1]
	v_pk_fma_f32 v[170:171], v[148:149], v[168:169], v[170:171] op_sel_hi:[1,0,1] neg_lo:[0,0,1] neg_hi:[0,0,1]
	s_nop 0
	v_mov_b32_e32 v171, v173
	s_waitcnt lgkmcnt(4)
	v_pk_add_f32 v[170:171], v[94:95], v[170:171]
	s_nop 0
	v_pk_mul_f32 v[172:173], v[148:149], v[170:171] op_sel:[1,1] op_sel_hi:[0,1]
	v_pk_fma_f32 v[174:175], v[148:149], v[170:171], v[172:173] op_sel_hi:[1,0,1]
	v_pk_fma_f32 v[172:173], v[148:149], v[170:171], v[172:173] op_sel_hi:[1,0,1] neg_lo:[0,0,1] neg_hi:[0,0,1]
	s_nop 0
	v_mov_b32_e32 v173, v175
	v_pk_add_f32 v[172:173], v[96:97], v[172:173]
	s_nop 0
	v_pk_mul_f32 v[174:175], v[148:149], v[172:173] op_sel:[1,1] op_sel_hi:[0,1]
	v_pk_fma_f32 v[176:177], v[148:149], v[172:173], v[174:175] op_sel_hi:[1,0,1]
	v_pk_fma_f32 v[174:175], v[148:149], v[172:173], v[174:175] op_sel_hi:[1,0,1] neg_lo:[0,0,1] neg_hi:[0,0,1]
	s_nop 0
	v_mov_b32_e32 v175, v177
	s_waitcnt lgkmcnt(3)
	v_pk_add_f32 v[174:175], v[90:91], v[174:175]
	s_nop 0
	v_pk_mul_f32 v[176:177], v[148:149], v[174:175] op_sel:[1,1] op_sel_hi:[0,1]
	v_pk_fma_f32 v[178:179], v[148:149], v[174:175], v[176:177] op_sel_hi:[1,0,1]
	v_pk_fma_f32 v[176:177], v[148:149], v[174:175], v[176:177] op_sel_hi:[1,0,1] neg_lo:[0,0,1] neg_hi:[0,0,1]
	s_nop 0
	v_mov_b32_e32 v177, v179
	v_pk_add_f32 v[176:177], v[92:93], v[176:177]
	s_nop 0
	v_pk_mul_f32 v[178:179], v[148:149], v[176:177] op_sel:[1,1] op_sel_hi:[0,1]
	v_pk_fma_f32 v[180:181], v[148:149], v[176:177], v[178:179] op_sel_hi:[1,0,1]
	v_pk_fma_f32 v[178:179], v[148:149], v[176:177], v[178:179] op_sel_hi:[1,0,1] neg_lo:[0,0,1] neg_hi:[0,0,1]
	s_nop 0
	v_mov_b32_e32 v179, v181
	s_waitcnt lgkmcnt(2)
	v_pk_add_f32 v[178:179], v[86:87], v[178:179]
	s_nop 0
	v_pk_mul_f32 v[180:181], v[148:149], v[178:179] op_sel:[1,1] op_sel_hi:[0,1]
	v_pk_fma_f32 v[182:183], v[148:149], v[178:179], v[180:181] op_sel_hi:[1,0,1]
	v_pk_fma_f32 v[180:181], v[148:149], v[178:179], v[180:181] op_sel_hi:[1,0,1] neg_lo:[0,0,1] neg_hi:[0,0,1]
	s_nop 0
	v_mov_b32_e32 v181, v183
	v_pk_add_f32 v[182:183], v[88:89], v[180:181]
	s_nop 0
	v_pk_mul_f32 v[180:181], v[148:149], v[182:183] op_sel:[1,1] op_sel_hi:[0,1]
	v_pk_fma_f32 v[184:185], v[148:149], v[182:183], v[180:181] op_sel_hi:[1,0,1]
	v_pk_fma_f32 v[180:181], v[148:149], v[182:183], v[180:181] op_sel_hi:[1,0,1] neg_lo:[0,0,1] neg_hi:[0,0,1]
	s_nop 0
	v_mov_b32_e32 v181, v185
	s_waitcnt lgkmcnt(1)
	v_pk_add_f32 v[184:185], v[82:83], v[180:181]
	s_nop 0
	v_pk_mul_f32 v[180:181], v[148:149], v[184:185] op_sel:[1,1] op_sel_hi:[0,1]
	v_pk_fma_f32 v[186:187], v[148:149], v[184:185], v[180:181] op_sel_hi:[1,0,1]
	v_pk_fma_f32 v[180:181], v[148:149], v[184:185], v[180:181] op_sel_hi:[1,0,1] neg_lo:[0,0,1] neg_hi:[0,0,1]
	s_nop 0
	v_mov_b32_e32 v181, v187
	v_pk_add_f32 v[186:187], v[84:85], v[180:181]
	s_nop 0
	v_pk_mul_f32 v[180:181], v[148:149], v[186:187] op_sel:[1,1] op_sel_hi:[0,1]
	v_pk_fma_f32 v[188:189], v[148:149], v[186:187], v[180:181] op_sel_hi:[1,0,1]
	v_pk_fma_f32 v[180:181], v[148:149], v[186:187], v[180:181] op_sel_hi:[1,0,1] neg_lo:[0,0,1] neg_hi:[0,0,1]
	s_nop 0
	v_mov_b32_e32 v181, v189
	s_waitcnt lgkmcnt(0)
	v_pk_add_f32 v[188:189], v[78:79], v[180:181]
	s_nop 0
	v_pk_mul_f32 v[180:181], v[148:149], v[188:189] op_sel:[1,1] op_sel_hi:[0,1]
	v_pk_fma_f32 v[198:199], v[148:149], v[188:189], v[180:181] op_sel_hi:[1,0,1]
	v_pk_fma_f32 v[180:181], v[148:149], v[188:189], v[180:181] op_sel_hi:[1,0,1] neg_lo:[0,0,1] neg_hi:[0,0,1]
	s_nop 0
	v_mov_b32_e32 v181, v199
	v_pk_add_f32 v[180:181], v[80:81], v[180:181]
	ds_write_b64 v11, v[180:181]
	s_waitcnt lgkmcnt(0)
	s_barrier
; __device__ __forceinline__ void s5_prompt_task(const Args& a, const Ctx& C, int b, int g, v4u (&xv)[8]) {
;     ...
;       float hr = 0.f, hi = 0.f;
;       for (int v = 0; v < w; ++v) { const float sr = TW[v * 128 + 2 * lane], si = TW[v * 128 + 2 * lane + 1];
;           const float nr = a256r * hr - a256i * hi + sr, ni = a256r * hi + a256i * hr + si; hr = nr; hi = ni; }
	s_cbranch_scc1 .LBB0_985
	s_add_i32 s4, s82, -1
	s_cmp_lt_u32 s4, 7
	v_mov_b32_e32 v160, v111
	v_mov_b32_e32 v152, v111
	s_cbranch_scc1 .LBB0_977
	v_lshl_add_u32 v11, v162, 3, 0
	s_and_b32 s2, s82, 0x3fffff8
	s_waitcnt vmcnt(2)
	v_pk_mov_b32 v[154:155], v[150:151], v[150:151] op_sel:[1,0]
	s_mov_b32 s4, 0
	v_add_u32_e32 v11, 0x21000, v11
	v_mov_b32_e32 v152, 0
	v_mov_b32_e32 v160, 0

; __device__ __forceinline__ void s5_prompt_task(const Args& a, const Ctx& C, int b, int g, v4u (&xv)[8]) {
;     ...
;       float hr = 0.f, hi = 0.f;
;       for (int v = 0; v < w; ++v) { const float sr = TW[v * 128 + 2 * lane], si = TW[v * 128 + 2 * lane + 1];
;           const float nr = a256r * hr - a256i * hi + sr, ni = a256r * hi + a256i * hr + si; hr = nr; hi = ni; }
.LBB0_977:
	s_bfe_u32 s4, s84, 0x30006
	v_pk_mov_b32 v[180:181], v[148:149], v[148:149] op_sel:[1,0]
	s_cmp_eq_u32 s4, 0
	s_cbranch_scc1 .LBB0_983
	s_lshl_b32 s2, s2, 9
	s_add_i32 s2, s2, 0
	v_lshl_add_u32 v11, v162, 3, s2
	s_waitcnt vmcnt(2)
	v_pk_mov_b32 v[154:155], v[150:151], v[150:151] op_sel:[1,0]
	v_add_u32_e32 v11, 0x21000, v11
	v_mov_b32_e32 v153, v160

; #define LAS __attribute__((address_space(3)))
; __device__ __forceinline__ void s5_prompt_task(const Args& a, const Ctx& C, int b, int g, v4u (&xv)[8]) {
;     ...
; #pragma unroll
;       for (int i = 0; i < 16; ++i) { *(LAS v2f*)(SH + (16 * w + i) * 132 + 2 * lane) = (v2f){hr, hi};
;           const float nr = a16r * hr - a16i * hi + sv[i][0], ni = a16r * hi + a16i * hr + sv[i][1]; hr = nr; hi = ni; }
.LBB0_984:
	s_waitcnt vmcnt(2)
	v_pk_mul_f32 v[150:151], v[180:181], v[152:153] op_sel:[0,1]
	s_nop 0
	v_pk_fma_f32 v[154:155], v[148:149], v[152:153], v[150:151] op_sel_hi:[1,0,1]
	v_pk_fma_f32 v[150:151], v[148:149], v[152:153], v[150:151] op_sel_hi:[1,0,1] neg_lo:[0,0,1] neg_hi:[0,0,1]
	s_nop 0
	v_mov_b32_e32 v151, v155
	v_pk_add_f32 v[154:155], v[106:107], v[150:151]
	s_nop 0
	v_pk_mul_f32 v[106:107], v[180:181], v[154:155] op_sel:[0,1]
	s_nop 0
	v_pk_fma_f32 v[150:151], v[148:149], v[154:155], v[106:107] op_sel_hi:[1,0,1]
	v_pk_fma_f32 v[106:107], v[148:149], v[154:155], v[106:107] op_sel_hi:[1,0,1] neg_lo:[0,0,1] neg_hi:[0,0,1]
	s_nop 0
	v_mov_b32_e32 v107, v151
	v_pk_add_f32 v[156:157], v[108:109], v[106:107]
	s_nop 0
	v_pk_mul_f32 v[106:107], v[180:181], v[156:157] op_sel:[0,1]
	s_nop 0
	v_pk_fma_f32 v[108:109], v[148:149], v[156:157], v[106:107] op_sel_hi:[1,0,1]
	v_pk_fma_f32 v[106:107], v[148:149], v[156:157], v[106:107] op_sel_hi:[1,0,1] neg_lo:[0,0,1] neg_hi:[0,0,1]
	s_nop 0
	v_mov_b32_e32 v107, v109
	v_pk_add_f32 v[158:159], v[102:103], v[106:107]
	s_nop 0
	v_pk_mul_f32 v[102:103], v[180:181], v[158:159] op_sel:[0,1]
	s_nop 0
	v_pk_fma_f32 v[106:107], v[148:149], v[158:159], v[102:103] op_sel_hi:[1,0,1]
	v_pk_fma_f32 v[102:103], v[148:149], v[158:159], v[102:103] op_sel_hi:[1,0,1] neg_lo:[0,0,1] neg_hi:[0,0,1]
	s_nop 0
	v_mov_b32_e32 v103, v107
	v_pk_add_f32 v[164:165], v[104:105], v[102:103]
	s_nop 0
	v_pk_mul_f32 v[102:103], v[180:181], v[164:165] op_sel:[0,1]
	s_nop 0
	v_pk_fma_f32 v[104:105], v[148:149], v[164:165], v[102:103] op_sel_hi:[1,0,1]
	v_pk_fma_f32 v[102:103], v[148:149], v[164:165], v[102:103] op_sel_hi:[1,0,1] neg_lo:[0,0,1] neg_hi:[0,0,1]
	s_nop 0
	v_mov_b32_e32 v103, v105
	v_pk_add_f32 v[166:167], v[98:99], v[102:103]
	s_nop 0
	v_pk_mul_f32 v[98:99], v[180:181], v[166:167] op_sel:[0,1]
	s_nop 0
	v_pk_fma_f32 v[102:103], v[148:149], v[166:167], v[98:99] op_sel_hi:[1,0,1]
	v_pk_fma_f32 v[98:99], v[148:149], v[166:167], v[98:99] op_sel_hi:[1,0,1] neg_lo:[0,0,1] neg_hi:[0,0,1]
	s_nop 0
	v_mov_b32_e32 v99, v103
	v_pk_add_f32 v[168:169], v[100:101], v[98:99]
	s_nop 0
	v_pk_mul_f32 v[98:99], v[180:181], v[168:169] op_sel:[0,1]
	s_nop 0
	v_pk_fma_f32 v[100:101], v[148:149], v[168:169], v[98:99] op_sel_hi:[1,0,1]
	v_pk_fma_f32 v[98:99], v[148:149], v[168:169], v[98:99] op_sel_hi:[1,0,1] neg_lo:[0,0,1] neg_hi:[0,0,1]
	s_nop 0
	v_mov_b32_e32 v99, v101
	v_pk_add_f32 v[170:171], v[94:95], v[98:99]
	s_nop 0
	v_pk_mul_f32 v[94:95], v[180:181], v[170:171] op_sel:[0,1]
	s_nop 0
	v_pk_fma_f32 v[98:99], v[148:149], v[170:171], v[94:95] op_sel_hi:[1,0,1]
	v_pk_fma_f32 v[94:95], v[148:149], v[170:171], v[94:95] op_sel_hi:[1,0,1] neg_lo:[0,0,1] neg_hi:[0,0,1]
	s_nop 0
	v_mov_b32_e32 v95, v99
	v_pk_add_f32 v[172:173], v[96:97], v[94:95]
	s_nop 0
	v_pk_mul_f32 v[94:95], v[180:181], v[172:173] op_sel:[0,1]
	s_nop 0
	v_pk_fma_f32 v[96:97], v[148:149], v[172:173], v[94:95] op_sel_hi:[1,0,1]
	v_pk_fma_f32 v[94:95], v[148:149], v[172:173], v[94:95] op_sel_hi:[1,0,1] neg_lo:[0,0,1] neg_hi:[0,0,1]
	s_nop 0
	v_mov_b32_e32 v95, v97
	v_pk_add_f32 v[174:175], v[90:91], v[94:95]
	s_nop 0
	v_pk_mul_f32 v[90:91], v[180:181], v[174:175] op_sel:[0,1]
	s_nop 0
	v_pk_fma_f32 v[94:95], v[148:149], v[174:175], v[90:91] op_sel_hi:[1,0,1]
	v_pk_fma_f32 v[90:91], v[148:149], v[174:175], v[90:91] op_sel_hi:[1,0,1] neg_lo:[0,0,1] neg_hi:[0,0,1]
	s_nop 0
	v_mov_b32_e32 v91, v95
	v_pk_add_f32 v[176:177], v[92:93], v[90:91]
	s_nop 0
	v_pk_mul_f32 v[90:91], v[180:181], v[176:177] op_sel:[0,1]
	s_nop 0
	v_pk_fma_f32 v[92:93], v[148:149], v[176:177], v[90:91] op_sel_hi:[1,0,1]
	v_pk_fma_f32 v[90:91], v[148:149], v[176:177], v[90:91] op_sel_hi:[1,0,1] neg_lo:[0,0,1] neg_hi:[0,0,1]
	s_nop 0
	v_mov_b32_e32 v91, v93
	v_pk_add_f32 v[178:179], v[86:87], v[90:91]
	s_nop 0
	v_pk_mul_f32 v[86:87], v[180:181], v[178:179] op_sel:[0,1]
	s_nop 0
	v_pk_fma_f32 v[90:91], v[148:149], v[178:179], v[86:87] op_sel_hi:[1,0,1]
	v_pk_fma_f32 v[86:87], v[148:149], v[178:179], v[86:87] op_sel_hi:[1,0,1] neg_lo:[0,0,1] neg_hi:[0,0,1]
	s_nop 0
	v_mov_b32_e32 v87, v91
	v_pk_add_f32 v[182:183], v[88:89], v[86:87]
	s_nop 0
	v_pk_mul_f32 v[86:87], v[180:181], v[182:183] op_sel:[0,1]
	s_nop 0
	v_pk_fma_f32 v[88:89], v[148:149], v[182:183], v[86:87] op_sel_hi:[1,0,1]
	v_pk_fma_f32 v[86:87], v[148:149], v[182:183], v[86:87] op_sel_hi:[1,0,1] neg_lo:[0,0,1] neg_hi:[0,0,1]
	s_nop 0
	v_mov_b32_e32 v87, v89
	v_pk_add_f32 v[184:185], v[82:83], v[86:87]
	s_nop 0
	v_pk_mul_f32 v[82:83], v[180:181], v[184:185] op_sel:[0,1]
	s_nop 0
	v_pk_fma_f32 v[86:87], v[148:149], v[184:185], v[82:83] op_sel_hi:[1,0,1]
	v_pk_fma_f32 v[82:83], v[148:149], v[184:185], v[82:83] op_sel_hi:[1,0,1] neg_lo:[0,0,1] neg_hi:[0,0,1]
	s_nop 0
	v_mov_b32_e32 v83, v87
	v_pk_add_f32 v[186:187], v[84:85], v[82:83]
	s_nop 0
	v_pk_mul_f32 v[82:83], v[180:181], v[186:187] op_sel:[0,1]
	s_nop 0
	v_pk_fma_f32 v[84:85], v[148:149], v[186:187], v[82:83] op_sel_hi:[1,0,1]
	v_pk_fma_f32 v[82:83], v[148:149], v[186:187], v[82:83] op_sel_hi:[1,0,1] neg_lo:[0,0,1] neg_hi:[0,0,1]
	s_nop 0
	v_mov_b32_e32 v83, v85
	v_pk_add_f32 v[188:189], v[78:79], v[82:83]
	s_nop 0
	v_pk_mul_f32 v[78:79], v[180:181], v[188:189] op_sel:[0,1]
	s_nop 0
	v_pk_fma_f32 v[82:83], v[148:149], v[188:189], v[78:79] op_sel_hi:[1,0,1]
	v_pk_fma_f32 v[78:79], v[148:149], v[188:189], v[78:79] op_sel_hi:[1,0,1] neg_lo:[0,0,1] neg_hi:[0,0,1]
	s_nop 0
	v_mov_b32_e32 v79, v83
	v_pk_add_f32 v[180:181], v[80:81], v[78:79]

; #define LAS __attribute__((address_space(3)))
; __device__ __forceinline__ unsigned pk2(float lo, float hi) { return pg8::cvt_pk_bf16(lo, hi); }
; __device__ __forceinline__ bf16x8 pack8(f32x4 lo, f32x4 hi) { v4u w; w.x = pk2(lo[0], lo[1]); w.y = pk2(lo[2], lo[3]); w.z = pk2(hi[0], hi[1]); w.w = pk2(hi[2], hi[3]); return __builtin_bit_cast(bf16x8, w); }
; #define S5_UPDATE(K, hre, him, xq) do { const v2u xb_ = (xq); \
;     _Pragma("unroll") for (int j = 0; j < 4; ++j) { const f32x4 cre_ = K.ar[j] * hre[j] - K.ai[j] * him[j], cim_ = K.ar[j] * him[j] + K.ai[j] * hre[j]; \
;         hre[j] = MFMA16K16(K.Bf[2 * j], xb_, cre_); him[j] = MFMA16K16(K.Bf[2 * j + 1], xb_, cim_); } } while (0)
; __device__ __forceinline__ void s5_load_consts(S5C& K, const Args& a, int g, int lane) {
;     ...
;     const float* cre = a.in[I_CRE] + ((size_t)g * 16 + fr) * 64; const float* cim = a.in[I_CIM] + ((size_t)g * 16 + fr) * 64;
; #pragma unroll
;     for (int j = 0; j < 4; ++j) { const f32x4 r4 = *(const f32x4*)(cre + 16 * j + 4 * q), i4 = *(const f32x4*)(cim + 16 * j + 4 * q); K.Cf[j] = pack8(r4, -i4); }
;     const float* wg = a.in[I_WGLU] + (size_t)g * 512;
;     { f32x4 v, gt;
; #pragma unroll
;       for (int e = 0; e < 4; ++e) { v[e] = wg[(4 * q + e) * 32 + fr]; gt[e] = wg[(4 * q + e) * 32 + 16 + fr]; }
;       K.Wv = (v2u){pk2(v[0], v[1]), pk2(v[2], v[3])}; K.Wg = (v2u){pk2(gt[0], gt[1]), pk2(gt[2], gt[3])}; }
; __device__ __forceinline__ void s5_prompt_task(const Args& a, const Ctx& C, int b, int g, v4u (&xv)[8]) {
;     ...
;     for (int j = 0; j < 4; ++j) { const LAS float* s = SH + chunk * 132 + 2 * (16 * j + 4 * q); const f32x4 x0 = *(const LAS f32x4*)s, x1 = *(const LAS f32x4*)(s + 4);
;         hre[j] = (f32x4){x0[0], x0[2], x1[0], x1[2]}; him[j] = (f32x4){x0[1], x0[3], x1[1], x1[3]}; }
; #pragma unroll 1
;     for (int t0 = 0; t0 < 16; t0 += 4) {
; #pragma unroll
;         for (int u = 0; u < 4; ++u) { const int t = t0 + u, tok = 16 * chunk + t;
;             const v2u xq = *(const LAS v2u*)(xsl + t * 32);
;             S5_UPDATE(K, hre, him, xq);
.LBB0_987:
	v_xor_b32_e32 v15, 0x80000000, v63
	v_xor_b32_e32 v32, 0x80000000, v62
	v_xor_b32_e32 v7, 0x80000000, v65
	v_xor_b32_e32 v11, 0x80000000, v64
	v_cvt_pk_bf16_f32 v32, v32, v15
	v_xor_b32_e32 v15, 0x80000000, v55
	v_xor_b32_e32 v54, 0x80000000, v54
	v_cvt_pk_bf16_f32 v33, v11, v7
	v_xor_b32_e32 v7, 0x80000000, v57
	v_xor_b32_e32 v11, 0x80000000, v56
	v_cvt_pk_bf16_f32 v50, v50, v51
	v_cvt_pk_bf16_f32 v51, v52, v53
	v_cvt_pk_bf16_f32 v52, v54, v15
	v_xor_b32_e32 v15, 0x80000000, v47
	v_xor_b32_e32 v46, 0x80000000, v46
	v_cvt_pk_bf16_f32 v53, v11, v7
	v_xor_b32_e32 v7, 0x80000000, v49
	v_xor_b32_e32 v11, 0x80000000, v48
	v_cvt_pk_bf16_f32 v42, v42, v43
	v_cvt_pk_bf16_f32 v43, v44, v45
	v_cvt_pk_bf16_f32 v44, v46, v15
	v_xor_b32_e32 v15, 0x80000000, v39
	v_xor_b32_e32 v38, 0x80000000, v38
	s_waitcnt lgkmcnt(0)
	v_cvt_pk_bf16_f32 v30, v58, v59
	v_cvt_pk_bf16_f32 v31, v60, v61
	v_cvt_pk_bf16_f32 v45, v11, v7
	v_xor_b32_e32 v7, 0x80000000, v41
	v_xor_b32_e32 v11, 0x80000000, v40
	v_cvt_pk_bf16_f32 v34, v34, v35
	v_cvt_pk_bf16_f32 v35, v36, v37
	v_cvt_pk_bf16_f32 v36, v38, v15
	ds_read_b128 v[46:49], v3
	ds_read_b128 v[78:81], v3 offset:16
	ds_read_b128 v[54:57], v3 offset:128
	ds_read_b128 v[82:85], v3 offset:144
	ds_read_b128 v[38:41], v3 offset:256
	s_waitcnt vmcnt(2)
	ds_read_b128 v[148:151], v3 offset:272
	ds_read_b128 v[58:61], v3 offset:384
	ds_read_b128 v[152:155], v3 offset:400
	s_lshl_b64 s[4:5], s[70:71], 22
	v_lshlrev_b64 v[62:63], 11, v[110:111]
	v_lshl_add_u64 v[62:63], s[4:5], 0, v[62:63]
	v_or_b32_e32 v62, s1, v62
	v_lshl_add_u64 v[62:63], v[62:63], 0, v[112:113]
	v_lshl_add_u64 v[62:63], s[94:95], 0, v[62:63]
	s_mov_b64 s[0:1], 0x9801c00
	v_cvt_pk_bf16_f32 v37, v11, v7
	v_cvt_pk_bf16_f32 v102, v191, v193
	v_cvt_pk_bf16_f32 v103, v195, v196
	v_cvt_pk_bf16_f32 v104, v161, v190
	v_cvt_pk_bf16_f32 v105, v192, v194
	v_lshl_add_u64 v[106:107], v[62:63], 0, s[0:1]
	s_mov_b32 s0, 0
	s_mov_b32 s1, 0xc3e00000
	v_mov_b32_e32 v109, 0
	s_movk_i32 s2, 0xf000
	s_mov_b64 s[4:5], 0x2000
	v_mov_b32_e32 v111, 0x43e00000
	s_waitcnt lgkmcnt(7)
	v_mov_b32_e32 v62, v47
	v_mov_b32_e32 v63, v49
	s_waitcnt lgkmcnt(6)
	v_mov_b32_e32 v64, v79
	v_mov_b32_e32 v65, v81
	s_waitcnt lgkmcnt(5)
	v_mov_b32_e32 v66, v55
	v_mov_b32_e32 v67, v57
	s_waitcnt lgkmcnt(4)
	v_mov_b32_e32 v68, v83
	v_mov_b32_e32 v69, v85
	s_waitcnt lgkmcnt(3)
	v_mov_b32_e32 v70, v39
	v_mov_b32_e32 v71, v41
	s_waitcnt lgkmcnt(2)
	v_mov_b32_e32 v72, v149
	v_mov_b32_e32 v73, v151
	s_waitcnt lgkmcnt(1)
	v_mov_b32_e32 v74, v59
	v_mov_b32_e32 v75, v61
	s_waitcnt lgkmcnt(0)
	v_mov_b32_e32 v76, v153
	v_mov_b32_e32 v77, v155
	v_mov_b32_e32 v47, v48
	v_mov_b32_e32 v48, v78
	v_mov_b32_e32 v49, v80
	v_mov_b32_e32 v55, v56
	v_mov_b32_e32 v56, v82
	v_mov_b32_e32 v57, v84
	v_mov_b32_e32 v39, v40
	v_mov_b32_e32 v40, v148
	v_mov_b32_e32 v41, v150
	v_mov_b32_e32 v59, v60
	v_mov_b32_e32 v60, v152
	v_mov_b32_e32 v61, v154
.LBB0_988:
	ds_read2_b64 v[78:81], v163 offset1:4
	v_mov_b32_e32 v119, v5
	v_mov_b32_e32 v3, v4
	v_pk_mul_f32 v[150:151], v[88:89], v[46:47]
	v_mov_b32_e32 v121, v9
	v_mov_b32_e32 v123, v13
	v_pk_mul_f32 v[142:143], v[118:119], v[48:49]
	v_pk_mul_f32 v[148:149], v[88:89], v[62:63]
	v_mov_b32_e32 v7, v8
	v_pk_mul_f32 v[154:155], v[92:93], v[54:55]
	v_mov_b32_e32 v11, v12
	v_pk_mul_f32 v[158:159], v[96:97], v[38:39]
	v_mov_b32_e32 v125, v17
	v_add_co_u32_e32 v112, vcc, s2, v106
	v_pk_mul_f32 v[140:141], v[118:119], v[64:65]
	v_pk_fma_f32 v[62:63], v[86:87], v[62:63], v[150:151]
	v_pk_mul_f32 v[146:147], v[120:121], v[56:57]
	v_pk_mul_f32 v[150:151], v[122:123], v[40:41]
	v_pk_fma_f32 v[64:65], v[2:3], v[64:65], v[142:143]
	v_pk_mul_f32 v[152:153], v[92:93], v[66:67]
	v_pk_mul_f32 v[156:157], v[96:97], v[70:71]
	v_mov_b32_e32 v15, v16
	v_pk_mul_f32 v[164:165], v[100:101], v[58:59]
	v_add_u32_e32 v108, s0, v110
	v_addc_co_u32_e32 v113, vcc, -1, v107, vcc
	s_cmp_lt_u32 s0, 12
	v_pk_fma_f32 v[46:47], v[86:87], v[46:47], v[148:149] neg_lo:[0,0,1] neg_hi:[0,0,1]
	v_pk_mul_f32 v[144:145], v[120:121], v[68:69]
	v_pk_fma_f32 v[66:67], v[90:91], v[66:67], v[154:155]
	v_pk_mul_f32 v[148:149], v[122:123], v[72:73]
	v_pk_fma_f32 v[70:71], v[94:95], v[70:71], v[158:159]
	v_pk_mul_f32 v[154:155], v[124:125], v[60:61]
	v_pk_fma_f32 v[48:49], v[2:3], v[48:49], v[140:141] neg_lo:[0,0,1] neg_hi:[0,0,1]
	s_waitcnt lgkmcnt(0)
; #define LAS __attribute__((address_space(3)))
; #define MFMA16(A, B, Cc) __builtin_amdgcn_mfma_f32_16x16x32_bf16((A), (B), (Cc), 0, 0, 0)
; __device__ __forceinline__ unsigned pk2(float lo, float hi) { return pg8::cvt_pk_bf16(lo, hi); }
; __device__ __forceinline__ float bf_lo(unsigned w) { return __uint_as_float(w << 16); }
; __device__ __forceinline__ float bf_hi(unsigned w) { return __uint_as_float(w & 0xffff0000u); }
; __device__ __forceinline__ bf16x8 pack8(f32x4 lo, f32x4 hi) { v4u w; w.x = pk2(lo[0], lo[1]); w.y = pk2(lo[2], lo[3]); w.z = pk2(hi[0], hi[1]); w.w = pk2(hi[2], hi[3]); return __builtin_bit_cast(bf16x8, w); }
; #define S5_UPDATE(K, hre, him, xq) do { const v2u xb_ = (xq); \
;     _Pragma("unroll") for (int j = 0; j < 4; ++j) { const f32x4 cre_ = K.ar[j] * hre[j] - K.ai[j] * him[j], cim_ = K.ar[j] * him[j] + K.ai[j] * hre[j]; \
;         hre[j] = MFMA16K16(K.Bf[2 * j], xb_, cre_); him[j] = MFMA16K16(K.Bf[2 * j + 1], xb_, cim_); } } while (0)
; __device__ __forceinline__ unsigned s5_output(const S5C& K, const f32x4 (&hre)[4], const f32x4 (&him)[4], v2u xq, v2u zq) {
;     f32x4 y = (f32x4){0.f, 0.f, 0.f, 0.f};
; #pragma unroll
;     for (int j = 0; j < 4; ++j) y = MFMA16(K.Cf[j], pack8(hre[j], him[j]), y);
;     const f32x4 xf = (f32x4){bf_lo(xq.x), bf_hi(xq.x), bf_lo(xq.y), bf_hi(xq.y)};
;     y = y + K.dsk * xf;
;     const v2u yb = (v2u){pk2(y[0], y[1]), pk2(y[2], y[3])};
; __device__ __forceinline__ void s5_prompt_task(const Args& a, const Ctx& C, int b, int g, v4u (&xv)[8]) {
;     ...
;     for (int t0 = 0; t0 < 16; t0 += 4) {
; #pragma unroll
;         for (int u = 0; u < 4; ++u) { const int t = t0 + u, tok = 16 * chunk + t;
;             const v2u xq = *(const LAS v2u*)(xsl + t * 32);
;             S5_UPDATE(K, hre, him, xq);
;             *(unsigned*)((unsigned char*)Y + (row0 + tok) * DM + DA + g * 16 + 4 * q) = s5_output(K, hre, him, xq, zq[u]);
;             const size_t tn = row0 + ((t + 4 < 16) ? tok + 4 : tok);
;             zq[u] = __builtin_nontemporal_load((const v2u*)(ZBg + (size_t)(tn - row0) * 16 + 4 * q)); } }
	v_mfma_f32_16x16x16_bf16 v[62:65], v[116:117], v[78:79], v[62:65]
	v_fma_f32 v68, v6, v68, v146
	v_fma_f32 v69, v7, v69, v147
	v_pk_fma_f32 v[72:73], v[10:11], v[72:73], v[150:151]
	v_pk_mul_f32 v[160:161], v[100:101], v[74:75]
	v_pk_fma_f32 v[54:55], v[90:91], v[54:55], v[152:153] neg_lo:[0,0,1] neg_hi:[0,0,1]
	v_pk_fma_f32 v[38:39], v[94:95], v[38:39], v[156:157] neg_lo:[0,0,1] neg_hi:[0,0,1]
	v_pk_mul_f32 v[152:153], v[124:125], v[76:77]
	v_pk_fma_f32 v[74:75], v[98:99], v[74:75], v[164:165]
	v_mfma_f32_16x16x16_bf16 v[46:49], v[114:115], v[78:79], v[46:49]
	v_add_u32_e32 v140, 4, v108
	s_cselect_b64 vcc, -1, 0
	v_pk_fma_f32 v[40:41], v[10:11], v[40:41], v[148:149] neg_lo:[0,0,1] neg_hi:[0,0,1]
	v_mfma_f32_16x16x16_bf16 v[66:69], v[128:129], v[78:79], v[66:69]
	v_fma_f32 v76, v14, v76, v154
	v_fma_f32 v77, v15, v77, v155
	v_pk_fma_f32 v[58:59], v[98:99], v[58:59], v[160:161] neg_lo:[0,0,1] neg_hi:[0,0,1]
	v_add_u32_e32 v142, 1, v108
	v_mfma_f32_16x16x16_bf16 v[70:73], v[132:133], v[78:79], v[70:73]
	v_add_u32_e32 v143, 5, v108
	v_pk_fma_f32 v[56:57], v[6:7], v[56:57], v[144:145] neg_lo:[0,0,1] neg_hi:[0,0,1]
	v_add_u32_e32 v144, 2, v108
	v_add_u32_e32 v145, 6, v108
	v_add_u32_e32 v156, 3, v108
	v_add_u32_e32 v157, 7, v108
	v_mfma_f32_16x16x16_bf16 v[38:41], v[130:131], v[78:79], v[38:41]
	v_fma_f32 v60, v14, v60, -v152
	v_fma_f32 v61, v15, v61, -v153
	v_cndmask_b32_e32 v108, v108, v140, vcc
	v_lshlrev_b64 v[140:141], 5, v[108:109]
	v_mfma_f32_16x16x16_bf16 v[74:77], v[136:137], v[78:79], v[74:77]
	v_cndmask_b32_e32 v108, v142, v143, vcc
	v_lshl_add_u64 v[142:143], v[138:139], 0, v[140:141]
	v_lshlrev_b64 v[140:141], 5, v[108:109]
	v_mfma_f32_16x16x16_bf16 v[58:61], v[134:135], v[78:79], v[58:61]
	v_cndmask_b32_e32 v108, v144, v145, vcc
	v_pk_mul_f32 v[184:185], v[118:119], v[64:65]
	v_lshlrev_b32_e32 v164, 16, v78
	v_mfma_f32_16x16x16_bf16 v[54:57], v[126:127], v[78:79], v[54:57]
	v_and_b32_e32 v165, 0xffff0000, v78
	v_lshlrev_b32_e32 v206, 16, v79
	v_and_b32_e32 v207, 0xffff0000, v79
	v_lshl_add_u64 v[78:79], v[138:139], 0, v[140:141]
	v_lshlrev_b64 v[140:141], 5, v[108:109]
	v_cndmask_b32_e32 v108, v156, v157, vcc
	v_cvt_pk_bf16_f32 v157, v68, v69
	v_pk_mul_f32 v[186:187], v[88:89], v[62:63]
	v_pk_mul_f32 v[188:189], v[2:3], v[64:65]
	v_pk_mul_f32 v[190:191], v[86:87], v[62:63]
	v_pk_mul_f32 v[192:193], v[120:121], v[68:69]
	v_pk_mul_f32 v[196:197], v[6:7], v[68:69]
	v_pk_fma_f32 v[68:69], v[2:3], v[48:49], v[184:185] neg_lo:[0,0,1] neg_hi:[0,0,1]
	v_pk_mul_f32 v[184:185], v[96:97], v[70:71]
	v_cvt_pk_bf16_f32 v150, v46, v47
	v_cvt_pk_bf16_f32 v151, v48, v49
	v_cvt_pk_bf16_f32 v156, v66, v67
	v_cvt_pk_bf16_f32 v160, v70, v71
	v_pk_mul_f32 v[194:195], v[92:93], v[66:67]
	v_pk_mul_f32 v[198:199], v[90:91], v[66:67]
	v_pk_mul_f32 v[200:201], v[122:123], v[72:73]
	v_pk_fma_f32 v[66:67], v[86:87], v[46:47], v[186:187] neg_lo:[0,0,1] neg_hi:[0,0,1]
	v_pk_fma_f32 v[48:49], v[118:119], v[48:49], v[188:189]
	v_pk_fma_f32 v[46:47], v[88:89], v[46:47], v[190:191]
	v_pk_mul_f32 v[186:187], v[10:11], v[72:73]
	v_pk_mul_f32 v[188:189], v[94:95], v[70:71]
	v_pk_mul_f32 v[190:191], v[124:125], v[76:77]
	v_pk_fma_f32 v[70:71], v[94:95], v[38:39], v[184:185] neg_lo:[0,0,1] neg_hi:[0,0,1]
	v_pk_mul_f32 v[184:185], v[100:101], v[74:75]
	v_cvt_pk_bf16_f32 v152, v62, v63
	v_cvt_pk_bf16_f32 v153, v64, v65
	v_cvt_pk_bf16_f32 v159, v40, v41
	v_cvt_pk_bf16_f32 v161, v72, v73
	v_pk_fma_f32 v[72:73], v[10:11], v[40:41], v[200:201] neg_lo:[0,0,1] neg_hi:[0,0,1]
	v_pk_fma_f32 v[40:41], v[122:123], v[40:41], v[186:187]
	v_pk_fma_f32 v[186:187], v[14:15], v[60:61], v[190:191] neg_lo:[0,0,1] neg_hi:[0,0,1]
	v_pk_fma_f32 v[184:185], v[98:99], v[58:59], v[184:185] neg_lo:[0,0,1] neg_hi:[0,0,1]
	v_cvt_pk_bf16_f32 v154, v54, v55
	v_cvt_pk_bf16_f32 v155, v56, v57
	v_cvt_pk_bf16_f32 v158, v38, v39
	v_mfma_f32_16x16x32_bf16 v[62:65], v[30:33], v[150:153], 0
	v_fma_f32 v152, v6, v56, -v192
	v_fma_f32 v153, v7, v57, -v193
	v_pk_fma_f32 v[150:151], v[90:91], v[54:55], v[194:195] neg_lo:[0,0,1] neg_hi:[0,0,1]
	v_pk_fma_f32 v[56:57], v[120:121], v[56:57], v[196:197]
	v_pk_fma_f32 v[54:55], v[92:93], v[54:55], v[198:199]
	v_pk_fma_f32 v[38:39], v[96:97], v[38:39], v[188:189]
	v_pk_mul_f32 v[192:193], v[14:15], v[76:77]
	v_mfma_f32_16x16x16_bf16 v[186:189], v[134:135], v[80:81], v[184:187]
	v_fma_f32 v192, v124, v60, v192
	v_fma_f32 v193, v125, v61, v193
	ds_read2_b64 v[82:85], v163 offset0:8 offset1:12
	v_cvt_pk_bf16_f32 v182, v58, v59
	v_pk_mul_f32 v[184:185], v[98:99], v[74:75]
	v_mfma_f32_16x16x16_bf16 v[66:69], v[114:115], v[80:81], v[66:69]
	v_fma_f32 v190, v100, v58, v184
	v_fma_f32 v191, v101, v59, v185
	v_cvt_pk_bf16_f32 v183, v60, v61
	v_cvt_pk_bf16_f32 v185, v76, v77
	v_mfma_f32_16x16x16_bf16 v[46:49], v[116:117], v[80:81], v[46:49]
	v_lshlrev_b32_e32 v208, 16, v80
	v_and_b32_e32 v209, 0xffff0000, v80
	v_cvt_pk_bf16_f32 v184, v74, v75
	v_mfma_f32_16x16x16_bf16 v[54:57], v[128:129], v[80:81], v[54:57]
	v_lshlrev_b32_e32 v210, 16, v81
	s_nop 2
	v_pk_mul_f32 v[194:195], v[2:3], v[48:49]
	v_pk_mul_f32 v[196:197], v[86:87], v[46:47]
	v_mfma_f32_16x16x16_bf16 v[150:153], v[126:127], v[80:81], v[150:153]
	v_and_b32_e32 v211, 0xffff0000, v81
	v_pk_mul_f32 v[198:199], v[120:121], v[56:57]
	v_cvt_pk_bf16_f32 v77, v56, v57
	v_mfma_f32_16x16x16_bf16 v[38:41], v[132:133], v[80:81], v[38:41]
	v_mul_f32_e64 v200, v92, v54
	v_mul_f32_e64 v201, v93, v55
	v_pk_mul_f32 v[202:203], v[6:7], v[56:57]
	s_nop 0
	v_cvt_pk_bf16_f32 v75, v152, v153
	v_mfma_f32_16x16x16_bf16 v[190:193], v[136:137], v[80:81], v[190:193]
	v_cvt_pk_bf16_f32 v76, v54, v55
	v_pk_mul_f32 v[204:205], v[90:91], v[54:55]
	v_pk_mul_f32 v[216:217], v[122:123], v[40:41]
	v_mfma_f32_16x16x16_bf16 v[70:73], v[130:131], v[80:81], v[70:73]
	v_cvt_pk_bf16_f32 v74, v150, v151
	s_waitcnt lgkmcnt(0)
; #define LAS __attribute__((address_space(3)))
; #define MFMA16(A, B, Cc) __builtin_amdgcn_mfma_f32_16x16x32_bf16((A), (B), (Cc), 0, 0, 0)
; __device__ __forceinline__ float bf_lo(unsigned w) { return __uint_as_float(w << 16); }
; __device__ __forceinline__ float bf_hi(unsigned w) { return __uint_as_float(w & 0xffff0000u); }
; __device__ __forceinline__ bf16x8 pack8(f32x4 lo, f32x4 hi) { v4u w; w.x = pk2(lo[0], lo[1]); w.y = pk2(lo[2], lo[3]); w.z = pk2(hi[0], hi[1]); w.w = pk2(hi[2], hi[3]); return __builtin_bit_cast(bf16x8, w); }
; #define S5_UPDATE(K, hre, him, xq) do { const v2u xb_ = (xq); \
;     _Pragma("unroll") for (int j = 0; j < 4; ++j) { const f32x4 cre_ = K.ar[j] * hre[j] - K.ai[j] * him[j], cim_ = K.ar[j] * him[j] + K.ai[j] * hre[j]; \
;         hre[j] = MFMA16K16(K.Bf[2 * j], xb_, cre_); him[j] = MFMA16K16(K.Bf[2 * j + 1], xb_, cim_); } } while (0)
; __device__ __forceinline__ unsigned s5_output(const S5C& K, const f32x4 (&hre)[4], const f32x4 (&him)[4], v2u xq, v2u zq) {
;     f32x4 y = (f32x4){0.f, 0.f, 0.f, 0.f};
; #pragma unroll
;     for (int j = 0; j < 4; ++j) y = MFMA16(K.Cf[j], pack8(hre[j], him[j]), y);
;     const f32x4 xf = (f32x4){bf_lo(xq.x), bf_hi(xq.x), bf_lo(xq.y), bf_hi(xq.y)};
;     y = y + K.dsk * xf;
; __device__ __forceinline__ void s5_prompt_task(const Args& a, const Ctx& C, int b, int g, v4u (&xv)[8]) {
;     ...
;     for (int t0 = 0; t0 < 16; t0 += 4) {
; #pragma unroll
;         for (int u = 0; u < 4; ++u) { const int t = t0 + u, tok = 16 * chunk + t;
;             const v2u xq = *(const LAS v2u*)(xsl + t * 32);
;             S5_UPDATE(K, hre, him, xq);
;             *(unsigned*)((unsigned char*)Y + (row0 + tok) * DM + DA + g * 16 + 4 * q) = s5_output(K, hre, him, xq, zq[u]);
	v_lshlrev_b32_e32 v212, 16, v82
	v_and_b32_e32 v213, 0xffff0000, v82
	v_mfma_f32_16x16x32_bf16 v[58:61], v[50:53], v[154:157], v[62:65]
	v_mul_f32_e64 v154, v118, v48
	v_mul_f32_e64 v155, v119, v49
	v_pk_mul_f32 v[156:157], v[88:89], v[46:47]
	v_pk_fma_f32 v[56:57], v[2:3], v[68:69], v[154:155] neg_lo:[0,0,1] neg_hi:[0,0,1]
	v_cvt_pk_bf16_f32 v62, v66, v67
	v_cvt_pk_bf16_f32 v63, v68, v69
	v_cvt_pk_bf16_f32 v64, v46, v47
	v_cvt_pk_bf16_f32 v65, v48, v49
	v_pk_mul_f32 v[154:155], v[96:97], v[38:39]
	v_cvt_pk_bf16_f32 v80, v70, v71
	v_mfma_f32_16x16x32_bf16 v[46:49], v[30:33], v[62:65], 0
	v_fma_f32 v64, v118, v68, v194
	v_fma_f32 v65, v119, v69, v195
	v_pk_fma_f32 v[62:63], v[88:89], v[66:67], v[196:197]
	v_pk_fma_f32 v[68:69], v[6:7], v[152:153], v[198:199] neg_lo:[0,0,1] neg_hi:[0,0,1]
	v_pk_mul_f32 v[196:197], v[94:95], v[38:39]
	v_pk_mul_f32 v[198:199], v[124:125], v[192:193]
	v_pk_fma_f32 v[54:55], v[86:87], v[66:67], v[156:157] neg_lo:[0,0,1] neg_hi:[0,0,1]
	v_pk_mul_f32 v[194:195], v[10:11], v[40:41]
	v_pk_fma_f32 v[66:67], v[90:91], v[150:151], v[200:201] neg_lo:[0,0,1] neg_hi:[0,0,1]
	v_pk_fma_f32 v[152:153], v[120:121], v[152:153], v[202:203]
	v_pk_fma_f32 v[154:155], v[94:95], v[70:71], v[154:155] neg_lo:[0,0,1] neg_hi:[0,0,1]
	v_pk_mul_f32 v[200:201], v[100:101], v[190:191]
	v_pk_fma_f32 v[70:71], v[96:97], v[70:71], v[196:197]
	v_pk_mul_f32 v[202:203], v[14:15], v[192:193]
	v_pk_fma_f32 v[196:197], v[14:15], v[188:189], v[198:199] neg_lo:[0,0,1] neg_hi:[0,0,1]
	v_pk_mul_f32 v[198:199], v[98:99], v[190:191]
	v_cvt_pk_bf16_f32 v81, v72, v73
	v_mfma_f32_16x16x16_bf16 v[62:65], v[116:117], v[82:83], v[62:65]
	v_fma_f32 v150, v92, v150, v204
	v_fma_f32 v151, v93, v151, v205
	v_pk_fma_f32 v[156:157], v[10:11], v[72:73], v[216:217] neg_lo:[0,0,1] neg_hi:[0,0,1]
	v_pk_fma_f32 v[72:73], v[122:123], v[72:73], v[194:195]
	v_pk_fma_f32 v[194:195], v[98:99], v[186:187], v[200:201] neg_lo:[0,0,1] neg_hi:[0,0,1]
	v_pk_fma_f32 v[200:201], v[124:125], v[188:189], v[202:203]
	v_pk_fma_f32 v[198:199], v[100:101], v[186:187], v[198:199]
	v_lshlrev_b32_e32 v214, 16, v83
	v_and_b32_e32 v215, 0xffff0000, v83
	v_mfma_f32_16x16x16_bf16 v[54:57], v[114:115], v[82:83], v[54:57]
	v_cvt_pk_bf16_f32 v186, v186, v187
	v_cvt_pk_bf16_f32 v187, v188, v189
	v_cvt_pk_bf16_f32 v189, v192, v193
	v_mfma_f32_16x16x16_bf16 v[66:69], v[126:127], v[82:83], v[66:69]
	v_cvt_pk_bf16_f32 v188, v190, v191
	v_lshlrev_b32_e32 v144, 16, v84
	v_and_b32_e32 v145, 0xffff0000, v84
	v_mfma_f32_16x16x16_bf16 v[150:153], v[128:129], v[82:83], v[150:153]
	v_lshlrev_b32_e32 v146, 16, v85
	s_nop 2
	v_cvt_pk_bf16_f32 v190, v66, v67
	v_cvt_pk_bf16_f32 v191, v68, v69
	v_mfma_f32_16x16x16_bf16 v[154:157], v[130:131], v[82:83], v[154:157]
	v_and_b32_e32 v147, 0xffff0000, v85
	v_cvt_pk_bf16_f32 v192, v150, v151
	v_cvt_pk_bf16_f32 v193, v152, v153
	v_mfma_f32_16x16x16_bf16 v[70:73], v[132:133], v[82:83], v[70:73]
	v_mul_f32_e64 v216, v6, v152
	v_mul_f32_e64 v217, v7, v153
	v_pk_mul_f32 v[218:219], v[90:91], v[150:151]
	s_nop 0
	v_cvt_pk_bf16_f32 v202, v154, v155
	v_mfma_f32_16x16x16_bf16 v[194:197], v[134:135], v[82:83], v[194:197]
	v_cvt_pk_bf16_f32 v203, v156, v157
	s_nop 0
	v_cvt_pk_bf16_f32 v204, v70, v71
	v_cvt_pk_bf16_f32 v205, v72, v73
	v_mfma_f32_16x16x16_bf16 v[198:201], v[136:137], v[82:83], v[198:201]
	v_cvt_pk_bf16_f32 v82, v38, v39
	v_cvt_pk_bf16_f32 v83, v40, v41
	v_pk_mul_f32 v[220:221], v[122:123], v[72:73]
	v_mfma_f32_16x16x32_bf16 v[38:41], v[42:45], v[158:161], v[58:61]
	v_lshlrev_b64 v[148:149], 5, v[108:109]
	v_mov_b32_e32 v166, 0
	v_mov_b32_e32 v171, v109
	v_pk_mul_f32 v[58:59], v[118:119], v[64:65]
	v_pk_mul_f32 v[60:61], v[88:89], v[62:63]
	v_mfma_f32_16x16x32_bf16 v[158:161], v[50:53], v[74:77], v[46:49]
	v_mul_f32_e64 v74, v120, v152
	v_mul_f32_e64 v75, v121, v153
	v_pk_mul_f32 v[76:77], v[92:93], v[150:151]
	v_mov_b32_e32 v176, v109
	v_cvt_pk_bf16_f32 v46, v54, v55
	v_cvt_pk_bf16_f32 v47, v56, v57
	v_cvt_pk_bf16_f32 v48, v62, v63
	v_cvt_pk_bf16_f32 v49, v64, v65
	v_pk_mul_f32 v[64:65], v[2:3], v[64:65]
	v_pk_mul_f32 v[62:63], v[86:87], v[62:63]
	v_mfma_f32_16x16x32_bf16 v[182:185], v[34:37], v[182:185], v[38:41]
	v_mov_b32_e32 v225, v109
	v_lshl_add_u64 v[140:141], v[138:139], 0, v[140:141]
	v_lshl_add_u64 v[148:149], v[138:139], 0, v[148:149]
	v_pk_fma_f32 v[40:41], v[2:3], v[56:57], v[58:59] neg_lo:[0,0,1] neg_hi:[0,0,1]
	v_pk_fma_f32 v[38:39], v[86:87], v[54:55], v[60:61] neg_lo:[0,0,1] neg_hi:[0,0,1]
	v_mfma_f32_16x16x32_bf16 v[150:153], v[30:33], v[46:49], 0
	v_mul_f32_e64 v58, v96, v70
	v_mul_f32_e64 v59, v97, v71
	v_pk_mul_f32 v[60:61], v[10:11], v[72:73]
	v_pk_mul_f32 v[70:71], v[94:95], v[70:71]
	v_mfma_f32_16x16x16_bf16 v[46:49], v[114:115], v[84:85], v[38:41]
	v_fma_f32 v60, v122, v156, v60
	v_fma_f32 v61, v123, v157, v61
	v_add_u32_e32 v163, 0x80, v163
	s_add_i32 s0, s0, 4
	v_pk_fma_f32 v[40:41], v[118:119], v[56:57], v[64:65]
	v_pk_fma_f32 v[38:39], v[88:89], v[54:55], v[62:63]
	v_mfma_f32_16x16x32_bf16 v[80:83], v[42:45], v[80:83], v[158:161]
	s_and_b64 vcc, exec, vcc
	v_mfma_f32_16x16x16_bf16 v[62:65], v[116:117], v[84:85], v[38:41]
	s_nop 0
	v_fma_f32 v158, v18, v164, v182
	v_fma_f32 v159, v19, v165, v183
	v_cvt_pk_bf16_f32 v164, v158, v159
	v_pk_fma_f32 v[40:41], v[6:7], v[68:69], v[74:75] neg_lo:[0,0,1] neg_hi:[0,0,1]
	v_pk_fma_f32 v[38:39], v[90:91], v[66:67], v[76:77] neg_lo:[0,0,1] neg_hi:[0,0,1]
	v_pk_mul_f32 v[74:75], v[124:125], v[200:201]
	v_pk_mul_f32 v[76:77], v[100:101], v[198:199]
	v_mfma_f32_16x16x16_bf16 v[54:57], v[126:127], v[84:85], v[38:41]
	v_cvt_pk_bf16_f32 v158, v46, v47
	v_cvt_pk_bf16_f32 v159, v48, v49
	v_cvt_pk_bf16_f32 v160, v62, v63
; #define LAS __attribute__((address_space(3)))
; #define MFMA16(A, B, Cc) __builtin_amdgcn_mfma_f32_16x16x32_bf16((A), (B), (Cc), 0, 0, 0)
; #define MFMA16K16(A, B, Cc) __builtin_amdgcn_mfma_f32_16x16x16bf16_1k(__builtin_bit_cast(bf16x4, (A)), __builtin_bit_cast(bf16x4, (B)), (Cc), 0, 0, 0)
; __device__ __forceinline__ unsigned pk2(float lo, float hi) { return pg8::cvt_pk_bf16(lo, hi); }
; __device__ __forceinline__ float bf_lo(unsigned w) { return __uint_as_float(w << 16); }
; __device__ __forceinline__ unsigned pk4f8(float a, float b, float c, float d) { int p = __builtin_amdgcn_cvt_pk_fp8_f32(sat8(a), sat8(b), 0, false); p = __builtin_amdgcn_cvt_pk_fp8_f32(sat8(c), sat8(d), p, true); return (unsigned)p; }
; __device__ __forceinline__ float bf_hi(unsigned w) { return __uint_as_float(w & 0xffff0000u); }
; __device__ __forceinline__ bf16x8 pack8(f32x4 lo, f32x4 hi) { v4u w; w.x = pk2(lo[0], lo[1]); w.y = pk2(lo[2], lo[3]); w.z = pk2(hi[0], hi[1]); w.w = pk2(hi[2], hi[3]); return __builtin_bit_cast(bf16x8, w); }
; __device__ __forceinline__ unsigned s5_output(const S5C& K, const f32x4 (&hre)[4], const f32x4 (&him)[4], v2u xq, v2u zq) {
;     f32x4 y = (f32x4){0.f, 0.f, 0.f, 0.f};
; #pragma unroll
;     for (int j = 0; j < 4; ++j) y = MFMA16(K.Cf[j], pack8(hre[j], him[j]), y);
;     const f32x4 xf = (f32x4){bf_lo(xq.x), bf_hi(xq.x), bf_lo(xq.y), bf_hi(xq.y)};
;     y = y + K.dsk * xf;
;     const v2u yb = (v2u){pk2(y[0], y[1]), pk2(y[2], y[3])};
;     const f32x4 gv = MFMA16K16(K.Wv, yb, K.bv), gg = MFMA16K16(K.Wg, yb, K.bg);
;     const f32x4 zf = (f32x4){bf_lo(zq.x), bf_hi(zq.x), bf_lo(zq.y), bf_hi(zq.y)};
;     f32x4 o;
; #pragma unroll
;     for (int r = 0; r < 4; ++r) o[r] = gv[r] * __builtin_amdgcn_rcpf(1.0f + __expf(-gg[r])) * zf[r];
;     return pk4f8(o[0], o[1], o[2], o[3]);
; __device__ __forceinline__ void s5_prompt_task(const Args& a, const Ctx& C, int b, int g, v4u (&xv)[8]) {
;     ...
;         for (int u = 0; u < 4; ++u) { const int t = t0 + u, tok = 16 * chunk + t;
;             const v2u xq = *(const LAS v2u*)(xsl + t * 32);
;             S5_UPDATE(K, hre, him, xq);
;             *(unsigned*)((unsigned char*)Y + (row0 + tok) * DM + DA + g * 16 + 4 * q) = s5_output(K, hre, him, xq, zq[u]);
	v_pk_fma_f32 v[40:41], v[120:121], v[68:69], v[216:217]
	v_pk_fma_f32 v[38:39], v[92:93], v[66:67], v[218:219]
	v_mfma_f32_16x16x32_bf16 v[150:153], v[50:53], v[190:193], v[150:153]
	v_cvt_pk_bf16_f32 v161, v64, v65
	v_mfma_f32_16x16x16_bf16 v[66:69], v[128:129], v[84:85], v[38:41]
	s_nop 2
	v_fma_f32 v38, v94, v154, -v58
	v_fma_f32 v39, v95, v155, -v59
	v_pk_fma_f32 v[58:59], v[96:97], v[154:155], v[70:71]
	v_pk_mul_f32 v[154:155], v[14:15], v[200:201]
	v_pk_fma_f32 v[40:41], v[10:11], v[156:157], v[220:221] neg_lo:[0,0,1] neg_hi:[0,0,1]
	v_mfma_f32_16x16x16_bf16 v[70:73], v[132:133], v[84:85], v[58:61]
	v_cvt_pk_bf16_f32 v156, v198, v199
	v_cvt_pk_bf16_f32 v157, v200, v201
	s_nop 0
	v_pk_fma_f32 v[60:61], v[14:15], v[196:197], v[74:75] neg_lo:[0,0,1] neg_hi:[0,0,1]
	v_pk_mul_f32 v[74:75], v[98:99], v[198:199]
	v_pk_fma_f32 v[58:59], v[98:99], v[194:195], v[76:77] neg_lo:[0,0,1] neg_hi:[0,0,1]
	v_pk_fma_f32 v[76:77], v[124:125], v[196:197], v[154:155]
	v_pk_fma_f32 v[74:75], v[100:101], v[194:195], v[74:75]
	v_mfma_f32_16x16x16_bf16 v[38:41], v[130:131], v[84:85], v[38:41]
	v_cvt_pk_bf16_f32 v154, v194, v195
	v_cvt_pk_bf16_f32 v155, v196, v197
	v_cvt_pk_bf16_f32 v194, v54, v55
	v_mfma_f32_16x16x16_bf16 v[58:61], v[134:135], v[84:85], v[58:61]
	v_cvt_pk_bf16_f32 v195, v56, v57
	v_cvt_pk_bf16_f32 v196, v66, v67
	v_cvt_pk_bf16_f32 v197, v68, v69
	v_mfma_f32_16x16x16_bf16 v[74:77], v[136:137], v[84:85], v[74:77]
	v_fma_f32 v84, v20, v206, v184
	v_fma_f32 v85, v21, v207, v185
	s_nop 1
	v_cvt_pk_bf16_f32 v198, v58, v59
	v_cvt_pk_bf16_f32 v165, v84, v85
	v_mfma_f32_16x16x32_bf16 v[80:83], v[34:37], v[186:189], v[80:83]
	v_cvt_pk_bf16_f32 v186, v38, v39
	v_cvt_pk_bf16_f32 v187, v40, v41
	v_cvt_pk_bf16_f32 v188, v70, v71
	v_mfma_f32_16x16x16_bf16 v[190:193], v[104:105], v[164:165], v[26:29]
	v_cvt_pk_bf16_f32 v189, v72, v73
	s_nop 2
	v_pk_fma_f32 v[80:81], v[18:19], v[208:209], v[80:81]
	v_cvt_pk_bf16_f32 v199, v60, v61
	v_mfma_f32_16x16x32_bf16 v[158:161], v[30:33], v[158:161], 0
	v_cvt_pk_bf16_f32 v80, v80, v81
	v_mul_f32_e32 v3, 0xbfb8aa3b, v190
	v_mul_f32_e32 v7, 0xbfb8aa3b, v191
	v_mfma_f32_16x16x32_bf16 v[150:153], v[42:45], v[202:205], v[150:153]
	v_exp_f32_e32 v3, v3
	v_exp_f32_e32 v7, v7
	v_mul_f32_e32 v11, 0xbfb8aa3b, v192
	v_mfma_f32_16x16x16_bf16 v[182:185], v[102:103], v[164:165], v[22:25]
	v_fma_f32 v164, v20, v210, v82
	v_fma_f32 v165, v21, v211, v83
	v_mul_f32_e32 v15, 0xbfb8aa3b, v193
	v_cvt_pk_bf16_f32 v81, v164, v165
	v_mfma_f32_16x16x32_bf16 v[82:85], v[50:53], v[194:197], v[158:161]
	v_exp_f32_e32 v11, v11
	v_exp_f32_e32 v15, v15
	v_add_f32_e32 v3, 1.0, v3
	v_mfma_f32_16x16x32_bf16 v[150:153], v[34:37], v[154:157], v[150:153]
	v_add_f32_e32 v7, 1.0, v7
	v_rcp_f32_e32 v3, v3
	v_rcp_f32_e32 v7, v7
	v_mfma_f32_16x16x16_bf16 v[194:197], v[104:105], v[80:81], v[26:29]
	v_cvt_pk_bf16_f32 v200, v74, v75
	s_nop 2
	v_pk_fma_f32 v[150:151], v[18:19], v[212:213], v[150:151]
	v_cvt_pk_bf16_f32 v201, v76, v77
	v_mfma_f32_16x16x16_bf16 v[158:161], v[102:103], v[80:81], v[22:25]
	v_cvt_pk_bf16_f32 v154, v150, v151
	v_mul_f32_e32 v108, 0xbfb8aa3b, v194
	v_mul_f32_e32 v119, 0xbfb8aa3b, v195
	v_mfma_f32_16x16x32_bf16 v[80:83], v[42:45], v[186:189], v[82:85]
	v_exp_f32_e32 v108, v108
	v_exp_f32_e32 v119, v119
	v_add_f32_e32 v11, 1.0, v11
	v_pk_fma_f32 v[84:85], v[20:21], v[214:215], v[152:153]
	v_mfma_f32_16x16x32_bf16 v[80:83], v[34:37], v[198:201], v[80:83]
	v_cvt_pk_bf16_f32 v155, v84, v85
	v_mul_f32_e32 v84, 0xbfb8aa3b, v196
	v_mul_f32_e32 v85, 0xbfb8aa3b, v197
	v_exp_f32_e32 v84, v84
	v_mfma_f32_16x16x16_bf16 v[150:153], v[102:103], v[154:155], v[22:25]
	v_exp_f32_e32 v85, v85
	v_add_f32_e32 v15, 1.0, v15
	v_rcp_f32_e32 v11, v11
	v_mfma_f32_16x16x16_bf16 v[154:157], v[104:105], v[154:155], v[26:29]
	v_rcp_f32_e32 v15, v15
	v_mul_f32_e32 v3, v182, v3
	v_mul_f32_e32 v7, v183, v7
	s_waitcnt vmcnt(0)
; #define LAS __attribute__((address_space(3)))
; #define MFMA16(A, B, Cc) __builtin_amdgcn_mfma_f32_16x16x32_bf16((A), (B), (Cc), 0, 0, 0)
; #define MFMA16K16(A, B, Cc) __builtin_amdgcn_mfma_f32_16x16x16bf16_1k(__builtin_bit_cast(bf16x4, (A)), __builtin_bit_cast(bf16x4, (B)), (Cc), 0, 0, 0)
; __device__ __forceinline__ unsigned pk2(float lo, float hi) { return pg8::cvt_pk_bf16(lo, hi); }
; __device__ __forceinline__ float bf_lo(unsigned w) { return __uint_as_float(w << 16); }
; __device__ __forceinline__ unsigned pk4f8(float a, float b, float c, float d) { int p = __builtin_amdgcn_cvt_pk_fp8_f32(sat8(a), sat8(b), 0, false); p = __builtin_amdgcn_cvt_pk_fp8_f32(sat8(c), sat8(d), p, true); return (unsigned)p; }
; __device__ __forceinline__ float bf_hi(unsigned w) { return __uint_as_float(w & 0xffff0000u); }
; __device__ __forceinline__ bf16x8 pack8(f32x4 lo, f32x4 hi) { v4u w; w.x = pk2(lo[0], lo[1]); w.y = pk2(lo[2], lo[3]); w.z = pk2(hi[0], hi[1]); w.w = pk2(hi[2], hi[3]); return __builtin_bit_cast(bf16x8, w); }
; __device__ __forceinline__ unsigned s5_output(const S5C& K, const f32x4 (&hre)[4], const f32x4 (&him)[4], v2u xq, v2u zq) {
;     f32x4 y = (f32x4){0.f, 0.f, 0.f, 0.f};
; #pragma unroll
;     for (int j = 0; j < 4; ++j) y = MFMA16(K.Cf[j], pack8(hre[j], him[j]), y);
;     const f32x4 xf = (f32x4){bf_lo(xq.x), bf_hi(xq.x), bf_lo(xq.y), bf_hi(xq.y)};
;     y = y + K.dsk * xf;
;     const v2u yb = (v2u){pk2(y[0], y[1]), pk2(y[2], y[3])};
;     const f32x4 gv = MFMA16K16(K.Wv, yb, K.bv), gg = MFMA16K16(K.Wg, yb, K.bg);
;     const f32x4 zf = (f32x4){bf_lo(zq.x), bf_hi(zq.x), bf_lo(zq.y), bf_hi(zq.y)};
;     f32x4 o;
; #pragma unroll
;     for (int r = 0; r < 4; ++r) o[r] = gv[r] * __builtin_amdgcn_rcpf(1.0f + __expf(-gg[r])) * zf[r];
;     return pk4f8(o[0], o[1], o[2], o[3]);
; __device__ __forceinline__ void s5_prompt_task(const Args& a, const Ctx& C, int b, int g, v4u (&xv)[8]) {
;     ...
;             const v2u xq = *(const LAS v2u*)(xsl + t * 32);
;             S5_UPDATE(K, hre, him, xq);
;             *(unsigned*)((unsigned char*)Y + (row0 + tok) * DM + DA + g * 16 + 4 * q) = s5_output(K, hre, him, xq, zq[u]);
;             const size_t tn = row0 + ((t + 4 < 16) ? tok + 4 : tok);
;             zq[u] = __builtin_nontemporal_load((const v2u*)(ZBg + (size_t)(tn - row0) * 16 + 4 * q)); } }
	v_permlane16_swap_b32_e32 v226, v228
	v_permlane16_swap_b32_e32 v227, v229
	v_permlane16_swap_b32_e32 v230, v232
	v_permlane16_swap_b32_e32 v231, v233
	s_nop 1
	v_permlane32_swap_b32_e32 v226, v228
	v_permlane32_swap_b32_e32 v227, v229
	v_permlane32_swap_b32_e32 v230, v232
	v_permlane32_swap_b32_e32 v231, v233
	s_nop 1
	v_lshlrev_b32_e32 v177, 16, v230
	v_and_b32_e32 v178, 0xffff0000, v230
	v_lshlrev_b32_e32 v179, 16, v231
	v_and_b32_e32 v180, 0xffff0000, v231
	v_lshlrev_b32_e32 v167, 16, v226
	v_and_b32_e32 v168, 0xffff0000, v226
	v_lshlrev_b32_e32 v169, 16, v227
	v_and_b32_e32 v170, 0xffff0000, v227
	v_lshlrev_b32_e32 v181, 16, v232
	v_and_b32_e32 v222, 0xffff0000, v232
	v_lshlrev_b32_e32 v223, 16, v233
	v_and_b32_e32 v224, 0xffff0000, v233
	v_lshlrev_b32_e32 v172, 16, v228
	v_and_b32_e32 v173, 0xffff0000, v228
	v_lshlrev_b32_e32 v174, 16, v229
	v_and_b32_e32 v175, 0xffff0000, v229
	v_mul_f32_e32 v3, v3, v167
	v_mul_f32_e32 v7, v7, v168
	v_add_f32_e32 v108, 1.0, v108
	v_add_f32_e32 v119, 1.0, v119
	v_add_f32_e32 v84, 1.0, v84
	v_add_f32_e32 v85, 1.0, v85
	v_med3_f32 v3, v3, s1, v111
	v_med3_f32 v7, v7, s1, v111
	v_rcp_f32_e32 v108, v108
	v_rcp_f32_e32 v119, v119
	v_rcp_f32_e32 v121, v84
	v_mul_f32_e32 v84, 0xbfb8aa3b, v154
	v_pk_fma_f32 v[82:83], v[20:21], v[146:147], v[82:83]
	v_pk_fma_f32 v[80:81], v[18:19], v[144:145], v[80:81]
	v_rcp_f32_e32 v123, v85
	v_cvt_pk_fp8_f32 v166, v3, v7
	v_exp_f32_e32 v3, v84
	v_cvt_pk_bf16_f32 v84, v80, v81
	v_cvt_pk_bf16_f32 v85, v82, v83
	v_mul_f32_e32 v11, v184, v11
	v_mul_f32_e32 v15, v185, v15
	v_mfma_f32_16x16x16_bf16 v[144:147], v[104:105], v[84:85], v[26:29]
	v_mul_f32_e32 v11, v11, v169
	v_mul_f32_e32 v15, v15, v170
	v_mul_f32_e32 v125, 0xbfb8aa3b, v155
	v_med3_f32 v11, v11, s1, v111
	v_med3_f32 v15, v15, s1, v111
	v_mul_f32_e32 v154, 0xbfb8aa3b, v156
	v_mul_f32_e32 v155, 0xbfb8aa3b, v157
	v_mfma_f32_16x16x16_bf16 v[80:83], v[102:103], v[84:85], v[22:25]
	v_exp_f32_e32 v7, v125
	v_mul_f32_e32 v84, v158, v108
	v_mul_f32_e32 v85, v159, v119
	v_exp_f32_e32 v125, v154
	v_exp_f32_e32 v154, v155
	v_cvt_pk_fp8_f32 v166, v11, v15 op_sel:[0,0,1]
	v_mul_f32_e32 v11, v84, v172
	v_mul_f32_e32 v15, v85, v173
	v_mul_f32_e32 v108, v160, v121
	v_mul_f32_e32 v119, v161, v123
	v_med3_f32 v11, v11, s1, v111
	v_med3_f32 v15, v15, s1, v111
	v_mul_f32_e32 v121, 0xbfb8aa3b, v144
	v_mul_f32_e32 v123, 0xbfb8aa3b, v145
	v_cvt_pk_fp8_f32 v171, v11, v15
	v_exp_f32_e32 v11, v121
	v_exp_f32_e32 v15, v123
	v_add_f32_e32 v3, 1.0, v3
	v_add_f32_e32 v7, 1.0, v7
	v_mul_f32_e32 v84, v108, v174
	v_mul_f32_e32 v85, v119, v175
	v_add_f32_e32 v108, 1.0, v125
	v_add_f32_e32 v119, 1.0, v154
	v_rcp_f32_e32 v3, v3
	v_rcp_f32_e32 v7, v7
	v_rcp_f32_e32 v108, v108
	v_rcp_f32_e32 v119, v119
	v_mul_f32_e32 v125, 0xbfb8aa3b, v146
	v_mul_f32_e32 v144, 0xbfb8aa3b, v147
	v_exp_f32_e32 v121, v125
	v_exp_f32_e32 v123, v144
	v_add_f32_e32 v11, 1.0, v11
	v_add_f32_e32 v15, 1.0, v15
	v_rcp_f32_e32 v11, v11
	v_rcp_f32_e32 v15, v15
	v_mul_f32_e32 v3, v150, v3
	v_mul_f32_e32 v7, v151, v7
	v_med3_f32 v84, v84, s1, v111
	v_med3_f32 v85, v85, s1, v111
	global_store_dword v[112:113], v166, off offset:-2048
	v_mul_f32_e32 v108, v152, v108
	v_mul_f32_e32 v112, v153, v119
	v_mul_f32_e32 v3, v3, v177
	v_mul_f32_e32 v7, v7, v178
	v_cvt_pk_fp8_f32 v171, v84, v85 op_sel:[0,0,1]
	v_mul_f32_e32 v84, v108, v179
	v_mul_f32_e32 v85, v112, v180
	v_add_f32_e32 v108, 1.0, v121
	v_add_f32_e32 v112, 1.0, v123
	v_med3_f32 v3, v3, s1, v111
	v_med3_f32 v7, v7, s1, v111
	v_rcp_f32_e32 v108, v108
	v_rcp_f32_e32 v112, v112
	v_cvt_pk_fp8_f32 v176, v3, v7
	v_mul_f32_e32 v3, v80, v11
	v_mul_f32_e32 v7, v81, v15
	v_mul_f32_e32 v3, v3, v181
	v_mul_f32_e32 v7, v7, v222
	v_med3_f32 v3, v3, s1, v111
	v_med3_f32 v7, v7, s1, v111
	v_cvt_pk_fp8_f32 v225, v3, v7
	v_mul_f32_e32 v11, v82, v108
	v_mul_f32_e32 v15, v83, v112
	v_med3_f32 v84, v84, s1, v111
	v_med3_f32 v85, v85, s1, v111
	v_mul_f32_e32 v11, v11, v223
	v_mul_f32_e32 v3, v15, v224
	v_cvt_pk_fp8_f32 v176, v84, v85 op_sel:[0,0,1]
	v_med3_f32 v7, v11, s1, v111
	v_med3_f32 v3, v3, s1, v111
	v_cvt_pk_fp8_f32 v225, v7, v3 op_sel:[0,0,1]
	v_lshl_add_u64 v[246:247], v[142:143], 0, v[244:245]
	global_load_dwordx4 v[226:229], v[246:247], off nt
	s_nop 0
	global_store_dword v[106:107], v171, off offset:-4096
	s_nop 0
	global_store_dword v[106:107], v176, off offset:-2048
	v_lshl_add_u64 v[242:243], v[140:141], 0, v[244:245]
	global_load_dwordx4 v[230:233], v[242:243], off nt
	s_nop 0
	global_store_dword v[106:107], v225, off
	v_lshl_add_u64 v[106:107], v[106:107], 0, s[4:5]
	s_cbranch_vccnz .LBB0_988
